# seam streaming with the first 12 attention-loop iterations peeled (one fixed stage load each, no dispatch); remaining iterations run the original loop body
# speedup vs baseline: 1.0051x; 1.0051x over previous
.Lpeel_0:
	s_add_i32 s9, s3, -1
	s_min_u32 s9, s9, s2
	s_lshl_b32 s9, s9, 6
	s_waitcnt vmcnt(1)
	ds_write_b128 v142, v[112:115] offset:16384
	s_waitcnt vmcnt(0)
	ds_write_b128 v142, v[116:119] offset:24576
	v_mad_u64_u32 v[64:65], s[18:19], s9, v237, v[132:133]
	global_load_dwordx4 v[120:123], v[64:65], off offset:2048
	global_load_dwordx4 v[124:127], v[136:137], off offset:-128
	ds_read_b128 v[64:67], v144 offset:8192
	ds_read_b128 v[68:71], v144 offset:12288
	ds_read_b128 v[72:75], v141 offset:8192
	ds_read_b128 v[76:79], v141 offset:12288
	v_exp_f32_e32 v151, v48
	v_exp_f32_e32 v152, v49
	s_waitcnt lgkmcnt(3)
	v_mfma_f32_32x32x16_bf16 v[16:31], v[64:67], v[80:83], v[16:31]
	v_exp_f32_e32 v153, v50
	v_exp_f32_e32 v154, v51
	ds_read_b128 v[48:51], v140 offset:8192
	ds_read_b128 v[64:67], v140 offset:12288
	v_exp_f32_e32 v155, v52
	s_waitcnt lgkmcnt(4)
	v_mfma_f32_32x32x16_bf16 v[0:15], v[68:71], v[80:83], v[0:15]
	v_exp_f32_e32 v156, v53
	v_exp_f32_e32 v159, v54
	v_exp_f32_e32 v160, v55
	v_exp_f32_e32 v162, v57
	s_waitcnt lgkmcnt(3)
	v_mfma_f32_32x32x16_bf16 v[16:31], v[72:75], v[84:87], v[16:31]
	ds_read_b128 v[68:71], v139 offset:8192
	ds_read_b128 v[80:83], v139 offset:12288
	v_add_f32_e32 v157, v155, v151
	v_add_f32_e32 v158, v156, v152
	ds_read_b128 v[52:55], v164
	ds_read_b128 v[72:75], v164 offset:4096
	v_add_f32_e32 v161, v159, v153
	s_waitcnt lgkmcnt(6)
	v_mfma_f32_32x32x16_bf16 v[0:15], v[76:79], v[84:87], v[0:15]
	v_exp_f32_e32 v77, v56
	v_add_f32_e32 v76, v160, v154
	v_exp_f32_e32 v62, v62
	ds_read_b128 v[112:115], v165
	ds_read_b128 v[116:119], v165 offset:4096
	v_cvt_pk_bf16_f32 v56, v151, v152
	s_waitcnt lgkmcnt(7)
	v_mfma_f32_32x32x16_bf16 v[16:31], v[48:51], v[88:91], v[16:31]
	v_exp_f32_e32 v49, v58
	v_exp_f32_e32 v50, v59
	v_add_f32_e32 v48, v77, v157
	v_add_f32_e32 v51, v162, v158
	v_add_f32_e32 v78, v49, v161
	v_add_f32_e32 v76, v50, v76
	s_waitcnt lgkmcnt(6)
	v_mfma_f32_32x32x16_bf16 v[0:15], v[64:67], v[88:91], v[0:15]
	v_exp_f32_e32 v60, v60
	v_add_f32_e32 v151, v62, v78
	v_exp_f32_e32 v61, v61
	v_exp_f32_e32 v63, v63
	v_cvt_pk_bf16_f32 v59, v159, v160
	v_exp_f32_e32 v160, v33
	s_waitcnt lgkmcnt(5)
	v_mfma_f32_32x32x16_bf16 v[16:31], v[68:71], v[92:95], v[16:31]
	v_cvt_pk_bf16_f32 v57, v153, v154
	v_cvt_pk_bf16_f32 v58, v155, v156
	v_add_f32_e32 v48, v60, v48
	v_add_f32_e32 v51, v61, v51
	v_cvt_pk_bf16_f32 v49, v49, v50
	s_waitcnt lgkmcnt(4)
	v_mfma_f32_32x32x16_bf16 v[0:15], v[80:83], v[92:95], v[0:15]
	v_readfirstlane_b32 s18, v171
	s_add_u32 m0, s18, 0x7600
	s_nop 0
	global_load_lds_dwordx4 v168, s[12:13] offset:2560
	v_exp_f32_e32 v95, v32
	v_add_f32_e32 v32, v63, v76
	v_add_f32_e32 v163, v160, v51
	v_add_f32_e32 v161, v95, v48
	v_cvt_pk_bf16_f32 v48, v77, v162
	v_cvt_pk_bf16_f32 v51, v62, v63
	s_waitcnt lgkmcnt(3)
	v_mfma_f32_32x32x16_bf16 v[78:93], v[52:55], v[96:99], 0
	v_cvt_pk_bf16_f32 v50, v60, v61
	v_exp_f32_e32 v60, v34
	v_exp_f32_e32 v61, v35
	v_exp_f32_e32 v36, v36
	v_exp_f32_e32 v37, v37
	v_exp_f32_e32 v38, v38
	v_exp_f32_e32 v39, v39
	s_waitcnt lgkmcnt(2)
	v_mfma_f32_32x32x16_bf16 v[62:77], v[72:75], v[96:99], 0
	ds_read_b128 v[52:55], v166
	ds_read_b128 v[152:155], v166 offset:4096
	v_add_f32_e32 v151, v60, v151
	v_add_f32_e32 v162, v61, v32
	s_waitcnt lgkmcnt(3)
	v_mfma_f32_32x32x16_bf16 v[78:93], v[112:115], v[100:103], v[78:93]
	v_add_f32_e32 v112, v36, v161
	v_add_f32_e32 v113, v37, v163
	v_add_f32_e32 v114, v38, v151
	v_exp_f32_e32 v115, v40
	v_add_f32_e32 v40, v39, v162
	ds_read_b128 v[32:35], v167
	ds_read_b128 v[156:159], v167 offset:4096
	s_waitcnt lgkmcnt(4)
	v_mfma_f32_32x32x16_bf16 v[62:77], v[116:119], v[100:103], v[62:77]
	v_exp_f32_e32 v116, v41
	v_add_f32_e32 v41, v115, v112
	s_min_u32 s9, s3, s2
	s_lshl_b32 s9, s9, 6
	v_add_f32_e32 v112, v116, v113
	s_waitcnt lgkmcnt(3)
	v_mfma_f32_32x32x16_bf16 v[78:93], v[52:55], v[104:107], v[78:93]
	v_cvt_pk_bf16_f32 v54, v36, v37
	v_exp_f32_e32 v37, v42
	v_cvt_pk_bf16_f32 v55, v38, v39
	v_exp_f32_e32 v38, v43
	v_exp_f32_e32 v39, v44
	v_exp_f32_e32 v44, v45
	v_exp_f32_e32 v45, v46
	v_exp_f32_e32 v46, v47
	v_cvt_pk_bf16_f32 v52, v95, v160
	v_cvt_pk_bf16_f32 v53, v60, v61
	v_add_f32_e32 v36, v37, v114
	v_add_f32_e32 v43, v38, v40
	v_add_f32_e32 v40, v39, v41
	v_add_f32_e32 v42, v44, v112
	v_add_f32_e32 v41, v45, v36
	v_add_f32_e32 v43, v46, v43
	v_cvt_pk_bf16_f32 v36, v115, v116
	v_cvt_pk_bf16_f32 v37, v37, v38
	v_cvt_pk_bf16_f32 v38, v39, v44
	v_cvt_pk_bf16_f32 v39, v45, v46
	s_waitcnt lgkmcnt(1)
	v_mfma_f32_32x32x16_bf16 v[78:93], v[32:35], v[108:111], v[78:93]
	s_waitcnt lgkmcnt(0)
	s_barrier
	v_mad_u64_u32 v[32:33], s[18:19], s9, v237, v[132:133]
	global_load_dwordx4 v[112:115], v[32:33], off offset:2048
	global_load_dwordx4 v[116:119], v[136:137], off
	v_add_f32_e64 v32, v40, v42
	v_add_f32_e64 v33, v41, v43
	s_waitcnt vmcnt(4)
	ds_write_b128 v142, v[120:123]
	s_waitcnt vmcnt(3)
	ds_write_b128 v142, v[124:127] offset:8192
	v_mfma_f32_32x32x16_bf16 v[62:77], v[152:155], v[104:107], v[62:77]
	v_add_f32_e32 v32, v32, v33
	v_add_f32_e32 v150, v150, v32
	s_waitcnt lgkmcnt(2)
	v_mfma_f32_32x32x16_bf16 v[62:77], v[156:159], v[108:111], v[62:77]
	ds_read_b128 v[32:35], v144 offset:24576
	ds_read_b128 v[40:43], v144 offset:28672
	ds_read_b128 v[44:47], v141 offset:24576
	ds_read_b128 v[120:123], v141 offset:28672
	v_exp_f32_e32 v60, v78
	s_waitcnt lgkmcnt(3)
	v_mfma_f32_32x32x16_bf16 v[16:31], v[32:35], v[56:59], v[16:31]
	v_exp_f32_e32 v61, v79
	v_exp_f32_e32 v95, v80
	v_exp_f32_e32 v81, v81
	ds_read_b128 v[152:155], v140 offset:24576
	ds_read_b128 v[156:159], v140 offset:28672
	s_waitcnt lgkmcnt(4)
	v_mfma_f32_32x32x16_bf16 v[0:15], v[40:43], v[56:59], v[0:15]
	v_exp_f32_e32 v82, v82
	v_exp_f32_e32 v83, v83
	v_add_f32_e32 v78, v82, v60
	v_add_f32_e32 v79, v83, v61
	s_waitcnt lgkmcnt(2)
	v_mfma_f32_32x32x16_bf16 v[0:15], v[120:123], v[48:51], v[0:15]
	ds_read_b128 v[56:59], v139 offset:24576
	ds_read_b128 v[160:163], v139 offset:28672
	ds_read_b128 v[40:43], v164 offset:16384
	ds_read_b128 v[32:35], v164 offset:20480
	v_cvt_pk_bf16_f32 v82, v82, v83
	v_exp_f32_e32 v151, v62
	v_exp_f32_e32 v64, v64
	v_exp_f32_e32 v65, v65
	v_mfma_f32_32x32x16_bf16 v[16:31], v[44:47], v[48:51], v[16:31]
	v_exp_f32_e32 v44, v84
	v_exp_f32_e32 v45, v85
	v_exp_f32_e32 v84, v86
	v_exp_f32_e32 v85, v87
	v_add_f32_e32 v46, v44, v95
	v_add_f32_e32 v47, v45, v81
	v_add_f32_e32 v48, v84, v78
	s_waitcnt lgkmcnt(4)
	v_mfma_f32_32x32x16_bf16 v[0:15], v[156:159], v[52:55], v[0:15]
	v_add_f32_e32 v49, v85, v79
	v_exp_f32_e32 v78, v88
	v_exp_f32_e32 v79, v89
	v_exp_f32_e32 v87, v92
	v_cvt_pk_bf16_f32 v83, v44, v45
	v_exp_f32_e32 v44, v90
	v_mfma_f32_32x32x16_bf16 v[16:31], v[152:155], v[52:55], v[16:31]
	v_exp_f32_e32 v45, v91
	v_exp_f32_e32 v92, v93
	v_add_f32_e32 v46, v78, v46
	v_add_f32_e32 v47, v79, v47
	ds_read_b128 v[124:127], v165 offset:16384
	ds_read_b128 v[120:123], v165 offset:20480
	s_waitcnt lgkmcnt(4)
	v_mfma_f32_32x32x16_bf16 v[0:15], v[160:163], v[36:39], v[0:15]
	v_exp_f32_e32 v160, v63
	v_cvt_pk_bf16_f32 v80, v60, v61
	v_cvt_pk_bf16_f32 v81, v95, v81
	v_add_f32_e32 v48, v44, v48
	v_add_f32_e32 v49, v45, v49
	v_add_f32_e32 v46, v87, v46
	v_add_f32_e32 v47, v92, v47
	v_mfma_f32_32x32x16_bf16 v[16:31], v[56:59], v[36:39], v[16:31]
	v_add_f32_e32 v161, v151, v48
	v_add_f32_e32 v162, v160, v49
	v_cvt_pk_bf16_f32 v84, v84, v85
	v_cvt_pk_bf16_f32 v85, v78, v79
	v_cvt_pk_bf16_f32 v86, v44, v45
	v_add_f32_e32 v78, v64, v46
	v_add_f32_e32 v79, v65, v47
	s_waitcnt lgkmcnt(3)
	v_mfma_f32_32x32x16_bf16 v[48:63], v[40:43], v[96:99], 0
	ds_read_b128 v[88:91], v166 offset:16384
	ds_read_b128 v[152:155], v166 offset:20480
	v_exp_f32_e32 v66, v66
	v_exp_f32_e32 v67, v67
	v_exp_f32_e32 v68, v68
	v_exp_f32_e32 v69, v69
	v_cvt_pk_bf16_f32 v87, v87, v92
	s_waitcnt lgkmcnt(4)
	v_mfma_f32_32x32x16_bf16 v[32:47], v[32:35], v[96:99], 0
	ds_read_b128 v[156:159], v167 offset:16384
	ds_read_b128 v[92:95], v167 offset:20480
	v_add_f32_e32 v161, v66, v161
	v_add_f32_e32 v162, v67, v162
	v_add_f32_e32 v78, v68, v78
	v_add_f32_e32 v79, v69, v79
	s_waitcnt lgkmcnt(5)
	v_mfma_f32_32x32x16_bf16 v[48:63], v[124:127], v[100:103], v[48:63]
	v_exp_f32_e32 v70, v70
	v_exp_f32_e32 v71, v71
	s_add_i32 s9, s3, 2
	s_add_i32 s3, s3, -2
	v_lshl_add_u64 v[136:137], v[136:137], 0, s[22:23]
	s_waitcnt lgkmcnt(4)
	v_mfma_f32_32x32x16_bf16 v[32:47], v[120:123], v[100:103], v[32:47]
	v_add_f32_e32 v120, v70, v161
	v_add_f32_e32 v121, v71, v162
	s_cmp_lt_u32 s3, s2
	s_mov_b32 s3, s9
	s_waitcnt lgkmcnt(3)
	v_mfma_f32_32x32x16_bf16 v[48:63], v[88:91], v[104:107], v[48:63]
	v_cvt_pk_bf16_f32 v91, v68, v69
	v_exp_f32_e32 v68, v72
	v_exp_f32_e32 v69, v73
	v_exp_f32_e32 v72, v74
	v_exp_f32_e32 v73, v75
	v_exp_f32_e32 v74, v76
	v_exp_f32_e32 v75, v77
	s_waitcnt lgkmcnt(2)
	v_mfma_f32_32x32x16_bf16 v[32:47], v[152:155], v[104:107], v[32:47]
	v_cvt_pk_bf16_f32 v88, v151, v160
	v_cvt_pk_bf16_f32 v89, v64, v65
	v_cvt_pk_bf16_f32 v90, v66, v67
	v_add_f32_e32 v65, v68, v78
	v_add_f32_e32 v67, v69, v79
	s_waitcnt lgkmcnt(1)
	v_mfma_f32_32x32x16_bf16 v[48:63], v[156:159], v[108:111], v[48:63]
	v_add_f32_e32 v64, v72, v120
	v_add_f32_e32 v66, v73, v121
	v_add_f32_e32 v65, v74, v65
	v_add_f32_e32 v67, v75, v67
	s_waitcnt lgkmcnt(0)
	v_mfma_f32_32x32x16_bf16 v[32:47], v[92:95], v[108:111], v[32:47]
	v_cvt_pk_bf16_f32 v92, v70, v71
	v_cvt_pk_bf16_f32 v93, v68, v69
	v_cvt_pk_bf16_f32 v94, v72, v73
	v_cvt_pk_bf16_f32 v95, v74, v75
	v_add_f32_e64 v64, v64, v66
	v_add_f32_e64 v65, v65, v67
	s_waitcnt lgkmcnt(0)
	s_barrier
	v_add_f32_e32 v64, v64, v65
	v_add_f32_e32 v150, v150, v64
.Lpeel_1:
	s_add_i32 s9, s3, -1
	s_min_u32 s9, s9, s2
	s_lshl_b32 s9, s9, 6
	s_waitcnt vmcnt(1)
	ds_write_b128 v142, v[112:115] offset:16384
	s_waitcnt vmcnt(0)
	ds_write_b128 v142, v[116:119] offset:24576
	v_mad_u64_u32 v[64:65], s[18:19], s9, v237, v[132:133]
	global_load_dwordx4 v[120:123], v[64:65], off offset:2048
	global_load_dwordx4 v[124:127], v[136:137], off offset:-128
	ds_read_b128 v[64:67], v144 offset:8192
	ds_read_b128 v[68:71], v144 offset:12288
	ds_read_b128 v[72:75], v141 offset:8192
	ds_read_b128 v[76:79], v141 offset:12288
	v_exp_f32_e32 v151, v48
	v_exp_f32_e32 v152, v49
	s_waitcnt lgkmcnt(3)
	v_mfma_f32_32x32x16_bf16 v[16:31], v[64:67], v[80:83], v[16:31]
	v_exp_f32_e32 v153, v50
	v_exp_f32_e32 v154, v51
	ds_read_b128 v[48:51], v140 offset:8192
	ds_read_b128 v[64:67], v140 offset:12288
	v_exp_f32_e32 v155, v52
	s_waitcnt lgkmcnt(4)
	v_mfma_f32_32x32x16_bf16 v[0:15], v[68:71], v[80:83], v[0:15]
	v_exp_f32_e32 v156, v53
	v_exp_f32_e32 v159, v54
	v_exp_f32_e32 v160, v55
	v_exp_f32_e32 v162, v57
	s_waitcnt lgkmcnt(3)
	v_mfma_f32_32x32x16_bf16 v[16:31], v[72:75], v[84:87], v[16:31]
	ds_read_b128 v[68:71], v139 offset:8192
	ds_read_b128 v[80:83], v139 offset:12288
	v_add_f32_e32 v157, v155, v151
	v_add_f32_e32 v158, v156, v152
	ds_read_b128 v[52:55], v164
	ds_read_b128 v[72:75], v164 offset:4096
	v_add_f32_e32 v161, v159, v153
	s_waitcnt lgkmcnt(6)
	v_mfma_f32_32x32x16_bf16 v[0:15], v[76:79], v[84:87], v[0:15]
	v_exp_f32_e32 v77, v56
	v_add_f32_e32 v76, v160, v154
	v_exp_f32_e32 v62, v62
	ds_read_b128 v[112:115], v165
	ds_read_b128 v[116:119], v165 offset:4096
	v_cvt_pk_bf16_f32 v56, v151, v152
	s_waitcnt lgkmcnt(7)
	v_mfma_f32_32x32x16_bf16 v[16:31], v[48:51], v[88:91], v[16:31]
	v_exp_f32_e32 v49, v58
	v_exp_f32_e32 v50, v59
	v_add_f32_e32 v48, v77, v157
	v_add_f32_e32 v51, v162, v158
	v_add_f32_e32 v78, v49, v161
	v_add_f32_e32 v76, v50, v76
	s_waitcnt lgkmcnt(6)
	v_mfma_f32_32x32x16_bf16 v[0:15], v[64:67], v[88:91], v[0:15]
	v_exp_f32_e32 v60, v60
	v_add_f32_e32 v151, v62, v78
	v_exp_f32_e32 v61, v61
	v_exp_f32_e32 v63, v63
	v_cvt_pk_bf16_f32 v59, v159, v160
	v_exp_f32_e32 v160, v33
	s_waitcnt lgkmcnt(5)
	v_mfma_f32_32x32x16_bf16 v[16:31], v[68:71], v[92:95], v[16:31]
	v_cvt_pk_bf16_f32 v57, v153, v154
	v_cvt_pk_bf16_f32 v58, v155, v156
	v_add_f32_e32 v48, v60, v48
	v_add_f32_e32 v51, v61, v51
	v_cvt_pk_bf16_f32 v49, v49, v50
	s_waitcnt lgkmcnt(4)
	v_mfma_f32_32x32x16_bf16 v[0:15], v[80:83], v[92:95], v[0:15]
	v_readfirstlane_b32 s18, v171
	s_add_u32 m0, s18, 0x95e0
	s_nop 0
	global_load_lds_dwordx4 v168, s[12:13] offset:2592
	v_exp_f32_e32 v95, v32
	v_add_f32_e32 v32, v63, v76
	v_add_f32_e32 v163, v160, v51
	v_add_f32_e32 v161, v95, v48
	v_cvt_pk_bf16_f32 v48, v77, v162
	v_cvt_pk_bf16_f32 v51, v62, v63
	s_waitcnt lgkmcnt(3)
	v_mfma_f32_32x32x16_bf16 v[78:93], v[52:55], v[96:99], 0
	v_cvt_pk_bf16_f32 v50, v60, v61
	v_exp_f32_e32 v60, v34
	v_exp_f32_e32 v61, v35
	v_exp_f32_e32 v36, v36
	v_exp_f32_e32 v37, v37
	v_exp_f32_e32 v38, v38
	v_exp_f32_e32 v39, v39
	s_waitcnt lgkmcnt(2)
	v_mfma_f32_32x32x16_bf16 v[62:77], v[72:75], v[96:99], 0
	ds_read_b128 v[52:55], v166
	ds_read_b128 v[152:155], v166 offset:4096
	v_add_f32_e32 v151, v60, v151
	v_add_f32_e32 v162, v61, v32
	s_waitcnt lgkmcnt(3)
	v_mfma_f32_32x32x16_bf16 v[78:93], v[112:115], v[100:103], v[78:93]
	v_add_f32_e32 v112, v36, v161
	v_add_f32_e32 v113, v37, v163
	v_add_f32_e32 v114, v38, v151
	v_exp_f32_e32 v115, v40
	v_add_f32_e32 v40, v39, v162
	ds_read_b128 v[32:35], v167
	ds_read_b128 v[156:159], v167 offset:4096
	s_waitcnt lgkmcnt(4)
	v_mfma_f32_32x32x16_bf16 v[62:77], v[116:119], v[100:103], v[62:77]
	v_exp_f32_e32 v116, v41
	v_add_f32_e32 v41, v115, v112
	s_min_u32 s9, s3, s2
	s_lshl_b32 s9, s9, 6
	v_add_f32_e32 v112, v116, v113
	s_waitcnt lgkmcnt(3)
	v_mfma_f32_32x32x16_bf16 v[78:93], v[52:55], v[104:107], v[78:93]
	v_cvt_pk_bf16_f32 v54, v36, v37
	v_exp_f32_e32 v37, v42
	v_cvt_pk_bf16_f32 v55, v38, v39
	v_exp_f32_e32 v38, v43
	v_exp_f32_e32 v39, v44
	v_exp_f32_e32 v44, v45
	v_exp_f32_e32 v45, v46
	v_exp_f32_e32 v46, v47
	v_cvt_pk_bf16_f32 v52, v95, v160
	v_cvt_pk_bf16_f32 v53, v60, v61
	v_add_f32_e32 v36, v37, v114
	v_add_f32_e32 v43, v38, v40
	v_add_f32_e32 v40, v39, v41
	v_add_f32_e32 v42, v44, v112
	v_add_f32_e32 v41, v45, v36
	v_add_f32_e32 v43, v46, v43
	v_cvt_pk_bf16_f32 v36, v115, v116
	v_cvt_pk_bf16_f32 v37, v37, v38
	v_cvt_pk_bf16_f32 v38, v39, v44
	v_cvt_pk_bf16_f32 v39, v45, v46
	s_waitcnt lgkmcnt(1)
	v_mfma_f32_32x32x16_bf16 v[78:93], v[32:35], v[108:111], v[78:93]
	s_waitcnt lgkmcnt(0)
	s_barrier
	v_mad_u64_u32 v[32:33], s[18:19], s9, v237, v[132:133]
	global_load_dwordx4 v[112:115], v[32:33], off offset:2048
	global_load_dwordx4 v[116:119], v[136:137], off
	v_add_f32_e64 v32, v40, v42
	v_add_f32_e64 v33, v41, v43
	s_waitcnt vmcnt(4)
	ds_write_b128 v142, v[120:123]
	s_waitcnt vmcnt(3)
	ds_write_b128 v142, v[124:127] offset:8192
	v_mfma_f32_32x32x16_bf16 v[62:77], v[152:155], v[104:107], v[62:77]
	v_add_f32_e32 v32, v32, v33
	v_add_f32_e32 v150, v150, v32
	s_waitcnt lgkmcnt(2)
	v_mfma_f32_32x32x16_bf16 v[62:77], v[156:159], v[108:111], v[62:77]
	ds_read_b128 v[32:35], v144 offset:24576
	ds_read_b128 v[40:43], v144 offset:28672
	ds_read_b128 v[44:47], v141 offset:24576
	ds_read_b128 v[120:123], v141 offset:28672
	v_exp_f32_e32 v60, v78
	s_waitcnt lgkmcnt(3)
	v_mfma_f32_32x32x16_bf16 v[16:31], v[32:35], v[56:59], v[16:31]
	v_exp_f32_e32 v61, v79
	v_exp_f32_e32 v95, v80
	v_exp_f32_e32 v81, v81
	ds_read_b128 v[152:155], v140 offset:24576
	ds_read_b128 v[156:159], v140 offset:28672
	s_waitcnt lgkmcnt(4)
	v_mfma_f32_32x32x16_bf16 v[0:15], v[40:43], v[56:59], v[0:15]
	v_exp_f32_e32 v82, v82
	v_exp_f32_e32 v83, v83
	v_add_f32_e32 v78, v82, v60
	v_add_f32_e32 v79, v83, v61
	s_waitcnt lgkmcnt(2)
	v_mfma_f32_32x32x16_bf16 v[0:15], v[120:123], v[48:51], v[0:15]
	ds_read_b128 v[56:59], v139 offset:24576
	ds_read_b128 v[160:163], v139 offset:28672
	ds_read_b128 v[40:43], v164 offset:16384
	ds_read_b128 v[32:35], v164 offset:20480
	v_cvt_pk_bf16_f32 v82, v82, v83
	v_exp_f32_e32 v151, v62
	v_exp_f32_e32 v64, v64
	v_exp_f32_e32 v65, v65
	v_mfma_f32_32x32x16_bf16 v[16:31], v[44:47], v[48:51], v[16:31]
	v_exp_f32_e32 v44, v84
	v_exp_f32_e32 v45, v85
	v_exp_f32_e32 v84, v86
	v_exp_f32_e32 v85, v87
	v_add_f32_e32 v46, v44, v95
	v_add_f32_e32 v47, v45, v81
	v_add_f32_e32 v48, v84, v78
	s_waitcnt lgkmcnt(4)
	v_mfma_f32_32x32x16_bf16 v[0:15], v[156:159], v[52:55], v[0:15]
	v_add_f32_e32 v49, v85, v79
	v_exp_f32_e32 v78, v88
	v_exp_f32_e32 v79, v89
	v_exp_f32_e32 v87, v92
	v_cvt_pk_bf16_f32 v83, v44, v45
	v_exp_f32_e32 v44, v90
	v_mfma_f32_32x32x16_bf16 v[16:31], v[152:155], v[52:55], v[16:31]
	v_exp_f32_e32 v45, v91
	v_exp_f32_e32 v92, v93
	v_add_f32_e32 v46, v78, v46
	v_add_f32_e32 v47, v79, v47
	ds_read_b128 v[124:127], v165 offset:16384
	ds_read_b128 v[120:123], v165 offset:20480
	s_waitcnt lgkmcnt(4)
	v_mfma_f32_32x32x16_bf16 v[0:15], v[160:163], v[36:39], v[0:15]
	v_exp_f32_e32 v160, v63
	v_cvt_pk_bf16_f32 v80, v60, v61
	v_cvt_pk_bf16_f32 v81, v95, v81
	v_add_f32_e32 v48, v44, v48
	v_add_f32_e32 v49, v45, v49
	v_add_f32_e32 v46, v87, v46
	v_add_f32_e32 v47, v92, v47
	v_mfma_f32_32x32x16_bf16 v[16:31], v[56:59], v[36:39], v[16:31]
	v_add_f32_e32 v161, v151, v48
	v_add_f32_e32 v162, v160, v49
	v_cvt_pk_bf16_f32 v84, v84, v85
	v_cvt_pk_bf16_f32 v85, v78, v79
	v_cvt_pk_bf16_f32 v86, v44, v45
	v_add_f32_e32 v78, v64, v46
	v_add_f32_e32 v79, v65, v47
	s_waitcnt lgkmcnt(3)
	v_mfma_f32_32x32x16_bf16 v[48:63], v[40:43], v[96:99], 0
	ds_read_b128 v[88:91], v166 offset:16384
	ds_read_b128 v[152:155], v166 offset:20480
	v_exp_f32_e32 v66, v66
	v_exp_f32_e32 v67, v67
	v_exp_f32_e32 v68, v68
	v_exp_f32_e32 v69, v69
	v_cvt_pk_bf16_f32 v87, v87, v92
	s_waitcnt lgkmcnt(4)
	v_mfma_f32_32x32x16_bf16 v[32:47], v[32:35], v[96:99], 0
	ds_read_b128 v[156:159], v167 offset:16384
	ds_read_b128 v[92:95], v167 offset:20480
	v_add_f32_e32 v161, v66, v161
	v_add_f32_e32 v162, v67, v162
	v_add_f32_e32 v78, v68, v78
	v_add_f32_e32 v79, v69, v79
	s_waitcnt lgkmcnt(5)
	v_mfma_f32_32x32x16_bf16 v[48:63], v[124:127], v[100:103], v[48:63]
	v_exp_f32_e32 v70, v70
	v_exp_f32_e32 v71, v71
	s_add_i32 s9, s3, 2
	s_add_i32 s3, s3, -2
	v_lshl_add_u64 v[136:137], v[136:137], 0, s[22:23]
	s_waitcnt lgkmcnt(4)
	v_mfma_f32_32x32x16_bf16 v[32:47], v[120:123], v[100:103], v[32:47]
	v_add_f32_e32 v120, v70, v161
	v_add_f32_e32 v121, v71, v162
	s_cmp_lt_u32 s3, s2
	s_mov_b32 s3, s9
	s_waitcnt lgkmcnt(3)
	v_mfma_f32_32x32x16_bf16 v[48:63], v[88:91], v[104:107], v[48:63]
	v_cvt_pk_bf16_f32 v91, v68, v69
	v_exp_f32_e32 v68, v72
	v_exp_f32_e32 v69, v73
	v_exp_f32_e32 v72, v74
	v_exp_f32_e32 v73, v75
	v_exp_f32_e32 v74, v76
	v_exp_f32_e32 v75, v77
	s_waitcnt lgkmcnt(2)
	v_mfma_f32_32x32x16_bf16 v[32:47], v[152:155], v[104:107], v[32:47]
	v_cvt_pk_bf16_f32 v88, v151, v160
	v_cvt_pk_bf16_f32 v89, v64, v65
	v_cvt_pk_bf16_f32 v90, v66, v67
	v_add_f32_e32 v65, v68, v78
	v_add_f32_e32 v67, v69, v79
	s_waitcnt lgkmcnt(1)
	v_mfma_f32_32x32x16_bf16 v[48:63], v[156:159], v[108:111], v[48:63]
	v_add_f32_e32 v64, v72, v120
	v_add_f32_e32 v66, v73, v121
	v_add_f32_e32 v65, v74, v65
	v_add_f32_e32 v67, v75, v67
	s_waitcnt lgkmcnt(0)
	v_mfma_f32_32x32x16_bf16 v[32:47], v[92:95], v[108:111], v[32:47]
	v_cvt_pk_bf16_f32 v92, v70, v71
	v_cvt_pk_bf16_f32 v93, v68, v69
	v_cvt_pk_bf16_f32 v94, v72, v73
	v_cvt_pk_bf16_f32 v95, v74, v75
	v_add_f32_e64 v64, v64, v66
	v_add_f32_e64 v65, v65, v67
	s_waitcnt lgkmcnt(0)
	s_barrier
	v_add_f32_e32 v64, v64, v65
	v_add_f32_e32 v150, v150, v64
.Lpeel_2:
	s_add_i32 s9, s3, -1
	s_min_u32 s9, s9, s2
	s_lshl_b32 s9, s9, 6
	s_waitcnt vmcnt(1)
	ds_write_b128 v142, v[112:115] offset:16384
	s_waitcnt vmcnt(0)
	ds_write_b128 v142, v[116:119] offset:24576
	v_mad_u64_u32 v[64:65], s[18:19], s9, v237, v[132:133]
	global_load_dwordx4 v[120:123], v[64:65], off offset:2048
	global_load_dwordx4 v[124:127], v[136:137], off offset:-128
	ds_read_b128 v[64:67], v144 offset:8192
	ds_read_b128 v[68:71], v144 offset:12288
	ds_read_b128 v[72:75], v141 offset:8192
	ds_read_b128 v[76:79], v141 offset:12288
	v_exp_f32_e32 v151, v48
	v_exp_f32_e32 v152, v49
	s_waitcnt lgkmcnt(3)
	v_mfma_f32_32x32x16_bf16 v[16:31], v[64:67], v[80:83], v[16:31]
	v_exp_f32_e32 v153, v50
	v_exp_f32_e32 v154, v51
	ds_read_b128 v[48:51], v140 offset:8192
	ds_read_b128 v[64:67], v140 offset:12288
	v_exp_f32_e32 v155, v52
	s_waitcnt lgkmcnt(4)
	v_mfma_f32_32x32x16_bf16 v[0:15], v[68:71], v[80:83], v[0:15]
	v_exp_f32_e32 v156, v53
	v_exp_f32_e32 v159, v54
	v_exp_f32_e32 v160, v55
	v_exp_f32_e32 v162, v57
	s_waitcnt lgkmcnt(3)
	v_mfma_f32_32x32x16_bf16 v[16:31], v[72:75], v[84:87], v[16:31]
	ds_read_b128 v[68:71], v139 offset:8192
	ds_read_b128 v[80:83], v139 offset:12288
	v_add_f32_e32 v157, v155, v151
	v_add_f32_e32 v158, v156, v152
	ds_read_b128 v[52:55], v164
	ds_read_b128 v[72:75], v164 offset:4096
	v_add_f32_e32 v161, v159, v153
	s_waitcnt lgkmcnt(6)
	v_mfma_f32_32x32x16_bf16 v[0:15], v[76:79], v[84:87], v[0:15]
	v_exp_f32_e32 v77, v56
	v_add_f32_e32 v76, v160, v154
	v_exp_f32_e32 v62, v62
	ds_read_b128 v[112:115], v165
	ds_read_b128 v[116:119], v165 offset:4096
	v_cvt_pk_bf16_f32 v56, v151, v152
	s_waitcnt lgkmcnt(7)
	v_mfma_f32_32x32x16_bf16 v[16:31], v[48:51], v[88:91], v[16:31]
	v_exp_f32_e32 v49, v58
	v_exp_f32_e32 v50, v59
	v_add_f32_e32 v48, v77, v157
	v_add_f32_e32 v51, v162, v158
	v_add_f32_e32 v78, v49, v161
	v_add_f32_e32 v76, v50, v76
	s_waitcnt lgkmcnt(6)
	v_mfma_f32_32x32x16_bf16 v[0:15], v[64:67], v[88:91], v[0:15]
	v_exp_f32_e32 v60, v60
	v_add_f32_e32 v151, v62, v78
	v_exp_f32_e32 v61, v61
	v_exp_f32_e32 v63, v63
	v_cvt_pk_bf16_f32 v59, v159, v160
	v_exp_f32_e32 v160, v33
	s_waitcnt lgkmcnt(5)
	v_mfma_f32_32x32x16_bf16 v[16:31], v[68:71], v[92:95], v[16:31]
	v_cvt_pk_bf16_f32 v57, v153, v154
	v_cvt_pk_bf16_f32 v58, v155, v156
	v_add_f32_e32 v48, v60, v48
	v_add_f32_e32 v51, v61, v51
	v_cvt_pk_bf16_f32 v49, v49, v50
	s_waitcnt lgkmcnt(4)
	v_mfma_f32_32x32x16_bf16 v[0:15], v[80:83], v[92:95], v[0:15]
	v_readfirstlane_b32 s18, v171
	s_add_u32 m0, s18, 0xb5c0
	s_nop 0
	global_load_lds_dwordx4 v168, s[12:13] offset:2624
	v_exp_f32_e32 v95, v32
	v_add_f32_e32 v32, v63, v76
	v_add_f32_e32 v163, v160, v51
	v_add_f32_e32 v161, v95, v48
	v_cvt_pk_bf16_f32 v48, v77, v162
	v_cvt_pk_bf16_f32 v51, v62, v63
	s_waitcnt lgkmcnt(3)
	v_mfma_f32_32x32x16_bf16 v[78:93], v[52:55], v[96:99], 0
	v_cvt_pk_bf16_f32 v50, v60, v61
	v_exp_f32_e32 v60, v34
	v_exp_f32_e32 v61, v35
	v_exp_f32_e32 v36, v36
	v_exp_f32_e32 v37, v37
	v_exp_f32_e32 v38, v38
	v_exp_f32_e32 v39, v39
	s_waitcnt lgkmcnt(2)
	v_mfma_f32_32x32x16_bf16 v[62:77], v[72:75], v[96:99], 0
	ds_read_b128 v[52:55], v166
	ds_read_b128 v[152:155], v166 offset:4096
	v_add_f32_e32 v151, v60, v151
	v_add_f32_e32 v162, v61, v32
	s_waitcnt lgkmcnt(3)
	v_mfma_f32_32x32x16_bf16 v[78:93], v[112:115], v[100:103], v[78:93]
	v_add_f32_e32 v112, v36, v161
	v_add_f32_e32 v113, v37, v163
	v_add_f32_e32 v114, v38, v151
	v_exp_f32_e32 v115, v40
	v_add_f32_e32 v40, v39, v162
	ds_read_b128 v[32:35], v167
	ds_read_b128 v[156:159], v167 offset:4096
	s_waitcnt lgkmcnt(4)
	v_mfma_f32_32x32x16_bf16 v[62:77], v[116:119], v[100:103], v[62:77]
	v_exp_f32_e32 v116, v41
	v_add_f32_e32 v41, v115, v112
	s_min_u32 s9, s3, s2
	s_lshl_b32 s9, s9, 6
	v_add_f32_e32 v112, v116, v113
	s_waitcnt lgkmcnt(3)
	v_mfma_f32_32x32x16_bf16 v[78:93], v[52:55], v[104:107], v[78:93]
	v_cvt_pk_bf16_f32 v54, v36, v37
	v_exp_f32_e32 v37, v42
	v_cvt_pk_bf16_f32 v55, v38, v39
	v_exp_f32_e32 v38, v43
	v_exp_f32_e32 v39, v44
	v_exp_f32_e32 v44, v45
	v_exp_f32_e32 v45, v46
	v_exp_f32_e32 v46, v47
	v_cvt_pk_bf16_f32 v52, v95, v160
	v_cvt_pk_bf16_f32 v53, v60, v61
	v_add_f32_e32 v36, v37, v114
	v_add_f32_e32 v43, v38, v40
	v_add_f32_e32 v40, v39, v41
	v_add_f32_e32 v42, v44, v112
	v_add_f32_e32 v41, v45, v36
	v_add_f32_e32 v43, v46, v43
	v_cvt_pk_bf16_f32 v36, v115, v116
	v_cvt_pk_bf16_f32 v37, v37, v38
	v_cvt_pk_bf16_f32 v38, v39, v44
	v_cvt_pk_bf16_f32 v39, v45, v46
	s_waitcnt lgkmcnt(1)
	v_mfma_f32_32x32x16_bf16 v[78:93], v[32:35], v[108:111], v[78:93]
	s_waitcnt lgkmcnt(0)
	s_barrier
	v_mad_u64_u32 v[32:33], s[18:19], s9, v237, v[132:133]
	global_load_dwordx4 v[112:115], v[32:33], off offset:2048
	global_load_dwordx4 v[116:119], v[136:137], off
	v_add_f32_e64 v32, v40, v42
	v_add_f32_e64 v33, v41, v43
	s_waitcnt vmcnt(4)
	ds_write_b128 v142, v[120:123]
	s_waitcnt vmcnt(3)
	ds_write_b128 v142, v[124:127] offset:8192
	v_mfma_f32_32x32x16_bf16 v[62:77], v[152:155], v[104:107], v[62:77]
	v_add_f32_e32 v32, v32, v33
	v_add_f32_e32 v150, v150, v32
	s_waitcnt lgkmcnt(2)
	v_mfma_f32_32x32x16_bf16 v[62:77], v[156:159], v[108:111], v[62:77]
	ds_read_b128 v[32:35], v144 offset:24576
	ds_read_b128 v[40:43], v144 offset:28672
	ds_read_b128 v[44:47], v141 offset:24576
	ds_read_b128 v[120:123], v141 offset:28672
	v_exp_f32_e32 v60, v78
	s_waitcnt lgkmcnt(3)
	v_mfma_f32_32x32x16_bf16 v[16:31], v[32:35], v[56:59], v[16:31]
	v_exp_f32_e32 v61, v79
	v_exp_f32_e32 v95, v80
	v_exp_f32_e32 v81, v81
	ds_read_b128 v[152:155], v140 offset:24576
	ds_read_b128 v[156:159], v140 offset:28672
	s_waitcnt lgkmcnt(4)
	v_mfma_f32_32x32x16_bf16 v[0:15], v[40:43], v[56:59], v[0:15]
	v_exp_f32_e32 v82, v82
	v_exp_f32_e32 v83, v83
	v_add_f32_e32 v78, v82, v60
	v_add_f32_e32 v79, v83, v61
	s_waitcnt lgkmcnt(2)
	v_mfma_f32_32x32x16_bf16 v[0:15], v[120:123], v[48:51], v[0:15]
	ds_read_b128 v[56:59], v139 offset:24576
	ds_read_b128 v[160:163], v139 offset:28672
	ds_read_b128 v[40:43], v164 offset:16384
	ds_read_b128 v[32:35], v164 offset:20480
	v_cvt_pk_bf16_f32 v82, v82, v83
	v_exp_f32_e32 v151, v62
	v_exp_f32_e32 v64, v64
	v_exp_f32_e32 v65, v65
	v_mfma_f32_32x32x16_bf16 v[16:31], v[44:47], v[48:51], v[16:31]
	v_exp_f32_e32 v44, v84
	v_exp_f32_e32 v45, v85
	v_exp_f32_e32 v84, v86
	v_exp_f32_e32 v85, v87
	v_add_f32_e32 v46, v44, v95
	v_add_f32_e32 v47, v45, v81
	v_add_f32_e32 v48, v84, v78
	s_waitcnt lgkmcnt(4)
	v_mfma_f32_32x32x16_bf16 v[0:15], v[156:159], v[52:55], v[0:15]
	v_add_f32_e32 v49, v85, v79
	v_exp_f32_e32 v78, v88
	v_exp_f32_e32 v79, v89
	v_exp_f32_e32 v87, v92
	v_cvt_pk_bf16_f32 v83, v44, v45
	v_exp_f32_e32 v44, v90
	v_mfma_f32_32x32x16_bf16 v[16:31], v[152:155], v[52:55], v[16:31]
	v_exp_f32_e32 v45, v91
	v_exp_f32_e32 v92, v93
	v_add_f32_e32 v46, v78, v46
	v_add_f32_e32 v47, v79, v47
	ds_read_b128 v[124:127], v165 offset:16384
	ds_read_b128 v[120:123], v165 offset:20480
	s_waitcnt lgkmcnt(4)
	v_mfma_f32_32x32x16_bf16 v[0:15], v[160:163], v[36:39], v[0:15]
	v_exp_f32_e32 v160, v63
	v_cvt_pk_bf16_f32 v80, v60, v61
	v_cvt_pk_bf16_f32 v81, v95, v81
	v_add_f32_e32 v48, v44, v48
	v_add_f32_e32 v49, v45, v49
	v_add_f32_e32 v46, v87, v46
	v_add_f32_e32 v47, v92, v47
	v_mfma_f32_32x32x16_bf16 v[16:31], v[56:59], v[36:39], v[16:31]
	v_add_f32_e32 v161, v151, v48
	v_add_f32_e32 v162, v160, v49
	v_cvt_pk_bf16_f32 v84, v84, v85
	v_cvt_pk_bf16_f32 v85, v78, v79
	v_cvt_pk_bf16_f32 v86, v44, v45
	v_add_f32_e32 v78, v64, v46
	v_add_f32_e32 v79, v65, v47
	s_waitcnt lgkmcnt(3)
	v_mfma_f32_32x32x16_bf16 v[48:63], v[40:43], v[96:99], 0
	ds_read_b128 v[88:91], v166 offset:16384
	ds_read_b128 v[152:155], v166 offset:20480
	v_exp_f32_e32 v66, v66
	v_exp_f32_e32 v67, v67
	v_exp_f32_e32 v68, v68
	v_exp_f32_e32 v69, v69
	v_cvt_pk_bf16_f32 v87, v87, v92
	s_waitcnt lgkmcnt(4)
	v_mfma_f32_32x32x16_bf16 v[32:47], v[32:35], v[96:99], 0
	ds_read_b128 v[156:159], v167 offset:16384
	ds_read_b128 v[92:95], v167 offset:20480
	v_add_f32_e32 v161, v66, v161
	v_add_f32_e32 v162, v67, v162
	v_add_f32_e32 v78, v68, v78
	v_add_f32_e32 v79, v69, v79
	s_waitcnt lgkmcnt(5)
	v_mfma_f32_32x32x16_bf16 v[48:63], v[124:127], v[100:103], v[48:63]
	v_exp_f32_e32 v70, v70
	v_exp_f32_e32 v71, v71
	s_add_i32 s9, s3, 2
	s_add_i32 s3, s3, -2
	v_lshl_add_u64 v[136:137], v[136:137], 0, s[22:23]
	s_waitcnt lgkmcnt(4)
	v_mfma_f32_32x32x16_bf16 v[32:47], v[120:123], v[100:103], v[32:47]
	v_add_f32_e32 v120, v70, v161
	v_add_f32_e32 v121, v71, v162
	s_cmp_lt_u32 s3, s2
	s_mov_b32 s3, s9
	s_waitcnt lgkmcnt(3)
	v_mfma_f32_32x32x16_bf16 v[48:63], v[88:91], v[104:107], v[48:63]
	v_cvt_pk_bf16_f32 v91, v68, v69
	v_exp_f32_e32 v68, v72
	v_exp_f32_e32 v69, v73
	v_exp_f32_e32 v72, v74
	v_exp_f32_e32 v73, v75
	v_exp_f32_e32 v74, v76
	v_exp_f32_e32 v75, v77
	s_waitcnt lgkmcnt(2)
	v_mfma_f32_32x32x16_bf16 v[32:47], v[152:155], v[104:107], v[32:47]
	v_cvt_pk_bf16_f32 v88, v151, v160
	v_cvt_pk_bf16_f32 v89, v64, v65
	v_cvt_pk_bf16_f32 v90, v66, v67
	v_add_f32_e32 v65, v68, v78
	v_add_f32_e32 v67, v69, v79
	s_waitcnt lgkmcnt(1)
	v_mfma_f32_32x32x16_bf16 v[48:63], v[156:159], v[108:111], v[48:63]
	v_add_f32_e32 v64, v72, v120
	v_add_f32_e32 v66, v73, v121
	v_add_f32_e32 v65, v74, v65
	v_add_f32_e32 v67, v75, v67
	s_waitcnt lgkmcnt(0)
	v_mfma_f32_32x32x16_bf16 v[32:47], v[92:95], v[108:111], v[32:47]
	v_cvt_pk_bf16_f32 v92, v70, v71
	v_cvt_pk_bf16_f32 v93, v68, v69
	v_cvt_pk_bf16_f32 v94, v72, v73
	v_cvt_pk_bf16_f32 v95, v74, v75
	v_add_f32_e64 v64, v64, v66
	v_add_f32_e64 v65, v65, v67
	s_waitcnt lgkmcnt(0)
	s_barrier
	v_add_f32_e32 v64, v64, v65
	v_add_f32_e32 v150, v150, v64
.Lpeel_3:
	s_add_i32 s9, s3, -1
	s_min_u32 s9, s9, s2
	s_lshl_b32 s9, s9, 6
	s_waitcnt vmcnt(1)
	ds_write_b128 v142, v[112:115] offset:16384
	s_waitcnt vmcnt(0)
	ds_write_b128 v142, v[116:119] offset:24576
	v_mad_u64_u32 v[64:65], s[18:19], s9, v237, v[132:133]
	global_load_dwordx4 v[120:123], v[64:65], off offset:2048
	global_load_dwordx4 v[124:127], v[136:137], off offset:-128
	ds_read_b128 v[64:67], v144 offset:8192
	ds_read_b128 v[68:71], v144 offset:12288
	ds_read_b128 v[72:75], v141 offset:8192
	ds_read_b128 v[76:79], v141 offset:12288
	v_exp_f32_e32 v151, v48
	v_exp_f32_e32 v152, v49
	s_waitcnt lgkmcnt(3)
	v_mfma_f32_32x32x16_bf16 v[16:31], v[64:67], v[80:83], v[16:31]
	v_exp_f32_e32 v153, v50
	v_exp_f32_e32 v154, v51
	ds_read_b128 v[48:51], v140 offset:8192
	ds_read_b128 v[64:67], v140 offset:12288
	v_exp_f32_e32 v155, v52
	s_waitcnt lgkmcnt(4)
	v_mfma_f32_32x32x16_bf16 v[0:15], v[68:71], v[80:83], v[0:15]
	v_exp_f32_e32 v156, v53
	v_exp_f32_e32 v159, v54
	v_exp_f32_e32 v160, v55
	v_exp_f32_e32 v162, v57
	s_waitcnt lgkmcnt(3)
	v_mfma_f32_32x32x16_bf16 v[16:31], v[72:75], v[84:87], v[16:31]
	ds_read_b128 v[68:71], v139 offset:8192
	ds_read_b128 v[80:83], v139 offset:12288
	v_add_f32_e32 v157, v155, v151
	v_add_f32_e32 v158, v156, v152
	ds_read_b128 v[52:55], v164
	ds_read_b128 v[72:75], v164 offset:4096
	v_add_f32_e32 v161, v159, v153
	s_waitcnt lgkmcnt(6)
	v_mfma_f32_32x32x16_bf16 v[0:15], v[76:79], v[84:87], v[0:15]
	v_exp_f32_e32 v77, v56
	v_add_f32_e32 v76, v160, v154
	v_exp_f32_e32 v62, v62
	ds_read_b128 v[112:115], v165
	ds_read_b128 v[116:119], v165 offset:4096
	v_cvt_pk_bf16_f32 v56, v151, v152
	s_waitcnt lgkmcnt(7)
	v_mfma_f32_32x32x16_bf16 v[16:31], v[48:51], v[88:91], v[16:31]
	v_exp_f32_e32 v49, v58
	v_exp_f32_e32 v50, v59
	v_add_f32_e32 v48, v77, v157
	v_add_f32_e32 v51, v162, v158
	v_add_f32_e32 v78, v49, v161
	v_add_f32_e32 v76, v50, v76
	s_waitcnt lgkmcnt(6)
	v_mfma_f32_32x32x16_bf16 v[0:15], v[64:67], v[88:91], v[0:15]
	v_exp_f32_e32 v60, v60
	v_add_f32_e32 v151, v62, v78
	v_exp_f32_e32 v61, v61
	v_exp_f32_e32 v63, v63
	v_cvt_pk_bf16_f32 v59, v159, v160
	v_exp_f32_e32 v160, v33
	s_waitcnt lgkmcnt(5)
	v_mfma_f32_32x32x16_bf16 v[16:31], v[68:71], v[92:95], v[16:31]
	v_cvt_pk_bf16_f32 v57, v153, v154
	v_cvt_pk_bf16_f32 v58, v155, v156
	v_add_f32_e32 v48, v60, v48
	v_add_f32_e32 v51, v61, v51
	v_cvt_pk_bf16_f32 v49, v49, v50
	s_waitcnt lgkmcnt(4)
	v_mfma_f32_32x32x16_bf16 v[0:15], v[80:83], v[92:95], v[0:15]
	v_readfirstlane_b32 s18, v171
	s_add_u32 m0, s18, 0xd5a0
	s_nop 0
	global_load_lds_dwordx4 v168, s[12:13] offset:2656
	v_exp_f32_e32 v95, v32
	v_add_f32_e32 v32, v63, v76
	v_add_f32_e32 v163, v160, v51
	v_add_f32_e32 v161, v95, v48
	v_cvt_pk_bf16_f32 v48, v77, v162
	v_cvt_pk_bf16_f32 v51, v62, v63
	s_waitcnt lgkmcnt(3)
	v_mfma_f32_32x32x16_bf16 v[78:93], v[52:55], v[96:99], 0
	v_cvt_pk_bf16_f32 v50, v60, v61
	v_exp_f32_e32 v60, v34
	v_exp_f32_e32 v61, v35
	v_exp_f32_e32 v36, v36
	v_exp_f32_e32 v37, v37
	v_exp_f32_e32 v38, v38
	v_exp_f32_e32 v39, v39
	s_waitcnt lgkmcnt(2)
	v_mfma_f32_32x32x16_bf16 v[62:77], v[72:75], v[96:99], 0
	ds_read_b128 v[52:55], v166
	ds_read_b128 v[152:155], v166 offset:4096
	v_add_f32_e32 v151, v60, v151
	v_add_f32_e32 v162, v61, v32
	s_waitcnt lgkmcnt(3)
	v_mfma_f32_32x32x16_bf16 v[78:93], v[112:115], v[100:103], v[78:93]
	v_add_f32_e32 v112, v36, v161
	v_add_f32_e32 v113, v37, v163
	v_add_f32_e32 v114, v38, v151
	v_exp_f32_e32 v115, v40
	v_add_f32_e32 v40, v39, v162
	ds_read_b128 v[32:35], v167
	ds_read_b128 v[156:159], v167 offset:4096
	s_waitcnt lgkmcnt(4)
	v_mfma_f32_32x32x16_bf16 v[62:77], v[116:119], v[100:103], v[62:77]
	v_exp_f32_e32 v116, v41
	v_add_f32_e32 v41, v115, v112
	s_min_u32 s9, s3, s2
	s_lshl_b32 s9, s9, 6
	v_add_f32_e32 v112, v116, v113
	s_waitcnt lgkmcnt(3)
	v_mfma_f32_32x32x16_bf16 v[78:93], v[52:55], v[104:107], v[78:93]
	v_cvt_pk_bf16_f32 v54, v36, v37
	v_exp_f32_e32 v37, v42
	v_cvt_pk_bf16_f32 v55, v38, v39
	v_exp_f32_e32 v38, v43
	v_exp_f32_e32 v39, v44
	v_exp_f32_e32 v44, v45
	v_exp_f32_e32 v45, v46
	v_exp_f32_e32 v46, v47
	v_cvt_pk_bf16_f32 v52, v95, v160
	v_cvt_pk_bf16_f32 v53, v60, v61
	v_add_f32_e32 v36, v37, v114
	v_add_f32_e32 v43, v38, v40
	v_add_f32_e32 v40, v39, v41
	v_add_f32_e32 v42, v44, v112
	v_add_f32_e32 v41, v45, v36
	v_add_f32_e32 v43, v46, v43
	v_cvt_pk_bf16_f32 v36, v115, v116
	v_cvt_pk_bf16_f32 v37, v37, v38
	v_cvt_pk_bf16_f32 v38, v39, v44
	v_cvt_pk_bf16_f32 v39, v45, v46
	s_waitcnt lgkmcnt(1)
	v_mfma_f32_32x32x16_bf16 v[78:93], v[32:35], v[108:111], v[78:93]
	s_waitcnt lgkmcnt(0)
	s_barrier
	v_mad_u64_u32 v[32:33], s[18:19], s9, v237, v[132:133]
	global_load_dwordx4 v[112:115], v[32:33], off offset:2048
	global_load_dwordx4 v[116:119], v[136:137], off
	v_add_f32_e64 v32, v40, v42
	v_add_f32_e64 v33, v41, v43
	s_waitcnt vmcnt(4)
	ds_write_b128 v142, v[120:123]
	s_waitcnt vmcnt(3)
	ds_write_b128 v142, v[124:127] offset:8192
	v_mfma_f32_32x32x16_bf16 v[62:77], v[152:155], v[104:107], v[62:77]
	v_add_f32_e32 v32, v32, v33
	v_add_f32_e32 v150, v150, v32
	s_waitcnt lgkmcnt(2)
	v_mfma_f32_32x32x16_bf16 v[62:77], v[156:159], v[108:111], v[62:77]
	ds_read_b128 v[32:35], v144 offset:24576
	ds_read_b128 v[40:43], v144 offset:28672
	ds_read_b128 v[44:47], v141 offset:24576
	ds_read_b128 v[120:123], v141 offset:28672
	v_exp_f32_e32 v60, v78
	s_waitcnt lgkmcnt(3)
	v_mfma_f32_32x32x16_bf16 v[16:31], v[32:35], v[56:59], v[16:31]
	v_exp_f32_e32 v61, v79
	v_exp_f32_e32 v95, v80
	v_exp_f32_e32 v81, v81
	ds_read_b128 v[152:155], v140 offset:24576
	ds_read_b128 v[156:159], v140 offset:28672
	s_waitcnt lgkmcnt(4)
	v_mfma_f32_32x32x16_bf16 v[0:15], v[40:43], v[56:59], v[0:15]
	v_exp_f32_e32 v82, v82
	v_exp_f32_e32 v83, v83
	v_add_f32_e32 v78, v82, v60
	v_add_f32_e32 v79, v83, v61
	s_waitcnt lgkmcnt(2)
	v_mfma_f32_32x32x16_bf16 v[0:15], v[120:123], v[48:51], v[0:15]
	ds_read_b128 v[56:59], v139 offset:24576
	ds_read_b128 v[160:163], v139 offset:28672
	ds_read_b128 v[40:43], v164 offset:16384
	ds_read_b128 v[32:35], v164 offset:20480
	v_cvt_pk_bf16_f32 v82, v82, v83
	v_exp_f32_e32 v151, v62
	v_exp_f32_e32 v64, v64
	v_exp_f32_e32 v65, v65
	v_mfma_f32_32x32x16_bf16 v[16:31], v[44:47], v[48:51], v[16:31]
	v_exp_f32_e32 v44, v84
	v_exp_f32_e32 v45, v85
	v_exp_f32_e32 v84, v86
	v_exp_f32_e32 v85, v87
	v_add_f32_e32 v46, v44, v95
	v_add_f32_e32 v47, v45, v81
	v_add_f32_e32 v48, v84, v78
	s_waitcnt lgkmcnt(4)
	v_mfma_f32_32x32x16_bf16 v[0:15], v[156:159], v[52:55], v[0:15]
	v_add_f32_e32 v49, v85, v79
	v_exp_f32_e32 v78, v88
	v_exp_f32_e32 v79, v89
	v_exp_f32_e32 v87, v92
	v_cvt_pk_bf16_f32 v83, v44, v45
	v_exp_f32_e32 v44, v90
	v_mfma_f32_32x32x16_bf16 v[16:31], v[152:155], v[52:55], v[16:31]
	v_exp_f32_e32 v45, v91
	v_exp_f32_e32 v92, v93
	v_add_f32_e32 v46, v78, v46
	v_add_f32_e32 v47, v79, v47
	ds_read_b128 v[124:127], v165 offset:16384
	ds_read_b128 v[120:123], v165 offset:20480
	s_waitcnt lgkmcnt(4)
	v_mfma_f32_32x32x16_bf16 v[0:15], v[160:163], v[36:39], v[0:15]
	v_exp_f32_e32 v160, v63
	v_cvt_pk_bf16_f32 v80, v60, v61
	v_cvt_pk_bf16_f32 v81, v95, v81
	v_add_f32_e32 v48, v44, v48
	v_add_f32_e32 v49, v45, v49
	v_add_f32_e32 v46, v87, v46
	v_add_f32_e32 v47, v92, v47
	v_mfma_f32_32x32x16_bf16 v[16:31], v[56:59], v[36:39], v[16:31]
	v_add_f32_e32 v161, v151, v48
	v_add_f32_e32 v162, v160, v49
	v_cvt_pk_bf16_f32 v84, v84, v85
	v_cvt_pk_bf16_f32 v85, v78, v79
	v_cvt_pk_bf16_f32 v86, v44, v45
	v_add_f32_e32 v78, v64, v46
	v_add_f32_e32 v79, v65, v47
	s_waitcnt lgkmcnt(3)
	v_mfma_f32_32x32x16_bf16 v[48:63], v[40:43], v[96:99], 0
	ds_read_b128 v[88:91], v166 offset:16384
	ds_read_b128 v[152:155], v166 offset:20480
	v_exp_f32_e32 v66, v66
	v_exp_f32_e32 v67, v67
	v_exp_f32_e32 v68, v68
	v_exp_f32_e32 v69, v69
	v_cvt_pk_bf16_f32 v87, v87, v92
	s_waitcnt lgkmcnt(4)
	v_mfma_f32_32x32x16_bf16 v[32:47], v[32:35], v[96:99], 0
	ds_read_b128 v[156:159], v167 offset:16384
	ds_read_b128 v[92:95], v167 offset:20480
	v_add_f32_e32 v161, v66, v161
	v_add_f32_e32 v162, v67, v162
	v_add_f32_e32 v78, v68, v78
	v_add_f32_e32 v79, v69, v79
	s_waitcnt lgkmcnt(5)
	v_mfma_f32_32x32x16_bf16 v[48:63], v[124:127], v[100:103], v[48:63]
	v_exp_f32_e32 v70, v70
	v_exp_f32_e32 v71, v71
	s_add_i32 s9, s3, 2
	s_add_i32 s3, s3, -2
	v_lshl_add_u64 v[136:137], v[136:137], 0, s[22:23]
	s_waitcnt lgkmcnt(4)
	v_mfma_f32_32x32x16_bf16 v[32:47], v[120:123], v[100:103], v[32:47]
	v_add_f32_e32 v120, v70, v161
	v_add_f32_e32 v121, v71, v162
	s_cmp_lt_u32 s3, s2
	s_mov_b32 s3, s9
	s_waitcnt lgkmcnt(3)
	v_mfma_f32_32x32x16_bf16 v[48:63], v[88:91], v[104:107], v[48:63]
	v_cvt_pk_bf16_f32 v91, v68, v69
	v_exp_f32_e32 v68, v72
	v_exp_f32_e32 v69, v73
	v_exp_f32_e32 v72, v74
	v_exp_f32_e32 v73, v75
	v_exp_f32_e32 v74, v76
	v_exp_f32_e32 v75, v77
	s_waitcnt lgkmcnt(2)
	v_mfma_f32_32x32x16_bf16 v[32:47], v[152:155], v[104:107], v[32:47]
	v_cvt_pk_bf16_f32 v88, v151, v160
	v_cvt_pk_bf16_f32 v89, v64, v65
	v_cvt_pk_bf16_f32 v90, v66, v67
	v_add_f32_e32 v65, v68, v78
	v_add_f32_e32 v67, v69, v79
	s_waitcnt lgkmcnt(1)
	v_mfma_f32_32x32x16_bf16 v[48:63], v[156:159], v[108:111], v[48:63]
	v_add_f32_e32 v64, v72, v120
	v_add_f32_e32 v66, v73, v121
	v_add_f32_e32 v65, v74, v65
	v_add_f32_e32 v67, v75, v67
	s_waitcnt lgkmcnt(0)
	v_mfma_f32_32x32x16_bf16 v[32:47], v[92:95], v[108:111], v[32:47]
	v_cvt_pk_bf16_f32 v92, v70, v71
	v_cvt_pk_bf16_f32 v93, v68, v69
	v_cvt_pk_bf16_f32 v94, v72, v73
	v_cvt_pk_bf16_f32 v95, v74, v75
	v_add_f32_e64 v64, v64, v66
	v_add_f32_e64 v65, v65, v67
	s_waitcnt lgkmcnt(0)
	s_barrier
	v_add_f32_e32 v64, v64, v65
	v_add_f32_e32 v150, v150, v64
.Lpeel_4:
	s_add_i32 s9, s3, -1
	s_min_u32 s9, s9, s2
	s_lshl_b32 s9, s9, 6
	s_waitcnt vmcnt(1)
	ds_write_b128 v142, v[112:115] offset:16384
	s_waitcnt vmcnt(0)
	ds_write_b128 v142, v[116:119] offset:24576
	v_mad_u64_u32 v[64:65], s[18:19], s9, v237, v[132:133]
	global_load_dwordx4 v[120:123], v[64:65], off offset:2048
	global_load_dwordx4 v[124:127], v[136:137], off offset:-128
	ds_read_b128 v[64:67], v144 offset:8192
	ds_read_b128 v[68:71], v144 offset:12288
	ds_read_b128 v[72:75], v141 offset:8192
	ds_read_b128 v[76:79], v141 offset:12288
	v_exp_f32_e32 v151, v48
	v_exp_f32_e32 v152, v49
	s_waitcnt lgkmcnt(3)
	v_mfma_f32_32x32x16_bf16 v[16:31], v[64:67], v[80:83], v[16:31]
	v_exp_f32_e32 v153, v50
	v_exp_f32_e32 v154, v51
	ds_read_b128 v[48:51], v140 offset:8192
	ds_read_b128 v[64:67], v140 offset:12288
	v_exp_f32_e32 v155, v52
	s_waitcnt lgkmcnt(4)
	v_mfma_f32_32x32x16_bf16 v[0:15], v[68:71], v[80:83], v[0:15]
	v_exp_f32_e32 v156, v53
	v_exp_f32_e32 v159, v54
	v_exp_f32_e32 v160, v55
	v_exp_f32_e32 v162, v57
	s_waitcnt lgkmcnt(3)
	v_mfma_f32_32x32x16_bf16 v[16:31], v[72:75], v[84:87], v[16:31]
	ds_read_b128 v[68:71], v139 offset:8192
	ds_read_b128 v[80:83], v139 offset:12288
	v_add_f32_e32 v157, v155, v151
	v_add_f32_e32 v158, v156, v152
	ds_read_b128 v[52:55], v164
	ds_read_b128 v[72:75], v164 offset:4096
	v_add_f32_e32 v161, v159, v153
	s_waitcnt lgkmcnt(6)
	v_mfma_f32_32x32x16_bf16 v[0:15], v[76:79], v[84:87], v[0:15]
	v_exp_f32_e32 v77, v56
	v_add_f32_e32 v76, v160, v154
	v_exp_f32_e32 v62, v62
	ds_read_b128 v[112:115], v165
	ds_read_b128 v[116:119], v165 offset:4096
	v_cvt_pk_bf16_f32 v56, v151, v152
	s_waitcnt lgkmcnt(7)
	v_mfma_f32_32x32x16_bf16 v[16:31], v[48:51], v[88:91], v[16:31]
	v_exp_f32_e32 v49, v58
	v_exp_f32_e32 v50, v59
	v_add_f32_e32 v48, v77, v157
	v_add_f32_e32 v51, v162, v158
	v_add_f32_e32 v78, v49, v161
	v_add_f32_e32 v76, v50, v76
	s_waitcnt lgkmcnt(6)
	v_mfma_f32_32x32x16_bf16 v[0:15], v[64:67], v[88:91], v[0:15]
	v_exp_f32_e32 v60, v60
	v_add_f32_e32 v151, v62, v78
	v_exp_f32_e32 v61, v61
	v_exp_f32_e32 v63, v63
	v_cvt_pk_bf16_f32 v59, v159, v160
	v_exp_f32_e32 v160, v33
	s_waitcnt lgkmcnt(5)
	v_mfma_f32_32x32x16_bf16 v[16:31], v[68:71], v[92:95], v[16:31]
	v_cvt_pk_bf16_f32 v57, v153, v154
	v_cvt_pk_bf16_f32 v58, v155, v156
	v_add_f32_e32 v48, v60, v48
	v_add_f32_e32 v51, v61, v51
	v_cvt_pk_bf16_f32 v49, v49, v50
	s_waitcnt lgkmcnt(4)
	v_mfma_f32_32x32x16_bf16 v[0:15], v[80:83], v[92:95], v[0:15]
	v_readfirstlane_b32 s18, v171
	s_add_u32 m0, s18, 0xfc00
	s_nop 0
	global_load_lds_dwordx4 v168, s[14:15] offset:1024
	v_exp_f32_e32 v95, v32
	v_add_f32_e32 v32, v63, v76
	v_add_f32_e32 v163, v160, v51
	v_add_f32_e32 v161, v95, v48
	v_cvt_pk_bf16_f32 v48, v77, v162
	v_cvt_pk_bf16_f32 v51, v62, v63
	s_waitcnt lgkmcnt(3)
	v_mfma_f32_32x32x16_bf16 v[78:93], v[52:55], v[96:99], 0
	v_cvt_pk_bf16_f32 v50, v60, v61
	v_exp_f32_e32 v60, v34
	v_exp_f32_e32 v61, v35
	v_exp_f32_e32 v36, v36
	v_exp_f32_e32 v37, v37
	v_exp_f32_e32 v38, v38
	v_exp_f32_e32 v39, v39
	s_waitcnt lgkmcnt(2)
	v_mfma_f32_32x32x16_bf16 v[62:77], v[72:75], v[96:99], 0
	ds_read_b128 v[52:55], v166
	ds_read_b128 v[152:155], v166 offset:4096
	v_add_f32_e32 v151, v60, v151
	v_add_f32_e32 v162, v61, v32
	s_waitcnt lgkmcnt(3)
	v_mfma_f32_32x32x16_bf16 v[78:93], v[112:115], v[100:103], v[78:93]
	v_add_f32_e32 v112, v36, v161
	v_add_f32_e32 v113, v37, v163
	v_add_f32_e32 v114, v38, v151
	v_exp_f32_e32 v115, v40
	v_add_f32_e32 v40, v39, v162
	ds_read_b128 v[32:35], v167
	ds_read_b128 v[156:159], v167 offset:4096
	s_waitcnt lgkmcnt(4)
	v_mfma_f32_32x32x16_bf16 v[62:77], v[116:119], v[100:103], v[62:77]
	v_exp_f32_e32 v116, v41
	v_add_f32_e32 v41, v115, v112
	s_min_u32 s9, s3, s2
	s_lshl_b32 s9, s9, 6
	v_add_f32_e32 v112, v116, v113
	s_waitcnt lgkmcnt(3)
	v_mfma_f32_32x32x16_bf16 v[78:93], v[52:55], v[104:107], v[78:93]
	v_cvt_pk_bf16_f32 v54, v36, v37
	v_exp_f32_e32 v37, v42
	v_cvt_pk_bf16_f32 v55, v38, v39
	v_exp_f32_e32 v38, v43
	v_exp_f32_e32 v39, v44
	v_exp_f32_e32 v44, v45
	v_exp_f32_e32 v45, v46
	v_exp_f32_e32 v46, v47
	v_cvt_pk_bf16_f32 v52, v95, v160
	v_cvt_pk_bf16_f32 v53, v60, v61
	v_add_f32_e32 v36, v37, v114
	v_add_f32_e32 v43, v38, v40
	v_add_f32_e32 v40, v39, v41
	v_add_f32_e32 v42, v44, v112
	v_add_f32_e32 v41, v45, v36
	v_add_f32_e32 v43, v46, v43
	v_cvt_pk_bf16_f32 v36, v115, v116
	v_cvt_pk_bf16_f32 v37, v37, v38
	v_cvt_pk_bf16_f32 v38, v39, v44
	v_cvt_pk_bf16_f32 v39, v45, v46
	s_waitcnt lgkmcnt(1)
	v_mfma_f32_32x32x16_bf16 v[78:93], v[32:35], v[108:111], v[78:93]
	s_waitcnt lgkmcnt(0)
	s_barrier
	v_mad_u64_u32 v[32:33], s[18:19], s9, v237, v[132:133]
	global_load_dwordx4 v[112:115], v[32:33], off offset:2048
	global_load_dwordx4 v[116:119], v[136:137], off
	v_add_f32_e64 v32, v40, v42
	v_add_f32_e64 v33, v41, v43
	s_waitcnt vmcnt(4)
	ds_write_b128 v142, v[120:123]
	s_waitcnt vmcnt(3)
	ds_write_b128 v142, v[124:127] offset:8192
	v_mfma_f32_32x32x16_bf16 v[62:77], v[152:155], v[104:107], v[62:77]
	v_add_f32_e32 v32, v32, v33
	v_add_f32_e32 v150, v150, v32
	s_waitcnt lgkmcnt(2)
	v_mfma_f32_32x32x16_bf16 v[62:77], v[156:159], v[108:111], v[62:77]
	ds_read_b128 v[32:35], v144 offset:24576
	ds_read_b128 v[40:43], v144 offset:28672
	ds_read_b128 v[44:47], v141 offset:24576
	ds_read_b128 v[120:123], v141 offset:28672
	v_exp_f32_e32 v60, v78
	s_waitcnt lgkmcnt(3)
	v_mfma_f32_32x32x16_bf16 v[16:31], v[32:35], v[56:59], v[16:31]
	v_exp_f32_e32 v61, v79
	v_exp_f32_e32 v95, v80
	v_exp_f32_e32 v81, v81
	ds_read_b128 v[152:155], v140 offset:24576
	ds_read_b128 v[156:159], v140 offset:28672
	s_waitcnt lgkmcnt(4)
	v_mfma_f32_32x32x16_bf16 v[0:15], v[40:43], v[56:59], v[0:15]
	v_exp_f32_e32 v82, v82
	v_exp_f32_e32 v83, v83
	v_add_f32_e32 v78, v82, v60
	v_add_f32_e32 v79, v83, v61
	s_waitcnt lgkmcnt(2)
	v_mfma_f32_32x32x16_bf16 v[0:15], v[120:123], v[48:51], v[0:15]
	ds_read_b128 v[56:59], v139 offset:24576
	ds_read_b128 v[160:163], v139 offset:28672
	ds_read_b128 v[40:43], v164 offset:16384
	ds_read_b128 v[32:35], v164 offset:20480
	v_cvt_pk_bf16_f32 v82, v82, v83
	v_exp_f32_e32 v151, v62
	v_exp_f32_e32 v64, v64
	v_exp_f32_e32 v65, v65
	v_mfma_f32_32x32x16_bf16 v[16:31], v[44:47], v[48:51], v[16:31]
	v_exp_f32_e32 v44, v84
	v_exp_f32_e32 v45, v85
	v_exp_f32_e32 v84, v86
	v_exp_f32_e32 v85, v87
	v_add_f32_e32 v46, v44, v95
	v_add_f32_e32 v47, v45, v81
	v_add_f32_e32 v48, v84, v78
	s_waitcnt lgkmcnt(4)
	v_mfma_f32_32x32x16_bf16 v[0:15], v[156:159], v[52:55], v[0:15]
	v_add_f32_e32 v49, v85, v79
	v_exp_f32_e32 v78, v88
	v_exp_f32_e32 v79, v89
	v_exp_f32_e32 v87, v92
	v_cvt_pk_bf16_f32 v83, v44, v45
	v_exp_f32_e32 v44, v90
	v_mfma_f32_32x32x16_bf16 v[16:31], v[152:155], v[52:55], v[16:31]
	v_exp_f32_e32 v45, v91
	v_exp_f32_e32 v92, v93
	v_add_f32_e32 v46, v78, v46
	v_add_f32_e32 v47, v79, v47
	ds_read_b128 v[124:127], v165 offset:16384
	ds_read_b128 v[120:123], v165 offset:20480
	s_waitcnt lgkmcnt(4)
	v_mfma_f32_32x32x16_bf16 v[0:15], v[160:163], v[36:39], v[0:15]
	v_exp_f32_e32 v160, v63
	v_cvt_pk_bf16_f32 v80, v60, v61
	v_cvt_pk_bf16_f32 v81, v95, v81
	v_add_f32_e32 v48, v44, v48
	v_add_f32_e32 v49, v45, v49
	v_add_f32_e32 v46, v87, v46
	v_add_f32_e32 v47, v92, v47
	v_mfma_f32_32x32x16_bf16 v[16:31], v[56:59], v[36:39], v[16:31]
	v_add_f32_e32 v161, v151, v48
	v_add_f32_e32 v162, v160, v49
	v_cvt_pk_bf16_f32 v84, v84, v85
	v_cvt_pk_bf16_f32 v85, v78, v79
	v_cvt_pk_bf16_f32 v86, v44, v45
	v_add_f32_e32 v78, v64, v46
	v_add_f32_e32 v79, v65, v47
	s_waitcnt lgkmcnt(3)
	v_mfma_f32_32x32x16_bf16 v[48:63], v[40:43], v[96:99], 0
	ds_read_b128 v[88:91], v166 offset:16384
	ds_read_b128 v[152:155], v166 offset:20480
	v_exp_f32_e32 v66, v66
	v_exp_f32_e32 v67, v67
	v_exp_f32_e32 v68, v68
	v_exp_f32_e32 v69, v69
	v_cvt_pk_bf16_f32 v87, v87, v92
	s_waitcnt lgkmcnt(4)
	v_mfma_f32_32x32x16_bf16 v[32:47], v[32:35], v[96:99], 0
	ds_read_b128 v[156:159], v167 offset:16384
	ds_read_b128 v[92:95], v167 offset:20480
	v_add_f32_e32 v161, v66, v161
	v_add_f32_e32 v162, v67, v162
	v_add_f32_e32 v78, v68, v78
	v_add_f32_e32 v79, v69, v79
	s_waitcnt lgkmcnt(5)
	v_mfma_f32_32x32x16_bf16 v[48:63], v[124:127], v[100:103], v[48:63]
	v_exp_f32_e32 v70, v70
	v_exp_f32_e32 v71, v71
	s_add_i32 s9, s3, 2
	s_add_i32 s3, s3, -2
	v_lshl_add_u64 v[136:137], v[136:137], 0, s[22:23]
	s_waitcnt lgkmcnt(4)
	v_mfma_f32_32x32x16_bf16 v[32:47], v[120:123], v[100:103], v[32:47]
	v_add_f32_e32 v120, v70, v161
	v_add_f32_e32 v121, v71, v162
	s_cmp_lt_u32 s3, s2
	s_mov_b32 s3, s9
	s_waitcnt lgkmcnt(3)
	v_mfma_f32_32x32x16_bf16 v[48:63], v[88:91], v[104:107], v[48:63]
	v_cvt_pk_bf16_f32 v91, v68, v69
	v_exp_f32_e32 v68, v72
	v_exp_f32_e32 v69, v73
	v_exp_f32_e32 v72, v74
	v_exp_f32_e32 v73, v75
	v_exp_f32_e32 v74, v76
	v_exp_f32_e32 v75, v77
	s_waitcnt lgkmcnt(2)
	v_mfma_f32_32x32x16_bf16 v[32:47], v[152:155], v[104:107], v[32:47]
	v_cvt_pk_bf16_f32 v88, v151, v160
	v_cvt_pk_bf16_f32 v89, v64, v65
	v_cvt_pk_bf16_f32 v90, v66, v67
	v_add_f32_e32 v65, v68, v78
	v_add_f32_e32 v67, v69, v79
	s_waitcnt lgkmcnt(1)
	v_mfma_f32_32x32x16_bf16 v[48:63], v[156:159], v[108:111], v[48:63]
	v_add_f32_e32 v64, v72, v120
	v_add_f32_e32 v66, v73, v121
	v_add_f32_e32 v65, v74, v65
	v_add_f32_e32 v67, v75, v67
	s_waitcnt lgkmcnt(0)
	v_mfma_f32_32x32x16_bf16 v[32:47], v[92:95], v[108:111], v[32:47]
	v_cvt_pk_bf16_f32 v92, v70, v71
	v_cvt_pk_bf16_f32 v93, v68, v69
	v_cvt_pk_bf16_f32 v94, v72, v73
	v_cvt_pk_bf16_f32 v95, v74, v75
	v_add_f32_e64 v64, v64, v66
	v_add_f32_e64 v65, v65, v67
	s_waitcnt lgkmcnt(0)
	s_barrier
	v_add_f32_e32 v64, v64, v65
	v_add_f32_e32 v150, v150, v64
.Lpeel_5:
	s_add_i32 s9, s3, -1
	s_min_u32 s9, s9, s2
	s_lshl_b32 s9, s9, 6
	s_waitcnt vmcnt(1)
	ds_write_b128 v142, v[112:115] offset:16384
	s_waitcnt vmcnt(0)
	ds_write_b128 v142, v[116:119] offset:24576
	v_mad_u64_u32 v[64:65], s[18:19], s9, v237, v[132:133]
	global_load_dwordx4 v[120:123], v[64:65], off offset:2048
	global_load_dwordx4 v[124:127], v[136:137], off offset:-128
	ds_read_b128 v[64:67], v144 offset:8192
	ds_read_b128 v[68:71], v144 offset:12288
	ds_read_b128 v[72:75], v141 offset:8192
	ds_read_b128 v[76:79], v141 offset:12288
	v_exp_f32_e32 v151, v48
	v_exp_f32_e32 v152, v49
	s_waitcnt lgkmcnt(3)
	v_mfma_f32_32x32x16_bf16 v[16:31], v[64:67], v[80:83], v[16:31]
	v_exp_f32_e32 v153, v50
	v_exp_f32_e32 v154, v51
	ds_read_b128 v[48:51], v140 offset:8192
	ds_read_b128 v[64:67], v140 offset:12288
	v_exp_f32_e32 v155, v52
	s_waitcnt lgkmcnt(4)
	v_mfma_f32_32x32x16_bf16 v[0:15], v[68:71], v[80:83], v[0:15]
	v_exp_f32_e32 v156, v53
	v_exp_f32_e32 v159, v54
	v_exp_f32_e32 v160, v55
	v_exp_f32_e32 v162, v57
	s_waitcnt lgkmcnt(3)
	v_mfma_f32_32x32x16_bf16 v[16:31], v[72:75], v[84:87], v[16:31]
	ds_read_b128 v[68:71], v139 offset:8192
	ds_read_b128 v[80:83], v139 offset:12288
	v_add_f32_e32 v157, v155, v151
	v_add_f32_e32 v158, v156, v152
	ds_read_b128 v[52:55], v164
	ds_read_b128 v[72:75], v164 offset:4096
	v_add_f32_e32 v161, v159, v153
	s_waitcnt lgkmcnt(6)
	v_mfma_f32_32x32x16_bf16 v[0:15], v[76:79], v[84:87], v[0:15]
	v_exp_f32_e32 v77, v56
	v_add_f32_e32 v76, v160, v154
	v_exp_f32_e32 v62, v62
	ds_read_b128 v[112:115], v165
	ds_read_b128 v[116:119], v165 offset:4096
	v_cvt_pk_bf16_f32 v56, v151, v152
	s_waitcnt lgkmcnt(7)
	v_mfma_f32_32x32x16_bf16 v[16:31], v[48:51], v[88:91], v[16:31]
	v_exp_f32_e32 v49, v58
	v_exp_f32_e32 v50, v59
	v_add_f32_e32 v48, v77, v157
	v_add_f32_e32 v51, v162, v158
	v_add_f32_e32 v78, v49, v161
	v_add_f32_e32 v76, v50, v76
	s_waitcnt lgkmcnt(6)
	v_mfma_f32_32x32x16_bf16 v[0:15], v[64:67], v[88:91], v[0:15]
	v_exp_f32_e32 v60, v60
	v_add_f32_e32 v151, v62, v78
	v_exp_f32_e32 v61, v61
	v_exp_f32_e32 v63, v63
	v_cvt_pk_bf16_f32 v59, v159, v160
	v_exp_f32_e32 v160, v33
	s_waitcnt lgkmcnt(5)
	v_mfma_f32_32x32x16_bf16 v[16:31], v[68:71], v[92:95], v[16:31]
	v_cvt_pk_bf16_f32 v57, v153, v154
	v_cvt_pk_bf16_f32 v58, v155, v156
	v_add_f32_e32 v48, v60, v48
	v_add_f32_e32 v51, v61, v51
	v_cvt_pk_bf16_f32 v49, v49, v50
	s_waitcnt lgkmcnt(4)
	v_mfma_f32_32x32x16_bf16 v[0:15], v[80:83], v[92:95], v[0:15]
	v_readfirstlane_b32 s18, v171
	s_add_u32 m0, s18, 0x11be0
	s_nop 0
	global_load_lds_dwordx4 v168, s[14:15] offset:1056
	v_exp_f32_e32 v95, v32
	v_add_f32_e32 v32, v63, v76
	v_add_f32_e32 v163, v160, v51
	v_add_f32_e32 v161, v95, v48
	v_cvt_pk_bf16_f32 v48, v77, v162
	v_cvt_pk_bf16_f32 v51, v62, v63
	s_waitcnt lgkmcnt(3)
	v_mfma_f32_32x32x16_bf16 v[78:93], v[52:55], v[96:99], 0
	v_cvt_pk_bf16_f32 v50, v60, v61
	v_exp_f32_e32 v60, v34
	v_exp_f32_e32 v61, v35
	v_exp_f32_e32 v36, v36
	v_exp_f32_e32 v37, v37
	v_exp_f32_e32 v38, v38
	v_exp_f32_e32 v39, v39
	s_waitcnt lgkmcnt(2)
	v_mfma_f32_32x32x16_bf16 v[62:77], v[72:75], v[96:99], 0
	ds_read_b128 v[52:55], v166
	ds_read_b128 v[152:155], v166 offset:4096
	v_add_f32_e32 v151, v60, v151
	v_add_f32_e32 v162, v61, v32
	s_waitcnt lgkmcnt(3)
	v_mfma_f32_32x32x16_bf16 v[78:93], v[112:115], v[100:103], v[78:93]
	v_add_f32_e32 v112, v36, v161
	v_add_f32_e32 v113, v37, v163
	v_add_f32_e32 v114, v38, v151
	v_exp_f32_e32 v115, v40
	v_add_f32_e32 v40, v39, v162
	ds_read_b128 v[32:35], v167
	ds_read_b128 v[156:159], v167 offset:4096
	s_waitcnt lgkmcnt(4)
	v_mfma_f32_32x32x16_bf16 v[62:77], v[116:119], v[100:103], v[62:77]
	v_exp_f32_e32 v116, v41
	v_add_f32_e32 v41, v115, v112
	s_min_u32 s9, s3, s2
	s_lshl_b32 s9, s9, 6
	v_add_f32_e32 v112, v116, v113
	s_waitcnt lgkmcnt(3)
	v_mfma_f32_32x32x16_bf16 v[78:93], v[52:55], v[104:107], v[78:93]
	v_cvt_pk_bf16_f32 v54, v36, v37
	v_exp_f32_e32 v37, v42
	v_cvt_pk_bf16_f32 v55, v38, v39
	v_exp_f32_e32 v38, v43
	v_exp_f32_e32 v39, v44
	v_exp_f32_e32 v44, v45
	v_exp_f32_e32 v45, v46
	v_exp_f32_e32 v46, v47
	v_cvt_pk_bf16_f32 v52, v95, v160
	v_cvt_pk_bf16_f32 v53, v60, v61
	v_add_f32_e32 v36, v37, v114
	v_add_f32_e32 v43, v38, v40
	v_add_f32_e32 v40, v39, v41
	v_add_f32_e32 v42, v44, v112
	v_add_f32_e32 v41, v45, v36
	v_add_f32_e32 v43, v46, v43
	v_cvt_pk_bf16_f32 v36, v115, v116
	v_cvt_pk_bf16_f32 v37, v37, v38
	v_cvt_pk_bf16_f32 v38, v39, v44
	v_cvt_pk_bf16_f32 v39, v45, v46
	s_waitcnt lgkmcnt(1)
	v_mfma_f32_32x32x16_bf16 v[78:93], v[32:35], v[108:111], v[78:93]
	s_waitcnt lgkmcnt(0)
	s_barrier
	v_mad_u64_u32 v[32:33], s[18:19], s9, v237, v[132:133]
	global_load_dwordx4 v[112:115], v[32:33], off offset:2048
	global_load_dwordx4 v[116:119], v[136:137], off
	v_add_f32_e64 v32, v40, v42
	v_add_f32_e64 v33, v41, v43
	s_waitcnt vmcnt(4)
	ds_write_b128 v142, v[120:123]
	s_waitcnt vmcnt(3)
	ds_write_b128 v142, v[124:127] offset:8192
	v_mfma_f32_32x32x16_bf16 v[62:77], v[152:155], v[104:107], v[62:77]
	v_add_f32_e32 v32, v32, v33
	v_add_f32_e32 v150, v150, v32
	s_waitcnt lgkmcnt(2)
	v_mfma_f32_32x32x16_bf16 v[62:77], v[156:159], v[108:111], v[62:77]
	ds_read_b128 v[32:35], v144 offset:24576
	ds_read_b128 v[40:43], v144 offset:28672
	ds_read_b128 v[44:47], v141 offset:24576
	ds_read_b128 v[120:123], v141 offset:28672
	v_exp_f32_e32 v60, v78
	s_waitcnt lgkmcnt(3)
	v_mfma_f32_32x32x16_bf16 v[16:31], v[32:35], v[56:59], v[16:31]
	v_exp_f32_e32 v61, v79
	v_exp_f32_e32 v95, v80
	v_exp_f32_e32 v81, v81
	ds_read_b128 v[152:155], v140 offset:24576
	ds_read_b128 v[156:159], v140 offset:28672
	s_waitcnt lgkmcnt(4)
	v_mfma_f32_32x32x16_bf16 v[0:15], v[40:43], v[56:59], v[0:15]
	v_exp_f32_e32 v82, v82
	v_exp_f32_e32 v83, v83
	v_add_f32_e32 v78, v82, v60
	v_add_f32_e32 v79, v83, v61
	s_waitcnt lgkmcnt(2)
	v_mfma_f32_32x32x16_bf16 v[0:15], v[120:123], v[48:51], v[0:15]
	ds_read_b128 v[56:59], v139 offset:24576
	ds_read_b128 v[160:163], v139 offset:28672
	ds_read_b128 v[40:43], v164 offset:16384
	ds_read_b128 v[32:35], v164 offset:20480
	v_cvt_pk_bf16_f32 v82, v82, v83
	v_exp_f32_e32 v151, v62
	v_exp_f32_e32 v64, v64
	v_exp_f32_e32 v65, v65
	v_mfma_f32_32x32x16_bf16 v[16:31], v[44:47], v[48:51], v[16:31]
	v_exp_f32_e32 v44, v84
	v_exp_f32_e32 v45, v85
	v_exp_f32_e32 v84, v86
	v_exp_f32_e32 v85, v87
	v_add_f32_e32 v46, v44, v95
	v_add_f32_e32 v47, v45, v81
	v_add_f32_e32 v48, v84, v78
	s_waitcnt lgkmcnt(4)
	v_mfma_f32_32x32x16_bf16 v[0:15], v[156:159], v[52:55], v[0:15]
	v_add_f32_e32 v49, v85, v79
	v_exp_f32_e32 v78, v88
	v_exp_f32_e32 v79, v89
	v_exp_f32_e32 v87, v92
	v_cvt_pk_bf16_f32 v83, v44, v45
	v_exp_f32_e32 v44, v90
	v_mfma_f32_32x32x16_bf16 v[16:31], v[152:155], v[52:55], v[16:31]
	v_exp_f32_e32 v45, v91
	v_exp_f32_e32 v92, v93
	v_add_f32_e32 v46, v78, v46
	v_add_f32_e32 v47, v79, v47
	ds_read_b128 v[124:127], v165 offset:16384
	ds_read_b128 v[120:123], v165 offset:20480
	s_waitcnt lgkmcnt(4)
	v_mfma_f32_32x32x16_bf16 v[0:15], v[160:163], v[36:39], v[0:15]
	v_exp_f32_e32 v160, v63
	v_cvt_pk_bf16_f32 v80, v60, v61
	v_cvt_pk_bf16_f32 v81, v95, v81
	v_add_f32_e32 v48, v44, v48
	v_add_f32_e32 v49, v45, v49
	v_add_f32_e32 v46, v87, v46
	v_add_f32_e32 v47, v92, v47
	v_mfma_f32_32x32x16_bf16 v[16:31], v[56:59], v[36:39], v[16:31]
	v_add_f32_e32 v161, v151, v48
	v_add_f32_e32 v162, v160, v49
	v_cvt_pk_bf16_f32 v84, v84, v85
	v_cvt_pk_bf16_f32 v85, v78, v79
	v_cvt_pk_bf16_f32 v86, v44, v45
	v_add_f32_e32 v78, v64, v46
	v_add_f32_e32 v79, v65, v47
	s_waitcnt lgkmcnt(3)
	v_mfma_f32_32x32x16_bf16 v[48:63], v[40:43], v[96:99], 0
	ds_read_b128 v[88:91], v166 offset:16384
	ds_read_b128 v[152:155], v166 offset:20480
	v_exp_f32_e32 v66, v66
	v_exp_f32_e32 v67, v67
	v_exp_f32_e32 v68, v68
	v_exp_f32_e32 v69, v69
	v_cvt_pk_bf16_f32 v87, v87, v92
	s_waitcnt lgkmcnt(4)
	v_mfma_f32_32x32x16_bf16 v[32:47], v[32:35], v[96:99], 0
	ds_read_b128 v[156:159], v167 offset:16384
	ds_read_b128 v[92:95], v167 offset:20480
	v_add_f32_e32 v161, v66, v161
	v_add_f32_e32 v162, v67, v162
	v_add_f32_e32 v78, v68, v78
	v_add_f32_e32 v79, v69, v79
	s_waitcnt lgkmcnt(5)
	v_mfma_f32_32x32x16_bf16 v[48:63], v[124:127], v[100:103], v[48:63]
	v_exp_f32_e32 v70, v70
	v_exp_f32_e32 v71, v71
	s_add_i32 s9, s3, 2
	s_add_i32 s3, s3, -2
	v_lshl_add_u64 v[136:137], v[136:137], 0, s[22:23]
	s_waitcnt lgkmcnt(4)
	v_mfma_f32_32x32x16_bf16 v[32:47], v[120:123], v[100:103], v[32:47]
	v_add_f32_e32 v120, v70, v161
	v_add_f32_e32 v121, v71, v162
	s_cmp_lt_u32 s3, s2
	s_mov_b32 s3, s9
	s_waitcnt lgkmcnt(3)
	v_mfma_f32_32x32x16_bf16 v[48:63], v[88:91], v[104:107], v[48:63]
	v_cvt_pk_bf16_f32 v91, v68, v69
	v_exp_f32_e32 v68, v72
	v_exp_f32_e32 v69, v73
	v_exp_f32_e32 v72, v74
	v_exp_f32_e32 v73, v75
	v_exp_f32_e32 v74, v76
	v_exp_f32_e32 v75, v77
	s_waitcnt lgkmcnt(2)
	v_mfma_f32_32x32x16_bf16 v[32:47], v[152:155], v[104:107], v[32:47]
	v_cvt_pk_bf16_f32 v88, v151, v160
	v_cvt_pk_bf16_f32 v89, v64, v65
	v_cvt_pk_bf16_f32 v90, v66, v67
	v_add_f32_e32 v65, v68, v78
	v_add_f32_e32 v67, v69, v79
	s_waitcnt lgkmcnt(1)
	v_mfma_f32_32x32x16_bf16 v[48:63], v[156:159], v[108:111], v[48:63]
	v_add_f32_e32 v64, v72, v120
	v_add_f32_e32 v66, v73, v121
	v_add_f32_e32 v65, v74, v65
	v_add_f32_e32 v67, v75, v67
	s_waitcnt lgkmcnt(0)
	v_mfma_f32_32x32x16_bf16 v[32:47], v[92:95], v[108:111], v[32:47]
	v_cvt_pk_bf16_f32 v92, v70, v71
	v_cvt_pk_bf16_f32 v93, v68, v69
	v_cvt_pk_bf16_f32 v94, v72, v73
	v_cvt_pk_bf16_f32 v95, v74, v75
	v_add_f32_e64 v64, v64, v66
	v_add_f32_e64 v65, v65, v67
	s_waitcnt lgkmcnt(0)
	s_barrier
	v_add_f32_e32 v64, v64, v65
	v_add_f32_e32 v150, v150, v64
.Lpeel_6:
	s_add_i32 s9, s3, -1
	s_min_u32 s9, s9, s2
	s_lshl_b32 s9, s9, 6
	s_waitcnt vmcnt(1)
	ds_write_b128 v142, v[112:115] offset:16384
	s_waitcnt vmcnt(0)
	ds_write_b128 v142, v[116:119] offset:24576
	v_mad_u64_u32 v[64:65], s[18:19], s9, v237, v[132:133]
	global_load_dwordx4 v[120:123], v[64:65], off offset:2048
	global_load_dwordx4 v[124:127], v[136:137], off offset:-128
	ds_read_b128 v[64:67], v144 offset:8192
	ds_read_b128 v[68:71], v144 offset:12288
	ds_read_b128 v[72:75], v141 offset:8192
	ds_read_b128 v[76:79], v141 offset:12288
	v_exp_f32_e32 v151, v48
	v_exp_f32_e32 v152, v49
	s_waitcnt lgkmcnt(3)
	v_mfma_f32_32x32x16_bf16 v[16:31], v[64:67], v[80:83], v[16:31]
	v_exp_f32_e32 v153, v50
	v_exp_f32_e32 v154, v51
	ds_read_b128 v[48:51], v140 offset:8192
	ds_read_b128 v[64:67], v140 offset:12288
	v_exp_f32_e32 v155, v52
	s_waitcnt lgkmcnt(4)
	v_mfma_f32_32x32x16_bf16 v[0:15], v[68:71], v[80:83], v[0:15]
	v_exp_f32_e32 v156, v53
	v_exp_f32_e32 v159, v54
	v_exp_f32_e32 v160, v55
	v_exp_f32_e32 v162, v57
	s_waitcnt lgkmcnt(3)
	v_mfma_f32_32x32x16_bf16 v[16:31], v[72:75], v[84:87], v[16:31]
	ds_read_b128 v[68:71], v139 offset:8192
	ds_read_b128 v[80:83], v139 offset:12288
	v_add_f32_e32 v157, v155, v151
	v_add_f32_e32 v158, v156, v152
	ds_read_b128 v[52:55], v164
	ds_read_b128 v[72:75], v164 offset:4096
	v_add_f32_e32 v161, v159, v153
	s_waitcnt lgkmcnt(6)
	v_mfma_f32_32x32x16_bf16 v[0:15], v[76:79], v[84:87], v[0:15]
	v_exp_f32_e32 v77, v56
	v_add_f32_e32 v76, v160, v154
	v_exp_f32_e32 v62, v62
	ds_read_b128 v[112:115], v165
	ds_read_b128 v[116:119], v165 offset:4096
	v_cvt_pk_bf16_f32 v56, v151, v152
	s_waitcnt lgkmcnt(7)
	v_mfma_f32_32x32x16_bf16 v[16:31], v[48:51], v[88:91], v[16:31]
	v_exp_f32_e32 v49, v58
	v_exp_f32_e32 v50, v59
	v_add_f32_e32 v48, v77, v157
	v_add_f32_e32 v51, v162, v158
	v_add_f32_e32 v78, v49, v161
	v_add_f32_e32 v76, v50, v76
	s_waitcnt lgkmcnt(6)
	v_mfma_f32_32x32x16_bf16 v[0:15], v[64:67], v[88:91], v[0:15]
	v_exp_f32_e32 v60, v60
	v_add_f32_e32 v151, v62, v78
	v_exp_f32_e32 v61, v61
	v_exp_f32_e32 v63, v63
	v_cvt_pk_bf16_f32 v59, v159, v160
	v_exp_f32_e32 v160, v33
	s_waitcnt lgkmcnt(5)
	v_mfma_f32_32x32x16_bf16 v[16:31], v[68:71], v[92:95], v[16:31]
	v_cvt_pk_bf16_f32 v57, v153, v154
	v_cvt_pk_bf16_f32 v58, v155, v156
	v_add_f32_e32 v48, v60, v48
	v_add_f32_e32 v51, v61, v51
	v_cvt_pk_bf16_f32 v49, v49, v50
	s_waitcnt lgkmcnt(4)
	v_mfma_f32_32x32x16_bf16 v[0:15], v[80:83], v[92:95], v[0:15]
	v_readfirstlane_b32 s18, v171
	s_add_u32 m0, s18, 0x13bc0
	s_nop 0
	global_load_lds_dwordx4 v168, s[14:15] offset:1088
	v_exp_f32_e32 v95, v32
	v_add_f32_e32 v32, v63, v76
	v_add_f32_e32 v163, v160, v51
	v_add_f32_e32 v161, v95, v48
	v_cvt_pk_bf16_f32 v48, v77, v162
	v_cvt_pk_bf16_f32 v51, v62, v63
	s_waitcnt lgkmcnt(3)
	v_mfma_f32_32x32x16_bf16 v[78:93], v[52:55], v[96:99], 0
	v_cvt_pk_bf16_f32 v50, v60, v61
	v_exp_f32_e32 v60, v34
	v_exp_f32_e32 v61, v35
	v_exp_f32_e32 v36, v36
	v_exp_f32_e32 v37, v37
	v_exp_f32_e32 v38, v38
	v_exp_f32_e32 v39, v39
	s_waitcnt lgkmcnt(2)
	v_mfma_f32_32x32x16_bf16 v[62:77], v[72:75], v[96:99], 0
	ds_read_b128 v[52:55], v166
	ds_read_b128 v[152:155], v166 offset:4096
	v_add_f32_e32 v151, v60, v151
	v_add_f32_e32 v162, v61, v32
	s_waitcnt lgkmcnt(3)
	v_mfma_f32_32x32x16_bf16 v[78:93], v[112:115], v[100:103], v[78:93]
	v_add_f32_e32 v112, v36, v161
	v_add_f32_e32 v113, v37, v163
	v_add_f32_e32 v114, v38, v151
	v_exp_f32_e32 v115, v40
	v_add_f32_e32 v40, v39, v162
	ds_read_b128 v[32:35], v167
	ds_read_b128 v[156:159], v167 offset:4096
	s_waitcnt lgkmcnt(4)
	v_mfma_f32_32x32x16_bf16 v[62:77], v[116:119], v[100:103], v[62:77]
	v_exp_f32_e32 v116, v41
	v_add_f32_e32 v41, v115, v112
	s_min_u32 s9, s3, s2
	s_lshl_b32 s9, s9, 6
	v_add_f32_e32 v112, v116, v113
	s_waitcnt lgkmcnt(3)
	v_mfma_f32_32x32x16_bf16 v[78:93], v[52:55], v[104:107], v[78:93]
	v_cvt_pk_bf16_f32 v54, v36, v37
	v_exp_f32_e32 v37, v42
	v_cvt_pk_bf16_f32 v55, v38, v39
	v_exp_f32_e32 v38, v43
	v_exp_f32_e32 v39, v44
	v_exp_f32_e32 v44, v45
	v_exp_f32_e32 v45, v46
	v_exp_f32_e32 v46, v47
	v_cvt_pk_bf16_f32 v52, v95, v160
	v_cvt_pk_bf16_f32 v53, v60, v61
	v_add_f32_e32 v36, v37, v114
	v_add_f32_e32 v43, v38, v40
	v_add_f32_e32 v40, v39, v41
	v_add_f32_e32 v42, v44, v112
	v_add_f32_e32 v41, v45, v36
	v_add_f32_e32 v43, v46, v43
	v_cvt_pk_bf16_f32 v36, v115, v116
	v_cvt_pk_bf16_f32 v37, v37, v38
	v_cvt_pk_bf16_f32 v38, v39, v44
	v_cvt_pk_bf16_f32 v39, v45, v46
	s_waitcnt lgkmcnt(1)
	v_mfma_f32_32x32x16_bf16 v[78:93], v[32:35], v[108:111], v[78:93]
	s_waitcnt lgkmcnt(0)
	s_barrier
	v_mad_u64_u32 v[32:33], s[18:19], s9, v237, v[132:133]
	global_load_dwordx4 v[112:115], v[32:33], off offset:2048
	global_load_dwordx4 v[116:119], v[136:137], off
	v_add_f32_e64 v32, v40, v42
	v_add_f32_e64 v33, v41, v43
	s_waitcnt vmcnt(4)
	ds_write_b128 v142, v[120:123]
	s_waitcnt vmcnt(3)
	ds_write_b128 v142, v[124:127] offset:8192
	v_mfma_f32_32x32x16_bf16 v[62:77], v[152:155], v[104:107], v[62:77]
	v_add_f32_e32 v32, v32, v33
	v_add_f32_e32 v150, v150, v32
	s_waitcnt lgkmcnt(2)
	v_mfma_f32_32x32x16_bf16 v[62:77], v[156:159], v[108:111], v[62:77]
	ds_read_b128 v[32:35], v144 offset:24576
	ds_read_b128 v[40:43], v144 offset:28672
	ds_read_b128 v[44:47], v141 offset:24576
	ds_read_b128 v[120:123], v141 offset:28672
	v_exp_f32_e32 v60, v78
	s_waitcnt lgkmcnt(3)
	v_mfma_f32_32x32x16_bf16 v[16:31], v[32:35], v[56:59], v[16:31]
	v_exp_f32_e32 v61, v79
	v_exp_f32_e32 v95, v80
	v_exp_f32_e32 v81, v81
	ds_read_b128 v[152:155], v140 offset:24576
	ds_read_b128 v[156:159], v140 offset:28672
	s_waitcnt lgkmcnt(4)
	v_mfma_f32_32x32x16_bf16 v[0:15], v[40:43], v[56:59], v[0:15]
	v_exp_f32_e32 v82, v82
	v_exp_f32_e32 v83, v83
	v_add_f32_e32 v78, v82, v60
	v_add_f32_e32 v79, v83, v61
	s_waitcnt lgkmcnt(2)
	v_mfma_f32_32x32x16_bf16 v[0:15], v[120:123], v[48:51], v[0:15]
	ds_read_b128 v[56:59], v139 offset:24576
	ds_read_b128 v[160:163], v139 offset:28672
	ds_read_b128 v[40:43], v164 offset:16384
	ds_read_b128 v[32:35], v164 offset:20480
	v_cvt_pk_bf16_f32 v82, v82, v83
	v_exp_f32_e32 v151, v62
	v_exp_f32_e32 v64, v64
	v_exp_f32_e32 v65, v65
	v_mfma_f32_32x32x16_bf16 v[16:31], v[44:47], v[48:51], v[16:31]
	v_exp_f32_e32 v44, v84
	v_exp_f32_e32 v45, v85
	v_exp_f32_e32 v84, v86
	v_exp_f32_e32 v85, v87
	v_add_f32_e32 v46, v44, v95
	v_add_f32_e32 v47, v45, v81
	v_add_f32_e32 v48, v84, v78
	s_waitcnt lgkmcnt(4)
	v_mfma_f32_32x32x16_bf16 v[0:15], v[156:159], v[52:55], v[0:15]
	v_add_f32_e32 v49, v85, v79
	v_exp_f32_e32 v78, v88
	v_exp_f32_e32 v79, v89
	v_exp_f32_e32 v87, v92
	v_cvt_pk_bf16_f32 v83, v44, v45
	v_exp_f32_e32 v44, v90
	v_mfma_f32_32x32x16_bf16 v[16:31], v[152:155], v[52:55], v[16:31]
	v_exp_f32_e32 v45, v91
	v_exp_f32_e32 v92, v93
	v_add_f32_e32 v46, v78, v46
	v_add_f32_e32 v47, v79, v47
	ds_read_b128 v[124:127], v165 offset:16384
	ds_read_b128 v[120:123], v165 offset:20480
	s_waitcnt lgkmcnt(4)
	v_mfma_f32_32x32x16_bf16 v[0:15], v[160:163], v[36:39], v[0:15]
	v_exp_f32_e32 v160, v63
	v_cvt_pk_bf16_f32 v80, v60, v61
	v_cvt_pk_bf16_f32 v81, v95, v81
	v_add_f32_e32 v48, v44, v48
	v_add_f32_e32 v49, v45, v49
	v_add_f32_e32 v46, v87, v46
	v_add_f32_e32 v47, v92, v47
	v_mfma_f32_32x32x16_bf16 v[16:31], v[56:59], v[36:39], v[16:31]
	v_add_f32_e32 v161, v151, v48
	v_add_f32_e32 v162, v160, v49
	v_cvt_pk_bf16_f32 v84, v84, v85
	v_cvt_pk_bf16_f32 v85, v78, v79
	v_cvt_pk_bf16_f32 v86, v44, v45
	v_add_f32_e32 v78, v64, v46
	v_add_f32_e32 v79, v65, v47
	s_waitcnt lgkmcnt(3)
	v_mfma_f32_32x32x16_bf16 v[48:63], v[40:43], v[96:99], 0
	ds_read_b128 v[88:91], v166 offset:16384
	ds_read_b128 v[152:155], v166 offset:20480
	v_exp_f32_e32 v66, v66
	v_exp_f32_e32 v67, v67
	v_exp_f32_e32 v68, v68
	v_exp_f32_e32 v69, v69
	v_cvt_pk_bf16_f32 v87, v87, v92
	s_waitcnt lgkmcnt(4)
	v_mfma_f32_32x32x16_bf16 v[32:47], v[32:35], v[96:99], 0
	ds_read_b128 v[156:159], v167 offset:16384
	ds_read_b128 v[92:95], v167 offset:20480
	v_add_f32_e32 v161, v66, v161
	v_add_f32_e32 v162, v67, v162
	v_add_f32_e32 v78, v68, v78
	v_add_f32_e32 v79, v69, v79
	s_waitcnt lgkmcnt(5)
	v_mfma_f32_32x32x16_bf16 v[48:63], v[124:127], v[100:103], v[48:63]
	v_exp_f32_e32 v70, v70
	v_exp_f32_e32 v71, v71
	s_add_i32 s9, s3, 2
	s_add_i32 s3, s3, -2
	v_lshl_add_u64 v[136:137], v[136:137], 0, s[22:23]
	s_waitcnt lgkmcnt(4)
	v_mfma_f32_32x32x16_bf16 v[32:47], v[120:123], v[100:103], v[32:47]
	v_add_f32_e32 v120, v70, v161
	v_add_f32_e32 v121, v71, v162
	s_cmp_lt_u32 s3, s2
	s_mov_b32 s3, s9
	s_waitcnt lgkmcnt(3)
	v_mfma_f32_32x32x16_bf16 v[48:63], v[88:91], v[104:107], v[48:63]
	v_cvt_pk_bf16_f32 v91, v68, v69
	v_exp_f32_e32 v68, v72
	v_exp_f32_e32 v69, v73
	v_exp_f32_e32 v72, v74
	v_exp_f32_e32 v73, v75
	v_exp_f32_e32 v74, v76
	v_exp_f32_e32 v75, v77
	s_waitcnt lgkmcnt(2)
	v_mfma_f32_32x32x16_bf16 v[32:47], v[152:155], v[104:107], v[32:47]
	v_cvt_pk_bf16_f32 v88, v151, v160
	v_cvt_pk_bf16_f32 v89, v64, v65
	v_cvt_pk_bf16_f32 v90, v66, v67
	v_add_f32_e32 v65, v68, v78
	v_add_f32_e32 v67, v69, v79
	s_waitcnt lgkmcnt(1)
	v_mfma_f32_32x32x16_bf16 v[48:63], v[156:159], v[108:111], v[48:63]
	v_add_f32_e32 v64, v72, v120
	v_add_f32_e32 v66, v73, v121
	v_add_f32_e32 v65, v74, v65
	v_add_f32_e32 v67, v75, v67
	s_waitcnt lgkmcnt(0)
	v_mfma_f32_32x32x16_bf16 v[32:47], v[92:95], v[108:111], v[32:47]
	v_cvt_pk_bf16_f32 v92, v70, v71
	v_cvt_pk_bf16_f32 v93, v68, v69
	v_cvt_pk_bf16_f32 v94, v72, v73
	v_cvt_pk_bf16_f32 v95, v74, v75
	v_add_f32_e64 v64, v64, v66
	v_add_f32_e64 v65, v65, v67
	s_waitcnt lgkmcnt(0)
	s_barrier
	v_add_f32_e32 v64, v64, v65
	v_add_f32_e32 v150, v150, v64
.Lpeel_7:
	s_add_i32 s9, s3, -1
	s_min_u32 s9, s9, s2
	s_lshl_b32 s9, s9, 6
	s_waitcnt vmcnt(1)
	ds_write_b128 v142, v[112:115] offset:16384
	s_waitcnt vmcnt(0)
	ds_write_b128 v142, v[116:119] offset:24576
	v_mad_u64_u32 v[64:65], s[18:19], s9, v237, v[132:133]
	global_load_dwordx4 v[120:123], v[64:65], off offset:2048
	global_load_dwordx4 v[124:127], v[136:137], off offset:-128
	ds_read_b128 v[64:67], v144 offset:8192
	ds_read_b128 v[68:71], v144 offset:12288
	ds_read_b128 v[72:75], v141 offset:8192
	ds_read_b128 v[76:79], v141 offset:12288
	v_exp_f32_e32 v151, v48
	v_exp_f32_e32 v152, v49
	s_waitcnt lgkmcnt(3)
	v_mfma_f32_32x32x16_bf16 v[16:31], v[64:67], v[80:83], v[16:31]
	v_exp_f32_e32 v153, v50
	v_exp_f32_e32 v154, v51
	ds_read_b128 v[48:51], v140 offset:8192
	ds_read_b128 v[64:67], v140 offset:12288
	v_exp_f32_e32 v155, v52
	s_waitcnt lgkmcnt(4)
	v_mfma_f32_32x32x16_bf16 v[0:15], v[68:71], v[80:83], v[0:15]
	v_exp_f32_e32 v156, v53
	v_exp_f32_e32 v159, v54
	v_exp_f32_e32 v160, v55
	v_exp_f32_e32 v162, v57
	s_waitcnt lgkmcnt(3)
	v_mfma_f32_32x32x16_bf16 v[16:31], v[72:75], v[84:87], v[16:31]
	ds_read_b128 v[68:71], v139 offset:8192
	ds_read_b128 v[80:83], v139 offset:12288
	v_add_f32_e32 v157, v155, v151
	v_add_f32_e32 v158, v156, v152
	ds_read_b128 v[52:55], v164
	ds_read_b128 v[72:75], v164 offset:4096
	v_add_f32_e32 v161, v159, v153
	s_waitcnt lgkmcnt(6)
	v_mfma_f32_32x32x16_bf16 v[0:15], v[76:79], v[84:87], v[0:15]
	v_exp_f32_e32 v77, v56
	v_add_f32_e32 v76, v160, v154
	v_exp_f32_e32 v62, v62
	ds_read_b128 v[112:115], v165
	ds_read_b128 v[116:119], v165 offset:4096
	v_cvt_pk_bf16_f32 v56, v151, v152
	s_waitcnt lgkmcnt(7)
	v_mfma_f32_32x32x16_bf16 v[16:31], v[48:51], v[88:91], v[16:31]
	v_exp_f32_e32 v49, v58
	v_exp_f32_e32 v50, v59
	v_add_f32_e32 v48, v77, v157
	v_add_f32_e32 v51, v162, v158
	v_add_f32_e32 v78, v49, v161
	v_add_f32_e32 v76, v50, v76
	s_waitcnt lgkmcnt(6)
	v_mfma_f32_32x32x16_bf16 v[0:15], v[64:67], v[88:91], v[0:15]
	v_exp_f32_e32 v60, v60
	v_add_f32_e32 v151, v62, v78
	v_exp_f32_e32 v61, v61
	v_exp_f32_e32 v63, v63
	v_cvt_pk_bf16_f32 v59, v159, v160
	v_exp_f32_e32 v160, v33
	s_waitcnt lgkmcnt(5)
	v_mfma_f32_32x32x16_bf16 v[16:31], v[68:71], v[92:95], v[16:31]
	v_cvt_pk_bf16_f32 v57, v153, v154
	v_cvt_pk_bf16_f32 v58, v155, v156
	v_add_f32_e32 v48, v60, v48
	v_add_f32_e32 v51, v61, v51
	v_cvt_pk_bf16_f32 v49, v49, v50
	s_waitcnt lgkmcnt(4)
	v_mfma_f32_32x32x16_bf16 v[0:15], v[80:83], v[92:95], v[0:15]
	v_readfirstlane_b32 s18, v171
	s_add_u32 m0, s18, 0x15ba0
	s_nop 0
	global_load_lds_dwordx4 v168, s[14:15] offset:1120
	v_exp_f32_e32 v95, v32
	v_add_f32_e32 v32, v63, v76
	v_add_f32_e32 v163, v160, v51
	v_add_f32_e32 v161, v95, v48
	v_cvt_pk_bf16_f32 v48, v77, v162
	v_cvt_pk_bf16_f32 v51, v62, v63
	s_waitcnt lgkmcnt(3)
	v_mfma_f32_32x32x16_bf16 v[78:93], v[52:55], v[96:99], 0
	v_cvt_pk_bf16_f32 v50, v60, v61
	v_exp_f32_e32 v60, v34
	v_exp_f32_e32 v61, v35
	v_exp_f32_e32 v36, v36
	v_exp_f32_e32 v37, v37
	v_exp_f32_e32 v38, v38
	v_exp_f32_e32 v39, v39
	s_waitcnt lgkmcnt(2)
	v_mfma_f32_32x32x16_bf16 v[62:77], v[72:75], v[96:99], 0
	ds_read_b128 v[52:55], v166
	ds_read_b128 v[152:155], v166 offset:4096
	v_add_f32_e32 v151, v60, v151
	v_add_f32_e32 v162, v61, v32
	s_waitcnt lgkmcnt(3)
	v_mfma_f32_32x32x16_bf16 v[78:93], v[112:115], v[100:103], v[78:93]
	v_add_f32_e32 v112, v36, v161
	v_add_f32_e32 v113, v37, v163
	v_add_f32_e32 v114, v38, v151
	v_exp_f32_e32 v115, v40
	v_add_f32_e32 v40, v39, v162
	ds_read_b128 v[32:35], v167
	ds_read_b128 v[156:159], v167 offset:4096
	s_waitcnt lgkmcnt(4)
	v_mfma_f32_32x32x16_bf16 v[62:77], v[116:119], v[100:103], v[62:77]
	v_exp_f32_e32 v116, v41
	v_add_f32_e32 v41, v115, v112
	s_min_u32 s9, s3, s2
	s_lshl_b32 s9, s9, 6
	v_add_f32_e32 v112, v116, v113
	s_waitcnt lgkmcnt(3)
	v_mfma_f32_32x32x16_bf16 v[78:93], v[52:55], v[104:107], v[78:93]
	v_cvt_pk_bf16_f32 v54, v36, v37
	v_exp_f32_e32 v37, v42
	v_cvt_pk_bf16_f32 v55, v38, v39
	v_exp_f32_e32 v38, v43
	v_exp_f32_e32 v39, v44
	v_exp_f32_e32 v44, v45
	v_exp_f32_e32 v45, v46
	v_exp_f32_e32 v46, v47
	v_cvt_pk_bf16_f32 v52, v95, v160
	v_cvt_pk_bf16_f32 v53, v60, v61
	v_add_f32_e32 v36, v37, v114
	v_add_f32_e32 v43, v38, v40
	v_add_f32_e32 v40, v39, v41
	v_add_f32_e32 v42, v44, v112
	v_add_f32_e32 v41, v45, v36
	v_add_f32_e32 v43, v46, v43
	v_cvt_pk_bf16_f32 v36, v115, v116
	v_cvt_pk_bf16_f32 v37, v37, v38
	v_cvt_pk_bf16_f32 v38, v39, v44
	v_cvt_pk_bf16_f32 v39, v45, v46
	s_waitcnt lgkmcnt(1)
	v_mfma_f32_32x32x16_bf16 v[78:93], v[32:35], v[108:111], v[78:93]
	s_waitcnt lgkmcnt(0)
	s_barrier
	v_mad_u64_u32 v[32:33], s[18:19], s9, v237, v[132:133]
	global_load_dwordx4 v[112:115], v[32:33], off offset:2048
	global_load_dwordx4 v[116:119], v[136:137], off
	v_add_f32_e64 v32, v40, v42
	v_add_f32_e64 v33, v41, v43
	s_waitcnt vmcnt(4)
	ds_write_b128 v142, v[120:123]
	s_waitcnt vmcnt(3)
	ds_write_b128 v142, v[124:127] offset:8192
	v_mfma_f32_32x32x16_bf16 v[62:77], v[152:155], v[104:107], v[62:77]
	v_add_f32_e32 v32, v32, v33
	v_add_f32_e32 v150, v150, v32
	s_waitcnt lgkmcnt(2)
	v_mfma_f32_32x32x16_bf16 v[62:77], v[156:159], v[108:111], v[62:77]
	ds_read_b128 v[32:35], v144 offset:24576
	ds_read_b128 v[40:43], v144 offset:28672
	ds_read_b128 v[44:47], v141 offset:24576
	ds_read_b128 v[120:123], v141 offset:28672
	v_exp_f32_e32 v60, v78
	s_waitcnt lgkmcnt(3)
	v_mfma_f32_32x32x16_bf16 v[16:31], v[32:35], v[56:59], v[16:31]
	v_exp_f32_e32 v61, v79
	v_exp_f32_e32 v95, v80
	v_exp_f32_e32 v81, v81
	ds_read_b128 v[152:155], v140 offset:24576
	ds_read_b128 v[156:159], v140 offset:28672
	s_waitcnt lgkmcnt(4)
	v_mfma_f32_32x32x16_bf16 v[0:15], v[40:43], v[56:59], v[0:15]
	v_exp_f32_e32 v82, v82
	v_exp_f32_e32 v83, v83
	v_add_f32_e32 v78, v82, v60
	v_add_f32_e32 v79, v83, v61
	s_waitcnt lgkmcnt(2)
	v_mfma_f32_32x32x16_bf16 v[0:15], v[120:123], v[48:51], v[0:15]
	ds_read_b128 v[56:59], v139 offset:24576
	ds_read_b128 v[160:163], v139 offset:28672
	ds_read_b128 v[40:43], v164 offset:16384
	ds_read_b128 v[32:35], v164 offset:20480
	v_cvt_pk_bf16_f32 v82, v82, v83
	v_exp_f32_e32 v151, v62
	v_exp_f32_e32 v64, v64
	v_exp_f32_e32 v65, v65
	v_mfma_f32_32x32x16_bf16 v[16:31], v[44:47], v[48:51], v[16:31]
	v_exp_f32_e32 v44, v84
	v_exp_f32_e32 v45, v85
	v_exp_f32_e32 v84, v86
	v_exp_f32_e32 v85, v87
	v_add_f32_e32 v46, v44, v95
	v_add_f32_e32 v47, v45, v81
	v_add_f32_e32 v48, v84, v78
	s_waitcnt lgkmcnt(4)
	v_mfma_f32_32x32x16_bf16 v[0:15], v[156:159], v[52:55], v[0:15]
	v_add_f32_e32 v49, v85, v79
	v_exp_f32_e32 v78, v88
	v_exp_f32_e32 v79, v89
	v_exp_f32_e32 v87, v92
	v_cvt_pk_bf16_f32 v83, v44, v45
	v_exp_f32_e32 v44, v90
	v_mfma_f32_32x32x16_bf16 v[16:31], v[152:155], v[52:55], v[16:31]
	v_exp_f32_e32 v45, v91
	v_exp_f32_e32 v92, v93
	v_add_f32_e32 v46, v78, v46
	v_add_f32_e32 v47, v79, v47
	ds_read_b128 v[124:127], v165 offset:16384
	ds_read_b128 v[120:123], v165 offset:20480
	s_waitcnt lgkmcnt(4)
	v_mfma_f32_32x32x16_bf16 v[0:15], v[160:163], v[36:39], v[0:15]
	v_exp_f32_e32 v160, v63
	v_cvt_pk_bf16_f32 v80, v60, v61
	v_cvt_pk_bf16_f32 v81, v95, v81
	v_add_f32_e32 v48, v44, v48
	v_add_f32_e32 v49, v45, v49
	v_add_f32_e32 v46, v87, v46
	v_add_f32_e32 v47, v92, v47
	v_mfma_f32_32x32x16_bf16 v[16:31], v[56:59], v[36:39], v[16:31]
	v_add_f32_e32 v161, v151, v48
	v_add_f32_e32 v162, v160, v49
	v_cvt_pk_bf16_f32 v84, v84, v85
	v_cvt_pk_bf16_f32 v85, v78, v79
	v_cvt_pk_bf16_f32 v86, v44, v45
	v_add_f32_e32 v78, v64, v46
	v_add_f32_e32 v79, v65, v47
	s_waitcnt lgkmcnt(3)
	v_mfma_f32_32x32x16_bf16 v[48:63], v[40:43], v[96:99], 0
	ds_read_b128 v[88:91], v166 offset:16384
	ds_read_b128 v[152:155], v166 offset:20480
	v_exp_f32_e32 v66, v66
	v_exp_f32_e32 v67, v67
	v_exp_f32_e32 v68, v68
	v_exp_f32_e32 v69, v69
	v_cvt_pk_bf16_f32 v87, v87, v92
	s_waitcnt lgkmcnt(4)
	v_mfma_f32_32x32x16_bf16 v[32:47], v[32:35], v[96:99], 0
	ds_read_b128 v[156:159], v167 offset:16384
	ds_read_b128 v[92:95], v167 offset:20480
	v_add_f32_e32 v161, v66, v161
	v_add_f32_e32 v162, v67, v162
	v_add_f32_e32 v78, v68, v78
	v_add_f32_e32 v79, v69, v79
	s_waitcnt lgkmcnt(5)
	v_mfma_f32_32x32x16_bf16 v[48:63], v[124:127], v[100:103], v[48:63]
	v_exp_f32_e32 v70, v70
	v_exp_f32_e32 v71, v71
	s_add_i32 s9, s3, 2
	s_add_i32 s3, s3, -2
	v_lshl_add_u64 v[136:137], v[136:137], 0, s[22:23]
	s_waitcnt lgkmcnt(4)
	v_mfma_f32_32x32x16_bf16 v[32:47], v[120:123], v[100:103], v[32:47]
	v_add_f32_e32 v120, v70, v161
	v_add_f32_e32 v121, v71, v162
	s_cmp_lt_u32 s3, s2
	s_mov_b32 s3, s9
	s_waitcnt lgkmcnt(3)
	v_mfma_f32_32x32x16_bf16 v[48:63], v[88:91], v[104:107], v[48:63]
	v_cvt_pk_bf16_f32 v91, v68, v69
	v_exp_f32_e32 v68, v72
	v_exp_f32_e32 v69, v73
	v_exp_f32_e32 v72, v74
	v_exp_f32_e32 v73, v75
	v_exp_f32_e32 v74, v76
	v_exp_f32_e32 v75, v77
	s_waitcnt lgkmcnt(2)
	v_mfma_f32_32x32x16_bf16 v[32:47], v[152:155], v[104:107], v[32:47]
	v_cvt_pk_bf16_f32 v88, v151, v160
	v_cvt_pk_bf16_f32 v89, v64, v65
	v_cvt_pk_bf16_f32 v90, v66, v67
	v_add_f32_e32 v65, v68, v78
	v_add_f32_e32 v67, v69, v79
	s_waitcnt lgkmcnt(1)
	v_mfma_f32_32x32x16_bf16 v[48:63], v[156:159], v[108:111], v[48:63]
	v_add_f32_e32 v64, v72, v120
	v_add_f32_e32 v66, v73, v121
	v_add_f32_e32 v65, v74, v65
	v_add_f32_e32 v67, v75, v67
	s_waitcnt lgkmcnt(0)
	v_mfma_f32_32x32x16_bf16 v[32:47], v[92:95], v[108:111], v[32:47]
	v_cvt_pk_bf16_f32 v92, v70, v71
	v_cvt_pk_bf16_f32 v93, v68, v69
	v_cvt_pk_bf16_f32 v94, v72, v73
	v_cvt_pk_bf16_f32 v95, v74, v75
	v_add_f32_e64 v64, v64, v66
	v_add_f32_e64 v65, v65, v67
	s_waitcnt lgkmcnt(0)
	s_barrier
	v_add_f32_e32 v64, v64, v65
	v_add_f32_e32 v150, v150, v64
.Lpeel_8:
	s_add_i32 s9, s3, -1
	s_min_u32 s9, s9, s2
	s_lshl_b32 s9, s9, 6
	s_waitcnt vmcnt(1)
	ds_write_b128 v142, v[112:115] offset:16384
	s_waitcnt vmcnt(0)
	ds_write_b128 v142, v[116:119] offset:24576
	v_mad_u64_u32 v[64:65], s[18:19], s9, v237, v[132:133]
	global_load_dwordx4 v[120:123], v[64:65], off offset:2048
	global_load_dwordx4 v[124:127], v[136:137], off offset:-128
	ds_read_b128 v[64:67], v144 offset:8192
	ds_read_b128 v[68:71], v144 offset:12288
	ds_read_b128 v[72:75], v141 offset:8192
	ds_read_b128 v[76:79], v141 offset:12288
	v_exp_f32_e32 v151, v48
	v_exp_f32_e32 v152, v49
	s_waitcnt lgkmcnt(3)
	v_mfma_f32_32x32x16_bf16 v[16:31], v[64:67], v[80:83], v[16:31]
	v_exp_f32_e32 v153, v50
	v_exp_f32_e32 v154, v51
	ds_read_b128 v[48:51], v140 offset:8192
	ds_read_b128 v[64:67], v140 offset:12288
	v_exp_f32_e32 v155, v52
	s_waitcnt lgkmcnt(4)
	v_mfma_f32_32x32x16_bf16 v[0:15], v[68:71], v[80:83], v[0:15]
	v_exp_f32_e32 v156, v53
	v_exp_f32_e32 v159, v54
	v_exp_f32_e32 v160, v55
	v_exp_f32_e32 v162, v57
	s_waitcnt lgkmcnt(3)
	v_mfma_f32_32x32x16_bf16 v[16:31], v[72:75], v[84:87], v[16:31]
	ds_read_b128 v[68:71], v139 offset:8192
	ds_read_b128 v[80:83], v139 offset:12288
	v_add_f32_e32 v157, v155, v151
	v_add_f32_e32 v158, v156, v152
	ds_read_b128 v[52:55], v164
	ds_read_b128 v[72:75], v164 offset:4096
	v_add_f32_e32 v161, v159, v153
	s_waitcnt lgkmcnt(6)
	v_mfma_f32_32x32x16_bf16 v[0:15], v[76:79], v[84:87], v[0:15]
	v_exp_f32_e32 v77, v56
	v_add_f32_e32 v76, v160, v154
	v_exp_f32_e32 v62, v62
	ds_read_b128 v[112:115], v165
	ds_read_b128 v[116:119], v165 offset:4096
	v_cvt_pk_bf16_f32 v56, v151, v152
	s_waitcnt lgkmcnt(7)
	v_mfma_f32_32x32x16_bf16 v[16:31], v[48:51], v[88:91], v[16:31]
	v_exp_f32_e32 v49, v58
	v_exp_f32_e32 v50, v59
	v_add_f32_e32 v48, v77, v157
	v_add_f32_e32 v51, v162, v158
	v_add_f32_e32 v78, v49, v161
	v_add_f32_e32 v76, v50, v76
	s_waitcnt lgkmcnt(6)
	v_mfma_f32_32x32x16_bf16 v[0:15], v[64:67], v[88:91], v[0:15]
	v_exp_f32_e32 v60, v60
	v_add_f32_e32 v151, v62, v78
	v_exp_f32_e32 v61, v61
	v_exp_f32_e32 v63, v63
	v_cvt_pk_bf16_f32 v59, v159, v160
	v_exp_f32_e32 v160, v33
	s_waitcnt lgkmcnt(5)
	v_mfma_f32_32x32x16_bf16 v[16:31], v[68:71], v[92:95], v[16:31]
	v_cvt_pk_bf16_f32 v57, v153, v154
	v_cvt_pk_bf16_f32 v58, v155, v156
	v_add_f32_e32 v48, v60, v48
	v_add_f32_e32 v51, v61, v51
	v_cvt_pk_bf16_f32 v49, v49, v50
	s_waitcnt lgkmcnt(4)
	v_mfma_f32_32x32x16_bf16 v[0:15], v[80:83], v[92:95], v[0:15]
	v_readfirstlane_b32 s18, v171
	s_mov_b64 vcc, s[34:35]
	s_add_u32 m0, s18, 0x17800
	s_nop 0
	global_load_lds_dwordx4 v170, vcc offset:2048
	v_exp_f32_e32 v95, v32
	v_add_f32_e32 v32, v63, v76
	v_add_f32_e32 v163, v160, v51
	v_add_f32_e32 v161, v95, v48
	v_cvt_pk_bf16_f32 v48, v77, v162
	v_cvt_pk_bf16_f32 v51, v62, v63
	s_waitcnt lgkmcnt(3)
	v_mfma_f32_32x32x16_bf16 v[78:93], v[52:55], v[96:99], 0
	v_cvt_pk_bf16_f32 v50, v60, v61
	v_exp_f32_e32 v60, v34
	v_exp_f32_e32 v61, v35
	v_exp_f32_e32 v36, v36
	v_exp_f32_e32 v37, v37
	v_exp_f32_e32 v38, v38
	v_exp_f32_e32 v39, v39
	s_waitcnt lgkmcnt(2)
	v_mfma_f32_32x32x16_bf16 v[62:77], v[72:75], v[96:99], 0
	ds_read_b128 v[52:55], v166
	ds_read_b128 v[152:155], v166 offset:4096
	v_add_f32_e32 v151, v60, v151
	v_add_f32_e32 v162, v61, v32
	s_waitcnt lgkmcnt(3)
	v_mfma_f32_32x32x16_bf16 v[78:93], v[112:115], v[100:103], v[78:93]
	v_add_f32_e32 v112, v36, v161
	v_add_f32_e32 v113, v37, v163
	v_add_f32_e32 v114, v38, v151
	v_exp_f32_e32 v115, v40
	v_add_f32_e32 v40, v39, v162
	ds_read_b128 v[32:35], v167
	ds_read_b128 v[156:159], v167 offset:4096
	s_waitcnt lgkmcnt(4)
	v_mfma_f32_32x32x16_bf16 v[62:77], v[116:119], v[100:103], v[62:77]
	v_exp_f32_e32 v116, v41
	v_add_f32_e32 v41, v115, v112
	s_min_u32 s9, s3, s2
	s_lshl_b32 s9, s9, 6
	v_add_f32_e32 v112, v116, v113
	s_waitcnt lgkmcnt(3)
	v_mfma_f32_32x32x16_bf16 v[78:93], v[52:55], v[104:107], v[78:93]
	v_cvt_pk_bf16_f32 v54, v36, v37
	v_exp_f32_e32 v37, v42
	v_cvt_pk_bf16_f32 v55, v38, v39
	v_exp_f32_e32 v38, v43
	v_exp_f32_e32 v39, v44
	v_exp_f32_e32 v44, v45
	v_exp_f32_e32 v45, v46
	v_exp_f32_e32 v46, v47
	v_cvt_pk_bf16_f32 v52, v95, v160
	v_cvt_pk_bf16_f32 v53, v60, v61
	v_add_f32_e32 v36, v37, v114
	v_add_f32_e32 v43, v38, v40
	v_add_f32_e32 v40, v39, v41
	v_add_f32_e32 v42, v44, v112
	v_add_f32_e32 v41, v45, v36
	v_add_f32_e32 v43, v46, v43
	v_cvt_pk_bf16_f32 v36, v115, v116
	v_cvt_pk_bf16_f32 v37, v37, v38
	v_cvt_pk_bf16_f32 v38, v39, v44
	v_cvt_pk_bf16_f32 v39, v45, v46
	s_waitcnt lgkmcnt(1)
	v_mfma_f32_32x32x16_bf16 v[78:93], v[32:35], v[108:111], v[78:93]
	s_waitcnt lgkmcnt(0)
	s_barrier
	v_mad_u64_u32 v[32:33], s[18:19], s9, v237, v[132:133]
	global_load_dwordx4 v[112:115], v[32:33], off offset:2048
	global_load_dwordx4 v[116:119], v[136:137], off
	v_add_f32_e64 v32, v40, v42
	v_add_f32_e64 v33, v41, v43
	s_waitcnt vmcnt(4)
	ds_write_b128 v142, v[120:123]
	s_waitcnt vmcnt(3)
	ds_write_b128 v142, v[124:127] offset:8192
	v_mfma_f32_32x32x16_bf16 v[62:77], v[152:155], v[104:107], v[62:77]
	v_add_f32_e32 v32, v32, v33
	v_add_f32_e32 v150, v150, v32
	s_waitcnt lgkmcnt(2)
	v_mfma_f32_32x32x16_bf16 v[62:77], v[156:159], v[108:111], v[62:77]
	ds_read_b128 v[32:35], v144 offset:24576
	ds_read_b128 v[40:43], v144 offset:28672
	ds_read_b128 v[44:47], v141 offset:24576
	ds_read_b128 v[120:123], v141 offset:28672
	v_exp_f32_e32 v60, v78
	s_waitcnt lgkmcnt(3)
	v_mfma_f32_32x32x16_bf16 v[16:31], v[32:35], v[56:59], v[16:31]
	v_exp_f32_e32 v61, v79
	v_exp_f32_e32 v95, v80
	v_exp_f32_e32 v81, v81
	ds_read_b128 v[152:155], v140 offset:24576
	ds_read_b128 v[156:159], v140 offset:28672
	s_waitcnt lgkmcnt(4)
	v_mfma_f32_32x32x16_bf16 v[0:15], v[40:43], v[56:59], v[0:15]
	v_exp_f32_e32 v82, v82
	v_exp_f32_e32 v83, v83
	v_add_f32_e32 v78, v82, v60
	v_add_f32_e32 v79, v83, v61
	s_waitcnt lgkmcnt(2)
	v_mfma_f32_32x32x16_bf16 v[0:15], v[120:123], v[48:51], v[0:15]
	ds_read_b128 v[56:59], v139 offset:24576
	ds_read_b128 v[160:163], v139 offset:28672
	ds_read_b128 v[40:43], v164 offset:16384
	ds_read_b128 v[32:35], v164 offset:20480
	v_cvt_pk_bf16_f32 v82, v82, v83
	v_exp_f32_e32 v151, v62
	v_exp_f32_e32 v64, v64
	v_exp_f32_e32 v65, v65
	v_mfma_f32_32x32x16_bf16 v[16:31], v[44:47], v[48:51], v[16:31]
	v_exp_f32_e32 v44, v84
	v_exp_f32_e32 v45, v85
	v_exp_f32_e32 v84, v86
	v_exp_f32_e32 v85, v87
	v_add_f32_e32 v46, v44, v95
	v_add_f32_e32 v47, v45, v81
	v_add_f32_e32 v48, v84, v78
	s_waitcnt lgkmcnt(4)
	v_mfma_f32_32x32x16_bf16 v[0:15], v[156:159], v[52:55], v[0:15]
	v_add_f32_e32 v49, v85, v79
	v_exp_f32_e32 v78, v88
	v_exp_f32_e32 v79, v89
	v_exp_f32_e32 v87, v92
	v_cvt_pk_bf16_f32 v83, v44, v45
	v_exp_f32_e32 v44, v90
	v_mfma_f32_32x32x16_bf16 v[16:31], v[152:155], v[52:55], v[16:31]
	v_exp_f32_e32 v45, v91
	v_exp_f32_e32 v92, v93
	v_add_f32_e32 v46, v78, v46
	v_add_f32_e32 v47, v79, v47
	ds_read_b128 v[124:127], v165 offset:16384
	ds_read_b128 v[120:123], v165 offset:20480
	s_waitcnt lgkmcnt(4)
	v_mfma_f32_32x32x16_bf16 v[0:15], v[160:163], v[36:39], v[0:15]
	v_exp_f32_e32 v160, v63
	v_cvt_pk_bf16_f32 v80, v60, v61
	v_cvt_pk_bf16_f32 v81, v95, v81
	v_add_f32_e32 v48, v44, v48
	v_add_f32_e32 v49, v45, v49
	v_add_f32_e32 v46, v87, v46
	v_add_f32_e32 v47, v92, v47
	v_mfma_f32_32x32x16_bf16 v[16:31], v[56:59], v[36:39], v[16:31]
	v_add_f32_e32 v161, v151, v48
	v_add_f32_e32 v162, v160, v49
	v_cvt_pk_bf16_f32 v84, v84, v85
	v_cvt_pk_bf16_f32 v85, v78, v79
	v_cvt_pk_bf16_f32 v86, v44, v45
	v_add_f32_e32 v78, v64, v46
	v_add_f32_e32 v79, v65, v47
	s_waitcnt lgkmcnt(3)
	v_mfma_f32_32x32x16_bf16 v[48:63], v[40:43], v[96:99], 0
	ds_read_b128 v[88:91], v166 offset:16384
	ds_read_b128 v[152:155], v166 offset:20480
	v_exp_f32_e32 v66, v66
	v_exp_f32_e32 v67, v67
	v_exp_f32_e32 v68, v68
	v_exp_f32_e32 v69, v69
	v_cvt_pk_bf16_f32 v87, v87, v92
	s_waitcnt lgkmcnt(4)
	v_mfma_f32_32x32x16_bf16 v[32:47], v[32:35], v[96:99], 0
	ds_read_b128 v[156:159], v167 offset:16384
	ds_read_b128 v[92:95], v167 offset:20480
	v_add_f32_e32 v161, v66, v161
	v_add_f32_e32 v162, v67, v162
	v_add_f32_e32 v78, v68, v78
	v_add_f32_e32 v79, v69, v79
	s_waitcnt lgkmcnt(5)
	v_mfma_f32_32x32x16_bf16 v[48:63], v[124:127], v[100:103], v[48:63]
	v_exp_f32_e32 v70, v70
	v_exp_f32_e32 v71, v71
	s_add_i32 s9, s3, 2
	s_add_i32 s3, s3, -2
	v_lshl_add_u64 v[136:137], v[136:137], 0, s[22:23]
	s_waitcnt lgkmcnt(4)
	v_mfma_f32_32x32x16_bf16 v[32:47], v[120:123], v[100:103], v[32:47]
	v_add_f32_e32 v120, v70, v161
	v_add_f32_e32 v121, v71, v162
	s_cmp_lt_u32 s3, s2
	s_mov_b32 s3, s9
	s_waitcnt lgkmcnt(3)
	v_mfma_f32_32x32x16_bf16 v[48:63], v[88:91], v[104:107], v[48:63]
	v_cvt_pk_bf16_f32 v91, v68, v69
	v_exp_f32_e32 v68, v72
	v_exp_f32_e32 v69, v73
	v_exp_f32_e32 v72, v74
	v_exp_f32_e32 v73, v75
	v_exp_f32_e32 v74, v76
	v_exp_f32_e32 v75, v77
	s_waitcnt lgkmcnt(2)
	v_mfma_f32_32x32x16_bf16 v[32:47], v[152:155], v[104:107], v[32:47]
	v_cvt_pk_bf16_f32 v88, v151, v160
	v_cvt_pk_bf16_f32 v89, v64, v65
	v_cvt_pk_bf16_f32 v90, v66, v67
	v_add_f32_e32 v65, v68, v78
	v_add_f32_e32 v67, v69, v79
	s_waitcnt lgkmcnt(1)
	v_mfma_f32_32x32x16_bf16 v[48:63], v[156:159], v[108:111], v[48:63]
	v_add_f32_e32 v64, v72, v120
	v_add_f32_e32 v66, v73, v121
	v_add_f32_e32 v65, v74, v65
	v_add_f32_e32 v67, v75, v67
	s_waitcnt lgkmcnt(0)
	v_mfma_f32_32x32x16_bf16 v[32:47], v[92:95], v[108:111], v[32:47]
	v_cvt_pk_bf16_f32 v92, v70, v71
	v_cvt_pk_bf16_f32 v93, v68, v69
	v_cvt_pk_bf16_f32 v94, v72, v73
	v_cvt_pk_bf16_f32 v95, v74, v75
	v_add_f32_e64 v64, v64, v66
	v_add_f32_e64 v65, v65, v67
	s_waitcnt lgkmcnt(0)
	s_barrier
	v_add_f32_e32 v64, v64, v65
	v_add_f32_e32 v150, v150, v64
.Lpeel_9:
	s_add_i32 s9, s3, -1
	s_min_u32 s9, s9, s2
	s_lshl_b32 s9, s9, 6
	s_waitcnt vmcnt(1)
	ds_write_b128 v142, v[112:115] offset:16384
	s_waitcnt vmcnt(0)
	ds_write_b128 v142, v[116:119] offset:24576
	v_mad_u64_u32 v[64:65], s[18:19], s9, v237, v[132:133]
	global_load_dwordx4 v[120:123], v[64:65], off offset:2048
	global_load_dwordx4 v[124:127], v[136:137], off offset:-128
	ds_read_b128 v[64:67], v144 offset:8192
	ds_read_b128 v[68:71], v144 offset:12288
	ds_read_b128 v[72:75], v141 offset:8192
	ds_read_b128 v[76:79], v141 offset:12288
	v_exp_f32_e32 v151, v48
	v_exp_f32_e32 v152, v49
	s_waitcnt lgkmcnt(3)
	v_mfma_f32_32x32x16_bf16 v[16:31], v[64:67], v[80:83], v[16:31]
	v_exp_f32_e32 v153, v50
	v_exp_f32_e32 v154, v51
	ds_read_b128 v[48:51], v140 offset:8192
	ds_read_b128 v[64:67], v140 offset:12288
	v_exp_f32_e32 v155, v52
	s_waitcnt lgkmcnt(4)
	v_mfma_f32_32x32x16_bf16 v[0:15], v[68:71], v[80:83], v[0:15]
	v_exp_f32_e32 v156, v53
	v_exp_f32_e32 v159, v54
	v_exp_f32_e32 v160, v55
	v_exp_f32_e32 v162, v57
	s_waitcnt lgkmcnt(3)
	v_mfma_f32_32x32x16_bf16 v[16:31], v[72:75], v[84:87], v[16:31]
	ds_read_b128 v[68:71], v139 offset:8192
	ds_read_b128 v[80:83], v139 offset:12288
	v_add_f32_e32 v157, v155, v151
	v_add_f32_e32 v158, v156, v152
	ds_read_b128 v[52:55], v164
	ds_read_b128 v[72:75], v164 offset:4096
	v_add_f32_e32 v161, v159, v153
	s_waitcnt lgkmcnt(6)
	v_mfma_f32_32x32x16_bf16 v[0:15], v[76:79], v[84:87], v[0:15]
	v_exp_f32_e32 v77, v56
	v_add_f32_e32 v76, v160, v154
	v_exp_f32_e32 v62, v62
	ds_read_b128 v[112:115], v165
	ds_read_b128 v[116:119], v165 offset:4096
	v_cvt_pk_bf16_f32 v56, v151, v152
	s_waitcnt lgkmcnt(7)
	v_mfma_f32_32x32x16_bf16 v[16:31], v[48:51], v[88:91], v[16:31]
	v_exp_f32_e32 v49, v58
	v_exp_f32_e32 v50, v59
	v_add_f32_e32 v48, v77, v157
	v_add_f32_e32 v51, v162, v158
	v_add_f32_e32 v78, v49, v161
	v_add_f32_e32 v76, v50, v76
	s_waitcnt lgkmcnt(6)
	v_mfma_f32_32x32x16_bf16 v[0:15], v[64:67], v[88:91], v[0:15]
	v_exp_f32_e32 v60, v60
	v_add_f32_e32 v151, v62, v78
	v_exp_f32_e32 v61, v61
	v_exp_f32_e32 v63, v63
	v_cvt_pk_bf16_f32 v59, v159, v160
	v_exp_f32_e32 v160, v33
	s_waitcnt lgkmcnt(5)
	v_mfma_f32_32x32x16_bf16 v[16:31], v[68:71], v[92:95], v[16:31]
	v_cvt_pk_bf16_f32 v57, v153, v154
	v_cvt_pk_bf16_f32 v58, v155, v156
	v_add_f32_e32 v48, v60, v48
	v_add_f32_e32 v51, v61, v51
	v_cvt_pk_bf16_f32 v49, v49, v50
	s_waitcnt lgkmcnt(4)
	v_mfma_f32_32x32x16_bf16 v[0:15], v[80:83], v[92:95], v[0:15]
	v_readfirstlane_b32 s18, v171
	s_add_u32 vcc_lo, s34, 0x48000
	s_addc_u32 vcc_hi, s35, 0
	s_add_u32 m0, s18, 0x19800
	s_nop 0
	global_load_lds_dwordx4 v170, vcc offset:2048
	v_exp_f32_e32 v95, v32
	v_add_f32_e32 v32, v63, v76
	v_add_f32_e32 v163, v160, v51
	v_add_f32_e32 v161, v95, v48
	v_cvt_pk_bf16_f32 v48, v77, v162
	v_cvt_pk_bf16_f32 v51, v62, v63
	s_waitcnt lgkmcnt(3)
	v_mfma_f32_32x32x16_bf16 v[78:93], v[52:55], v[96:99], 0
	v_cvt_pk_bf16_f32 v50, v60, v61
	v_exp_f32_e32 v60, v34
	v_exp_f32_e32 v61, v35
	v_exp_f32_e32 v36, v36
	v_exp_f32_e32 v37, v37
	v_exp_f32_e32 v38, v38
	v_exp_f32_e32 v39, v39
	s_waitcnt lgkmcnt(2)
	v_mfma_f32_32x32x16_bf16 v[62:77], v[72:75], v[96:99], 0
	ds_read_b128 v[52:55], v166
	ds_read_b128 v[152:155], v166 offset:4096
	v_add_f32_e32 v151, v60, v151
	v_add_f32_e32 v162, v61, v32
	s_waitcnt lgkmcnt(3)
	v_mfma_f32_32x32x16_bf16 v[78:93], v[112:115], v[100:103], v[78:93]
	v_add_f32_e32 v112, v36, v161
	v_add_f32_e32 v113, v37, v163
	v_add_f32_e32 v114, v38, v151
	v_exp_f32_e32 v115, v40
	v_add_f32_e32 v40, v39, v162
	ds_read_b128 v[32:35], v167
	ds_read_b128 v[156:159], v167 offset:4096
	s_waitcnt lgkmcnt(4)
	v_mfma_f32_32x32x16_bf16 v[62:77], v[116:119], v[100:103], v[62:77]
	v_exp_f32_e32 v116, v41
	v_add_f32_e32 v41, v115, v112
	s_min_u32 s9, s3, s2
	s_lshl_b32 s9, s9, 6
	v_add_f32_e32 v112, v116, v113
	s_waitcnt lgkmcnt(3)
	v_mfma_f32_32x32x16_bf16 v[78:93], v[52:55], v[104:107], v[78:93]
	v_cvt_pk_bf16_f32 v54, v36, v37
	v_exp_f32_e32 v37, v42
	v_cvt_pk_bf16_f32 v55, v38, v39
	v_exp_f32_e32 v38, v43
	v_exp_f32_e32 v39, v44
	v_exp_f32_e32 v44, v45
	v_exp_f32_e32 v45, v46
	v_exp_f32_e32 v46, v47
	v_cvt_pk_bf16_f32 v52, v95, v160
	v_cvt_pk_bf16_f32 v53, v60, v61
	v_add_f32_e32 v36, v37, v114
	v_add_f32_e32 v43, v38, v40
	v_add_f32_e32 v40, v39, v41
	v_add_f32_e32 v42, v44, v112
	v_add_f32_e32 v41, v45, v36
	v_add_f32_e32 v43, v46, v43
	v_cvt_pk_bf16_f32 v36, v115, v116
	v_cvt_pk_bf16_f32 v37, v37, v38
	v_cvt_pk_bf16_f32 v38, v39, v44
	v_cvt_pk_bf16_f32 v39, v45, v46
	s_waitcnt lgkmcnt(1)
	v_mfma_f32_32x32x16_bf16 v[78:93], v[32:35], v[108:111], v[78:93]
	s_waitcnt lgkmcnt(0)
	s_barrier
	v_mad_u64_u32 v[32:33], s[18:19], s9, v237, v[132:133]
	global_load_dwordx4 v[112:115], v[32:33], off offset:2048
	global_load_dwordx4 v[116:119], v[136:137], off
	v_add_f32_e64 v32, v40, v42
	v_add_f32_e64 v33, v41, v43
	s_waitcnt vmcnt(4)
	ds_write_b128 v142, v[120:123]
	s_waitcnt vmcnt(3)
	ds_write_b128 v142, v[124:127] offset:8192
	v_mfma_f32_32x32x16_bf16 v[62:77], v[152:155], v[104:107], v[62:77]
	v_add_f32_e32 v32, v32, v33
	v_add_f32_e32 v150, v150, v32
	s_waitcnt lgkmcnt(2)
	v_mfma_f32_32x32x16_bf16 v[62:77], v[156:159], v[108:111], v[62:77]
	ds_read_b128 v[32:35], v144 offset:24576
	ds_read_b128 v[40:43], v144 offset:28672
	ds_read_b128 v[44:47], v141 offset:24576
	ds_read_b128 v[120:123], v141 offset:28672
	v_exp_f32_e32 v60, v78
	s_waitcnt lgkmcnt(3)
	v_mfma_f32_32x32x16_bf16 v[16:31], v[32:35], v[56:59], v[16:31]
	v_exp_f32_e32 v61, v79
	v_exp_f32_e32 v95, v80
	v_exp_f32_e32 v81, v81
	ds_read_b128 v[152:155], v140 offset:24576
	ds_read_b128 v[156:159], v140 offset:28672
	s_waitcnt lgkmcnt(4)
	v_mfma_f32_32x32x16_bf16 v[0:15], v[40:43], v[56:59], v[0:15]
	v_exp_f32_e32 v82, v82
	v_exp_f32_e32 v83, v83
	v_add_f32_e32 v78, v82, v60
	v_add_f32_e32 v79, v83, v61
	s_waitcnt lgkmcnt(2)
	v_mfma_f32_32x32x16_bf16 v[0:15], v[120:123], v[48:51], v[0:15]
	ds_read_b128 v[56:59], v139 offset:24576
	ds_read_b128 v[160:163], v139 offset:28672
	ds_read_b128 v[40:43], v164 offset:16384
	ds_read_b128 v[32:35], v164 offset:20480
	v_cvt_pk_bf16_f32 v82, v82, v83
	v_exp_f32_e32 v151, v62
	v_exp_f32_e32 v64, v64
	v_exp_f32_e32 v65, v65
	v_mfma_f32_32x32x16_bf16 v[16:31], v[44:47], v[48:51], v[16:31]
	v_exp_f32_e32 v44, v84
	v_exp_f32_e32 v45, v85
	v_exp_f32_e32 v84, v86
	v_exp_f32_e32 v85, v87
	v_add_f32_e32 v46, v44, v95
	v_add_f32_e32 v47, v45, v81
	v_add_f32_e32 v48, v84, v78
	s_waitcnt lgkmcnt(4)
	v_mfma_f32_32x32x16_bf16 v[0:15], v[156:159], v[52:55], v[0:15]
	v_add_f32_e32 v49, v85, v79
	v_exp_f32_e32 v78, v88
	v_exp_f32_e32 v79, v89
	v_exp_f32_e32 v87, v92
	v_cvt_pk_bf16_f32 v83, v44, v45
	v_exp_f32_e32 v44, v90
	v_mfma_f32_32x32x16_bf16 v[16:31], v[152:155], v[52:55], v[16:31]
	v_exp_f32_e32 v45, v91
	v_exp_f32_e32 v92, v93
	v_add_f32_e32 v46, v78, v46
	v_add_f32_e32 v47, v79, v47
	ds_read_b128 v[124:127], v165 offset:16384
	ds_read_b128 v[120:123], v165 offset:20480
	s_waitcnt lgkmcnt(4)
	v_mfma_f32_32x32x16_bf16 v[0:15], v[160:163], v[36:39], v[0:15]
	v_exp_f32_e32 v160, v63
	v_cvt_pk_bf16_f32 v80, v60, v61
	v_cvt_pk_bf16_f32 v81, v95, v81
	v_add_f32_e32 v48, v44, v48
	v_add_f32_e32 v49, v45, v49
	v_add_f32_e32 v46, v87, v46
	v_add_f32_e32 v47, v92, v47
	v_mfma_f32_32x32x16_bf16 v[16:31], v[56:59], v[36:39], v[16:31]
	v_add_f32_e32 v161, v151, v48
	v_add_f32_e32 v162, v160, v49
	v_cvt_pk_bf16_f32 v84, v84, v85
	v_cvt_pk_bf16_f32 v85, v78, v79
	v_cvt_pk_bf16_f32 v86, v44, v45
	v_add_f32_e32 v78, v64, v46
	v_add_f32_e32 v79, v65, v47
	s_waitcnt lgkmcnt(3)
	v_mfma_f32_32x32x16_bf16 v[48:63], v[40:43], v[96:99], 0
	ds_read_b128 v[88:91], v166 offset:16384
	ds_read_b128 v[152:155], v166 offset:20480
	v_exp_f32_e32 v66, v66
	v_exp_f32_e32 v67, v67
	v_exp_f32_e32 v68, v68
	v_exp_f32_e32 v69, v69
	v_cvt_pk_bf16_f32 v87, v87, v92
	s_waitcnt lgkmcnt(4)
	v_mfma_f32_32x32x16_bf16 v[32:47], v[32:35], v[96:99], 0
	ds_read_b128 v[156:159], v167 offset:16384
	ds_read_b128 v[92:95], v167 offset:20480
	v_add_f32_e32 v161, v66, v161
	v_add_f32_e32 v162, v67, v162
	v_add_f32_e32 v78, v68, v78
	v_add_f32_e32 v79, v69, v79
	s_waitcnt lgkmcnt(5)
	v_mfma_f32_32x32x16_bf16 v[48:63], v[124:127], v[100:103], v[48:63]
	v_exp_f32_e32 v70, v70
	v_exp_f32_e32 v71, v71
	s_add_i32 s9, s3, 2
	s_add_i32 s3, s3, -2
	v_lshl_add_u64 v[136:137], v[136:137], 0, s[22:23]
	s_waitcnt lgkmcnt(4)
	v_mfma_f32_32x32x16_bf16 v[32:47], v[120:123], v[100:103], v[32:47]
	v_add_f32_e32 v120, v70, v161
	v_add_f32_e32 v121, v71, v162
	s_cmp_lt_u32 s3, s2
	s_mov_b32 s3, s9
	s_waitcnt lgkmcnt(3)
	v_mfma_f32_32x32x16_bf16 v[48:63], v[88:91], v[104:107], v[48:63]
	v_cvt_pk_bf16_f32 v91, v68, v69
	v_exp_f32_e32 v68, v72
	v_exp_f32_e32 v69, v73
	v_exp_f32_e32 v72, v74
	v_exp_f32_e32 v73, v75
	v_exp_f32_e32 v74, v76
	v_exp_f32_e32 v75, v77
	s_waitcnt lgkmcnt(2)
	v_mfma_f32_32x32x16_bf16 v[32:47], v[152:155], v[104:107], v[32:47]
	v_cvt_pk_bf16_f32 v88, v151, v160
	v_cvt_pk_bf16_f32 v89, v64, v65
	v_cvt_pk_bf16_f32 v90, v66, v67
	v_add_f32_e32 v65, v68, v78
	v_add_f32_e32 v67, v69, v79
	s_waitcnt lgkmcnt(1)
	v_mfma_f32_32x32x16_bf16 v[48:63], v[156:159], v[108:111], v[48:63]
	v_add_f32_e32 v64, v72, v120
	v_add_f32_e32 v66, v73, v121
	v_add_f32_e32 v65, v74, v65
	v_add_f32_e32 v67, v75, v67
	s_waitcnt lgkmcnt(0)
	v_mfma_f32_32x32x16_bf16 v[32:47], v[92:95], v[108:111], v[32:47]
	v_cvt_pk_bf16_f32 v92, v70, v71
	v_cvt_pk_bf16_f32 v93, v68, v69
	v_cvt_pk_bf16_f32 v94, v72, v73
	v_cvt_pk_bf16_f32 v95, v74, v75
	v_add_f32_e64 v64, v64, v66
	v_add_f32_e64 v65, v65, v67
	s_waitcnt lgkmcnt(0)
	s_barrier
	v_add_f32_e32 v64, v64, v65
	v_add_f32_e32 v150, v150, v64
.Lpeel_10:
	s_add_i32 s9, s3, -1
	s_min_u32 s9, s9, s2
	s_lshl_b32 s9, s9, 6
	s_waitcnt vmcnt(1)
	ds_write_b128 v142, v[112:115] offset:16384
	s_waitcnt vmcnt(0)
	ds_write_b128 v142, v[116:119] offset:24576
	v_mad_u64_u32 v[64:65], s[18:19], s9, v237, v[132:133]
	global_load_dwordx4 v[120:123], v[64:65], off offset:2048
	global_load_dwordx4 v[124:127], v[136:137], off offset:-128
	ds_read_b128 v[64:67], v144 offset:8192
	ds_read_b128 v[68:71], v144 offset:12288
	ds_read_b128 v[72:75], v141 offset:8192
	ds_read_b128 v[76:79], v141 offset:12288
	v_exp_f32_e32 v151, v48
	v_exp_f32_e32 v152, v49
	s_waitcnt lgkmcnt(3)
	v_mfma_f32_32x32x16_bf16 v[16:31], v[64:67], v[80:83], v[16:31]
	v_exp_f32_e32 v153, v50
	v_exp_f32_e32 v154, v51
	ds_read_b128 v[48:51], v140 offset:8192
	ds_read_b128 v[64:67], v140 offset:12288
	v_exp_f32_e32 v155, v52
	s_waitcnt lgkmcnt(4)
	v_mfma_f32_32x32x16_bf16 v[0:15], v[68:71], v[80:83], v[0:15]
	v_exp_f32_e32 v156, v53
	v_exp_f32_e32 v159, v54
	v_exp_f32_e32 v160, v55
	v_exp_f32_e32 v162, v57
	s_waitcnt lgkmcnt(3)
	v_mfma_f32_32x32x16_bf16 v[16:31], v[72:75], v[84:87], v[16:31]
	ds_read_b128 v[68:71], v139 offset:8192
	ds_read_b128 v[80:83], v139 offset:12288
	v_add_f32_e32 v157, v155, v151
	v_add_f32_e32 v158, v156, v152
	ds_read_b128 v[52:55], v164
	ds_read_b128 v[72:75], v164 offset:4096
	v_add_f32_e32 v161, v159, v153
	s_waitcnt lgkmcnt(6)
	v_mfma_f32_32x32x16_bf16 v[0:15], v[76:79], v[84:87], v[0:15]
	v_exp_f32_e32 v77, v56
	v_add_f32_e32 v76, v160, v154
	v_exp_f32_e32 v62, v62
	ds_read_b128 v[112:115], v165
	ds_read_b128 v[116:119], v165 offset:4096
	v_cvt_pk_bf16_f32 v56, v151, v152
	s_waitcnt lgkmcnt(7)
	v_mfma_f32_32x32x16_bf16 v[16:31], v[48:51], v[88:91], v[16:31]
	v_exp_f32_e32 v49, v58
	v_exp_f32_e32 v50, v59
	v_add_f32_e32 v48, v77, v157
	v_add_f32_e32 v51, v162, v158
	v_add_f32_e32 v78, v49, v161
	v_add_f32_e32 v76, v50, v76
	s_waitcnt lgkmcnt(6)
	v_mfma_f32_32x32x16_bf16 v[0:15], v[64:67], v[88:91], v[0:15]
	v_exp_f32_e32 v60, v60
	v_add_f32_e32 v151, v62, v78
	v_exp_f32_e32 v61, v61
	v_exp_f32_e32 v63, v63
	v_cvt_pk_bf16_f32 v59, v159, v160
	v_exp_f32_e32 v160, v33
	s_waitcnt lgkmcnt(5)
	v_mfma_f32_32x32x16_bf16 v[16:31], v[68:71], v[92:95], v[16:31]
	v_cvt_pk_bf16_f32 v57, v153, v154
	v_cvt_pk_bf16_f32 v58, v155, v156
	v_add_f32_e32 v48, v60, v48
	v_add_f32_e32 v51, v61, v51
	v_cvt_pk_bf16_f32 v49, v49, v50
	s_waitcnt lgkmcnt(4)
	v_mfma_f32_32x32x16_bf16 v[0:15], v[80:83], v[92:95], v[0:15]
	v_readfirstlane_b32 s18, v171
	s_add_u32 vcc_lo, s34, 0x90000
	s_addc_u32 vcc_hi, s35, 0
	s_add_u32 m0, s18, 0x1b800
	s_nop 0
	global_load_lds_dwordx4 v170, vcc offset:2048
	v_exp_f32_e32 v95, v32
	v_add_f32_e32 v32, v63, v76
	v_add_f32_e32 v163, v160, v51
	v_add_f32_e32 v161, v95, v48
	v_cvt_pk_bf16_f32 v48, v77, v162
	v_cvt_pk_bf16_f32 v51, v62, v63
	s_waitcnt lgkmcnt(3)
	v_mfma_f32_32x32x16_bf16 v[78:93], v[52:55], v[96:99], 0
	v_cvt_pk_bf16_f32 v50, v60, v61
	v_exp_f32_e32 v60, v34
	v_exp_f32_e32 v61, v35
	v_exp_f32_e32 v36, v36
	v_exp_f32_e32 v37, v37
	v_exp_f32_e32 v38, v38
	v_exp_f32_e32 v39, v39
	s_waitcnt lgkmcnt(2)
	v_mfma_f32_32x32x16_bf16 v[62:77], v[72:75], v[96:99], 0
	ds_read_b128 v[52:55], v166
	ds_read_b128 v[152:155], v166 offset:4096
	v_add_f32_e32 v151, v60, v151
	v_add_f32_e32 v162, v61, v32
	s_waitcnt lgkmcnt(3)
	v_mfma_f32_32x32x16_bf16 v[78:93], v[112:115], v[100:103], v[78:93]
	v_add_f32_e32 v112, v36, v161
	v_add_f32_e32 v113, v37, v163
	v_add_f32_e32 v114, v38, v151
	v_exp_f32_e32 v115, v40
	v_add_f32_e32 v40, v39, v162
	ds_read_b128 v[32:35], v167
	ds_read_b128 v[156:159], v167 offset:4096
	s_waitcnt lgkmcnt(4)
	v_mfma_f32_32x32x16_bf16 v[62:77], v[116:119], v[100:103], v[62:77]
	v_exp_f32_e32 v116, v41
	v_add_f32_e32 v41, v115, v112
	s_min_u32 s9, s3, s2
	s_lshl_b32 s9, s9, 6
	v_add_f32_e32 v112, v116, v113
	s_waitcnt lgkmcnt(3)
	v_mfma_f32_32x32x16_bf16 v[78:93], v[52:55], v[104:107], v[78:93]
	v_cvt_pk_bf16_f32 v54, v36, v37
	v_exp_f32_e32 v37, v42
	v_cvt_pk_bf16_f32 v55, v38, v39
	v_exp_f32_e32 v38, v43
	v_exp_f32_e32 v39, v44
	v_exp_f32_e32 v44, v45
	v_exp_f32_e32 v45, v46
	v_exp_f32_e32 v46, v47
	v_cvt_pk_bf16_f32 v52, v95, v160
	v_cvt_pk_bf16_f32 v53, v60, v61
	v_add_f32_e32 v36, v37, v114
	v_add_f32_e32 v43, v38, v40
	v_add_f32_e32 v40, v39, v41
	v_add_f32_e32 v42, v44, v112
	v_add_f32_e32 v41, v45, v36
	v_add_f32_e32 v43, v46, v43
	v_cvt_pk_bf16_f32 v36, v115, v116
	v_cvt_pk_bf16_f32 v37, v37, v38
	v_cvt_pk_bf16_f32 v38, v39, v44
	v_cvt_pk_bf16_f32 v39, v45, v46
	s_waitcnt lgkmcnt(1)
	v_mfma_f32_32x32x16_bf16 v[78:93], v[32:35], v[108:111], v[78:93]
	s_waitcnt lgkmcnt(0)
	s_barrier
	v_mad_u64_u32 v[32:33], s[18:19], s9, v237, v[132:133]
	global_load_dwordx4 v[112:115], v[32:33], off offset:2048
	global_load_dwordx4 v[116:119], v[136:137], off
	v_add_f32_e64 v32, v40, v42
	v_add_f32_e64 v33, v41, v43
	s_waitcnt vmcnt(4)
	ds_write_b128 v142, v[120:123]
	s_waitcnt vmcnt(3)
	ds_write_b128 v142, v[124:127] offset:8192
	v_mfma_f32_32x32x16_bf16 v[62:77], v[152:155], v[104:107], v[62:77]
	v_add_f32_e32 v32, v32, v33
	v_add_f32_e32 v150, v150, v32
	s_waitcnt lgkmcnt(2)
	v_mfma_f32_32x32x16_bf16 v[62:77], v[156:159], v[108:111], v[62:77]
	ds_read_b128 v[32:35], v144 offset:24576
	ds_read_b128 v[40:43], v144 offset:28672
	ds_read_b128 v[44:47], v141 offset:24576
	ds_read_b128 v[120:123], v141 offset:28672
	v_exp_f32_e32 v60, v78
	s_waitcnt lgkmcnt(3)
	v_mfma_f32_32x32x16_bf16 v[16:31], v[32:35], v[56:59], v[16:31]
	v_exp_f32_e32 v61, v79
	v_exp_f32_e32 v95, v80
	v_exp_f32_e32 v81, v81
	ds_read_b128 v[152:155], v140 offset:24576
	ds_read_b128 v[156:159], v140 offset:28672
	s_waitcnt lgkmcnt(4)
	v_mfma_f32_32x32x16_bf16 v[0:15], v[40:43], v[56:59], v[0:15]
	v_exp_f32_e32 v82, v82
	v_exp_f32_e32 v83, v83
	v_add_f32_e32 v78, v82, v60
	v_add_f32_e32 v79, v83, v61
	s_waitcnt lgkmcnt(2)
	v_mfma_f32_32x32x16_bf16 v[0:15], v[120:123], v[48:51], v[0:15]
	ds_read_b128 v[56:59], v139 offset:24576
	ds_read_b128 v[160:163], v139 offset:28672
	ds_read_b128 v[40:43], v164 offset:16384
	ds_read_b128 v[32:35], v164 offset:20480
	v_cvt_pk_bf16_f32 v82, v82, v83
	v_exp_f32_e32 v151, v62
	v_exp_f32_e32 v64, v64
	v_exp_f32_e32 v65, v65
	v_mfma_f32_32x32x16_bf16 v[16:31], v[44:47], v[48:51], v[16:31]
	v_exp_f32_e32 v44, v84
	v_exp_f32_e32 v45, v85
	v_exp_f32_e32 v84, v86
	v_exp_f32_e32 v85, v87
	v_add_f32_e32 v46, v44, v95
	v_add_f32_e32 v47, v45, v81
	v_add_f32_e32 v48, v84, v78
	s_waitcnt lgkmcnt(4)
	v_mfma_f32_32x32x16_bf16 v[0:15], v[156:159], v[52:55], v[0:15]
	v_add_f32_e32 v49, v85, v79
	v_exp_f32_e32 v78, v88
	v_exp_f32_e32 v79, v89
	v_exp_f32_e32 v87, v92
	v_cvt_pk_bf16_f32 v83, v44, v45
	v_exp_f32_e32 v44, v90
	v_mfma_f32_32x32x16_bf16 v[16:31], v[152:155], v[52:55], v[16:31]
	v_exp_f32_e32 v45, v91
	v_exp_f32_e32 v92, v93
	v_add_f32_e32 v46, v78, v46
	v_add_f32_e32 v47, v79, v47
	ds_read_b128 v[124:127], v165 offset:16384
	ds_read_b128 v[120:123], v165 offset:20480
	s_waitcnt lgkmcnt(4)
	v_mfma_f32_32x32x16_bf16 v[0:15], v[160:163], v[36:39], v[0:15]
	v_exp_f32_e32 v160, v63
	v_cvt_pk_bf16_f32 v80, v60, v61
	v_cvt_pk_bf16_f32 v81, v95, v81
	v_add_f32_e32 v48, v44, v48
	v_add_f32_e32 v49, v45, v49
	v_add_f32_e32 v46, v87, v46
	v_add_f32_e32 v47, v92, v47
	v_mfma_f32_32x32x16_bf16 v[16:31], v[56:59], v[36:39], v[16:31]
	v_add_f32_e32 v161, v151, v48
	v_add_f32_e32 v162, v160, v49
	v_cvt_pk_bf16_f32 v84, v84, v85
	v_cvt_pk_bf16_f32 v85, v78, v79
	v_cvt_pk_bf16_f32 v86, v44, v45
	v_add_f32_e32 v78, v64, v46
	v_add_f32_e32 v79, v65, v47
	s_waitcnt lgkmcnt(3)
	v_mfma_f32_32x32x16_bf16 v[48:63], v[40:43], v[96:99], 0
	ds_read_b128 v[88:91], v166 offset:16384
	ds_read_b128 v[152:155], v166 offset:20480
	v_exp_f32_e32 v66, v66
	v_exp_f32_e32 v67, v67
	v_exp_f32_e32 v68, v68
	v_exp_f32_e32 v69, v69
	v_cvt_pk_bf16_f32 v87, v87, v92
	s_waitcnt lgkmcnt(4)
	v_mfma_f32_32x32x16_bf16 v[32:47], v[32:35], v[96:99], 0
	ds_read_b128 v[156:159], v167 offset:16384
	ds_read_b128 v[92:95], v167 offset:20480
	v_add_f32_e32 v161, v66, v161
	v_add_f32_e32 v162, v67, v162
	v_add_f32_e32 v78, v68, v78
	v_add_f32_e32 v79, v69, v79
	s_waitcnt lgkmcnt(5)
	v_mfma_f32_32x32x16_bf16 v[48:63], v[124:127], v[100:103], v[48:63]
	v_exp_f32_e32 v70, v70
	v_exp_f32_e32 v71, v71
	s_add_i32 s9, s3, 2
	s_add_i32 s3, s3, -2
	v_lshl_add_u64 v[136:137], v[136:137], 0, s[22:23]
	s_waitcnt lgkmcnt(4)
	v_mfma_f32_32x32x16_bf16 v[32:47], v[120:123], v[100:103], v[32:47]
	v_add_f32_e32 v120, v70, v161
	v_add_f32_e32 v121, v71, v162
	s_cmp_lt_u32 s3, s2
	s_mov_b32 s3, s9
	s_waitcnt lgkmcnt(3)
	v_mfma_f32_32x32x16_bf16 v[48:63], v[88:91], v[104:107], v[48:63]
	v_cvt_pk_bf16_f32 v91, v68, v69
	v_exp_f32_e32 v68, v72
	v_exp_f32_e32 v69, v73
	v_exp_f32_e32 v72, v74
	v_exp_f32_e32 v73, v75
	v_exp_f32_e32 v74, v76
	v_exp_f32_e32 v75, v77
	s_waitcnt lgkmcnt(2)
	v_mfma_f32_32x32x16_bf16 v[32:47], v[152:155], v[104:107], v[32:47]
	v_cvt_pk_bf16_f32 v88, v151, v160
	v_cvt_pk_bf16_f32 v89, v64, v65
	v_cvt_pk_bf16_f32 v90, v66, v67
	v_add_f32_e32 v65, v68, v78
	v_add_f32_e32 v67, v69, v79
	s_waitcnt lgkmcnt(1)
	v_mfma_f32_32x32x16_bf16 v[48:63], v[156:159], v[108:111], v[48:63]
	v_add_f32_e32 v64, v72, v120
	v_add_f32_e32 v66, v73, v121
	v_add_f32_e32 v65, v74, v65
	v_add_f32_e32 v67, v75, v67
	s_waitcnt lgkmcnt(0)
	v_mfma_f32_32x32x16_bf16 v[32:47], v[92:95], v[108:111], v[32:47]
	v_cvt_pk_bf16_f32 v92, v70, v71
	v_cvt_pk_bf16_f32 v93, v68, v69
	v_cvt_pk_bf16_f32 v94, v72, v73
	v_cvt_pk_bf16_f32 v95, v74, v75
	v_add_f32_e64 v64, v64, v66
	v_add_f32_e64 v65, v65, v67
	s_waitcnt lgkmcnt(0)
	s_barrier
	v_add_f32_e32 v64, v64, v65
	v_add_f32_e32 v150, v150, v64
.Lpeel_11:
	s_add_i32 s9, s3, -1
	s_min_u32 s9, s9, s2
	s_lshl_b32 s9, s9, 6
	s_waitcnt vmcnt(1)
	ds_write_b128 v142, v[112:115] offset:16384
	s_waitcnt vmcnt(0)
	ds_write_b128 v142, v[116:119] offset:24576
	v_mad_u64_u32 v[64:65], s[18:19], s9, v237, v[132:133]
	global_load_dwordx4 v[120:123], v[64:65], off offset:2048
	global_load_dwordx4 v[124:127], v[136:137], off offset:-128
	ds_read_b128 v[64:67], v144 offset:8192
	ds_read_b128 v[68:71], v144 offset:12288
	ds_read_b128 v[72:75], v141 offset:8192
	ds_read_b128 v[76:79], v141 offset:12288
	v_exp_f32_e32 v151, v48
	v_exp_f32_e32 v152, v49
	s_waitcnt lgkmcnt(3)
	v_mfma_f32_32x32x16_bf16 v[16:31], v[64:67], v[80:83], v[16:31]
	v_exp_f32_e32 v153, v50
	v_exp_f32_e32 v154, v51
	ds_read_b128 v[48:51], v140 offset:8192
	ds_read_b128 v[64:67], v140 offset:12288
	v_exp_f32_e32 v155, v52
	s_waitcnt lgkmcnt(4)
	v_mfma_f32_32x32x16_bf16 v[0:15], v[68:71], v[80:83], v[0:15]
	v_exp_f32_e32 v156, v53
	v_exp_f32_e32 v159, v54
	v_exp_f32_e32 v160, v55
	v_exp_f32_e32 v162, v57
	s_waitcnt lgkmcnt(3)
	v_mfma_f32_32x32x16_bf16 v[16:31], v[72:75], v[84:87], v[16:31]
	ds_read_b128 v[68:71], v139 offset:8192
	ds_read_b128 v[80:83], v139 offset:12288
	v_add_f32_e32 v157, v155, v151
	v_add_f32_e32 v158, v156, v152
	ds_read_b128 v[52:55], v164
	ds_read_b128 v[72:75], v164 offset:4096
	v_add_f32_e32 v161, v159, v153
	s_waitcnt lgkmcnt(6)
	v_mfma_f32_32x32x16_bf16 v[0:15], v[76:79], v[84:87], v[0:15]
	v_exp_f32_e32 v77, v56
	v_add_f32_e32 v76, v160, v154
	v_exp_f32_e32 v62, v62
	ds_read_b128 v[112:115], v165
	ds_read_b128 v[116:119], v165 offset:4096
	v_cvt_pk_bf16_f32 v56, v151, v152
	s_waitcnt lgkmcnt(7)
	v_mfma_f32_32x32x16_bf16 v[16:31], v[48:51], v[88:91], v[16:31]
	v_exp_f32_e32 v49, v58
	v_exp_f32_e32 v50, v59
	v_add_f32_e32 v48, v77, v157
	v_add_f32_e32 v51, v162, v158
	v_add_f32_e32 v78, v49, v161
	v_add_f32_e32 v76, v50, v76
	s_waitcnt lgkmcnt(6)
	v_mfma_f32_32x32x16_bf16 v[0:15], v[64:67], v[88:91], v[0:15]
	v_exp_f32_e32 v60, v60
	v_add_f32_e32 v151, v62, v78
	v_exp_f32_e32 v61, v61
	v_exp_f32_e32 v63, v63
	v_cvt_pk_bf16_f32 v59, v159, v160
	v_exp_f32_e32 v160, v33
	s_waitcnt lgkmcnt(5)
	v_mfma_f32_32x32x16_bf16 v[16:31], v[68:71], v[92:95], v[16:31]
	v_cvt_pk_bf16_f32 v57, v153, v154
	v_cvt_pk_bf16_f32 v58, v155, v156
	v_add_f32_e32 v48, v60, v48
	v_add_f32_e32 v51, v61, v51
	v_cvt_pk_bf16_f32 v49, v49, v50
	s_waitcnt lgkmcnt(4)
	v_mfma_f32_32x32x16_bf16 v[0:15], v[80:83], v[92:95], v[0:15]
	v_readfirstlane_b32 s18, v171
	s_add_u32 m0, s18, 0x1e000
	s_nop 0
	global_load_lds_dwordx4 v169, s[10:11]
	v_exp_f32_e32 v95, v32
	v_add_f32_e32 v32, v63, v76
	v_add_f32_e32 v163, v160, v51
	v_add_f32_e32 v161, v95, v48
	v_cvt_pk_bf16_f32 v48, v77, v162
	v_cvt_pk_bf16_f32 v51, v62, v63
	s_waitcnt lgkmcnt(3)
	v_mfma_f32_32x32x16_bf16 v[78:93], v[52:55], v[96:99], 0
	v_cvt_pk_bf16_f32 v50, v60, v61
	v_exp_f32_e32 v60, v34
	v_exp_f32_e32 v61, v35
	v_exp_f32_e32 v36, v36
	v_exp_f32_e32 v37, v37
	v_exp_f32_e32 v38, v38
	v_exp_f32_e32 v39, v39
	s_waitcnt lgkmcnt(2)
	v_mfma_f32_32x32x16_bf16 v[62:77], v[72:75], v[96:99], 0
	ds_read_b128 v[52:55], v166
	ds_read_b128 v[152:155], v166 offset:4096
	v_add_f32_e32 v151, v60, v151
	v_add_f32_e32 v162, v61, v32
	s_waitcnt lgkmcnt(3)
	v_mfma_f32_32x32x16_bf16 v[78:93], v[112:115], v[100:103], v[78:93]
	v_add_f32_e32 v112, v36, v161
	v_add_f32_e32 v113, v37, v163
	v_add_f32_e32 v114, v38, v151
	v_exp_f32_e32 v115, v40
	v_add_f32_e32 v40, v39, v162
	ds_read_b128 v[32:35], v167
	ds_read_b128 v[156:159], v167 offset:4096
	s_waitcnt lgkmcnt(4)
	v_mfma_f32_32x32x16_bf16 v[62:77], v[116:119], v[100:103], v[62:77]
	v_exp_f32_e32 v116, v41
	v_add_f32_e32 v41, v115, v112
	s_min_u32 s9, s3, s2
	s_lshl_b32 s9, s9, 6
	v_add_f32_e32 v112, v116, v113
	s_waitcnt lgkmcnt(3)
	v_mfma_f32_32x32x16_bf16 v[78:93], v[52:55], v[104:107], v[78:93]
	v_cvt_pk_bf16_f32 v54, v36, v37
	v_exp_f32_e32 v37, v42
	v_cvt_pk_bf16_f32 v55, v38, v39
	v_exp_f32_e32 v38, v43
	v_exp_f32_e32 v39, v44
	v_exp_f32_e32 v44, v45
	v_exp_f32_e32 v45, v46
	v_exp_f32_e32 v46, v47
	v_cvt_pk_bf16_f32 v52, v95, v160
	v_cvt_pk_bf16_f32 v53, v60, v61
	v_add_f32_e32 v36, v37, v114
	v_add_f32_e32 v43, v38, v40
	v_add_f32_e32 v40, v39, v41
	v_add_f32_e32 v42, v44, v112
	v_add_f32_e32 v41, v45, v36
	v_add_f32_e32 v43, v46, v43
	v_cvt_pk_bf16_f32 v36, v115, v116
	v_cvt_pk_bf16_f32 v37, v37, v38
	v_cvt_pk_bf16_f32 v38, v39, v44
	v_cvt_pk_bf16_f32 v39, v45, v46
	s_waitcnt lgkmcnt(1)
	v_mfma_f32_32x32x16_bf16 v[78:93], v[32:35], v[108:111], v[78:93]
	s_waitcnt lgkmcnt(0)
	s_barrier
	v_mad_u64_u32 v[32:33], s[18:19], s9, v237, v[132:133]
	global_load_dwordx4 v[112:115], v[32:33], off offset:2048
	global_load_dwordx4 v[116:119], v[136:137], off
	v_add_f32_e64 v32, v40, v42
	v_add_f32_e64 v33, v41, v43
	s_waitcnt vmcnt(4)
	ds_write_b128 v142, v[120:123]
	s_waitcnt vmcnt(3)
	ds_write_b128 v142, v[124:127] offset:8192
	v_mfma_f32_32x32x16_bf16 v[62:77], v[152:155], v[104:107], v[62:77]
	v_add_f32_e32 v32, v32, v33
	v_add_f32_e32 v150, v150, v32
	s_waitcnt lgkmcnt(2)
	v_mfma_f32_32x32x16_bf16 v[62:77], v[156:159], v[108:111], v[62:77]
	ds_read_b128 v[32:35], v144 offset:24576
	ds_read_b128 v[40:43], v144 offset:28672
	ds_read_b128 v[44:47], v141 offset:24576
	ds_read_b128 v[120:123], v141 offset:28672
	v_exp_f32_e32 v60, v78
	s_waitcnt lgkmcnt(3)
	v_mfma_f32_32x32x16_bf16 v[16:31], v[32:35], v[56:59], v[16:31]
	v_exp_f32_e32 v61, v79
	v_exp_f32_e32 v95, v80
	v_exp_f32_e32 v81, v81
	ds_read_b128 v[152:155], v140 offset:24576
	ds_read_b128 v[156:159], v140 offset:28672
	s_waitcnt lgkmcnt(4)
	v_mfma_f32_32x32x16_bf16 v[0:15], v[40:43], v[56:59], v[0:15]
	v_exp_f32_e32 v82, v82
	v_exp_f32_e32 v83, v83
	v_add_f32_e32 v78, v82, v60
	v_add_f32_e32 v79, v83, v61
	s_waitcnt lgkmcnt(2)
	v_mfma_f32_32x32x16_bf16 v[0:15], v[120:123], v[48:51], v[0:15]
	ds_read_b128 v[56:59], v139 offset:24576
	ds_read_b128 v[160:163], v139 offset:28672
	ds_read_b128 v[40:43], v164 offset:16384
	ds_read_b128 v[32:35], v164 offset:20480
	v_cvt_pk_bf16_f32 v82, v82, v83
	v_exp_f32_e32 v151, v62
	v_exp_f32_e32 v64, v64
	v_exp_f32_e32 v65, v65
	v_mfma_f32_32x32x16_bf16 v[16:31], v[44:47], v[48:51], v[16:31]
	v_exp_f32_e32 v44, v84
	v_exp_f32_e32 v45, v85
	v_exp_f32_e32 v84, v86
	v_exp_f32_e32 v85, v87
	v_add_f32_e32 v46, v44, v95
	v_add_f32_e32 v47, v45, v81
	v_add_f32_e32 v48, v84, v78
	s_waitcnt lgkmcnt(4)
	v_mfma_f32_32x32x16_bf16 v[0:15], v[156:159], v[52:55], v[0:15]
	v_add_f32_e32 v49, v85, v79
	v_exp_f32_e32 v78, v88
	v_exp_f32_e32 v79, v89
	v_exp_f32_e32 v87, v92
	v_cvt_pk_bf16_f32 v83, v44, v45
	v_exp_f32_e32 v44, v90
	v_mfma_f32_32x32x16_bf16 v[16:31], v[152:155], v[52:55], v[16:31]
	v_exp_f32_e32 v45, v91
	v_exp_f32_e32 v92, v93
	v_add_f32_e32 v46, v78, v46
	v_add_f32_e32 v47, v79, v47
	ds_read_b128 v[124:127], v165 offset:16384
	ds_read_b128 v[120:123], v165 offset:20480
	s_waitcnt lgkmcnt(4)
	v_mfma_f32_32x32x16_bf16 v[0:15], v[160:163], v[36:39], v[0:15]
	v_exp_f32_e32 v160, v63
	v_cvt_pk_bf16_f32 v80, v60, v61
	v_cvt_pk_bf16_f32 v81, v95, v81
	v_add_f32_e32 v48, v44, v48
	v_add_f32_e32 v49, v45, v49
	v_add_f32_e32 v46, v87, v46
	v_add_f32_e32 v47, v92, v47
	v_mfma_f32_32x32x16_bf16 v[16:31], v[56:59], v[36:39], v[16:31]
	v_add_f32_e32 v161, v151, v48
	v_add_f32_e32 v162, v160, v49
	v_cvt_pk_bf16_f32 v84, v84, v85
	v_cvt_pk_bf16_f32 v85, v78, v79
	v_cvt_pk_bf16_f32 v86, v44, v45
	v_add_f32_e32 v78, v64, v46
	v_add_f32_e32 v79, v65, v47
	s_waitcnt lgkmcnt(3)
	v_mfma_f32_32x32x16_bf16 v[48:63], v[40:43], v[96:99], 0
	ds_read_b128 v[88:91], v166 offset:16384
	ds_read_b128 v[152:155], v166 offset:20480
	v_exp_f32_e32 v66, v66
	v_exp_f32_e32 v67, v67
	v_exp_f32_e32 v68, v68
	v_exp_f32_e32 v69, v69
	v_cvt_pk_bf16_f32 v87, v87, v92
	s_waitcnt lgkmcnt(4)
	v_mfma_f32_32x32x16_bf16 v[32:47], v[32:35], v[96:99], 0
	ds_read_b128 v[156:159], v167 offset:16384
	ds_read_b128 v[92:95], v167 offset:20480
	v_add_f32_e32 v161, v66, v161
	v_add_f32_e32 v162, v67, v162
	v_add_f32_e32 v78, v68, v78
	v_add_f32_e32 v79, v69, v79
	s_waitcnt lgkmcnt(5)
	v_mfma_f32_32x32x16_bf16 v[48:63], v[124:127], v[100:103], v[48:63]
	v_exp_f32_e32 v70, v70
	v_exp_f32_e32 v71, v71
	s_add_i32 s9, s3, 2
	s_add_i32 s3, s3, -2
	v_lshl_add_u64 v[136:137], v[136:137], 0, s[22:23]
	s_waitcnt lgkmcnt(4)
	v_mfma_f32_32x32x16_bf16 v[32:47], v[120:123], v[100:103], v[32:47]
	v_add_f32_e32 v120, v70, v161
	v_add_f32_e32 v121, v71, v162
	s_cmp_lt_u32 s3, s2
	s_mov_b32 s3, s9
	s_waitcnt lgkmcnt(3)
	v_mfma_f32_32x32x16_bf16 v[48:63], v[88:91], v[104:107], v[48:63]
	v_cvt_pk_bf16_f32 v91, v68, v69
	v_exp_f32_e32 v68, v72
	v_exp_f32_e32 v69, v73
	v_exp_f32_e32 v72, v74
	v_exp_f32_e32 v73, v75
	v_exp_f32_e32 v74, v76
	v_exp_f32_e32 v75, v77
	s_waitcnt lgkmcnt(2)
	v_mfma_f32_32x32x16_bf16 v[32:47], v[152:155], v[104:107], v[32:47]
	v_cvt_pk_bf16_f32 v88, v151, v160
	v_cvt_pk_bf16_f32 v89, v64, v65
	v_cvt_pk_bf16_f32 v90, v66, v67
	v_add_f32_e32 v65, v68, v78
	v_add_f32_e32 v67, v69, v79
	s_waitcnt lgkmcnt(1)
	v_mfma_f32_32x32x16_bf16 v[48:63], v[156:159], v[108:111], v[48:63]
	v_add_f32_e32 v64, v72, v120
	v_add_f32_e32 v66, v73, v121
	v_add_f32_e32 v65, v74, v65
	v_add_f32_e32 v67, v75, v67
	s_waitcnt lgkmcnt(0)
	v_mfma_f32_32x32x16_bf16 v[32:47], v[92:95], v[108:111], v[32:47]
	v_cvt_pk_bf16_f32 v92, v70, v71
	v_cvt_pk_bf16_f32 v93, v68, v69
	v_cvt_pk_bf16_f32 v94, v72, v73
	v_cvt_pk_bf16_f32 v95, v74, v75
	v_add_f32_e64 v64, v64, v66
	v_add_f32_e64 v65, v65, v67
	s_waitcnt lgkmcnt(0)
	s_barrier
	v_add_f32_e32 v64, v64, v65
	v_add_f32_e32 v150, v150, v64
.LBB0_898:
	s_add_i32 s9, s3, -1
	s_min_u32 s9, s9, s2
	s_lshl_b32 s9, s9, 6
	s_waitcnt vmcnt(1)
	ds_write_b128 v142, v[112:115] offset:16384
	s_waitcnt vmcnt(0)
	ds_write_b128 v142, v[116:119] offset:24576
	v_mad_u64_u32 v[64:65], s[18:19], s9, v237, v[132:133]
	global_load_dwordx4 v[120:123], v[64:65], off offset:2048
	global_load_dwordx4 v[124:127], v[136:137], off offset:-128
	ds_read_b128 v[64:67], v144 offset:8192
	ds_read_b128 v[68:71], v144 offset:12288
	ds_read_b128 v[72:75], v141 offset:8192
	ds_read_b128 v[76:79], v141 offset:12288
	v_exp_f32_e32 v151, v48
	v_exp_f32_e32 v152, v49
	s_waitcnt lgkmcnt(3)
	v_mfma_f32_32x32x16_bf16 v[16:31], v[64:67], v[80:83], v[16:31]
	v_exp_f32_e32 v153, v50
	v_exp_f32_e32 v154, v51
	ds_read_b128 v[48:51], v140 offset:8192
	ds_read_b128 v[64:67], v140 offset:12288
	v_exp_f32_e32 v155, v52
	s_waitcnt lgkmcnt(4)
	v_mfma_f32_32x32x16_bf16 v[0:15], v[68:71], v[80:83], v[0:15]
	v_exp_f32_e32 v156, v53
	v_exp_f32_e32 v159, v54
	v_exp_f32_e32 v160, v55
	v_exp_f32_e32 v162, v57
	s_waitcnt lgkmcnt(3)
	v_mfma_f32_32x32x16_bf16 v[16:31], v[72:75], v[84:87], v[16:31]
	ds_read_b128 v[68:71], v139 offset:8192
	ds_read_b128 v[80:83], v139 offset:12288
	v_add_f32_e32 v157, v155, v151
	v_add_f32_e32 v158, v156, v152
	ds_read_b128 v[52:55], v164
	ds_read_b128 v[72:75], v164 offset:4096
	v_add_f32_e32 v161, v159, v153
	s_waitcnt lgkmcnt(6)
	v_mfma_f32_32x32x16_bf16 v[0:15], v[76:79], v[84:87], v[0:15]
	v_exp_f32_e32 v77, v56
	v_add_f32_e32 v76, v160, v154
	v_exp_f32_e32 v62, v62
	ds_read_b128 v[112:115], v165
	ds_read_b128 v[116:119], v165 offset:4096
	v_cvt_pk_bf16_f32 v56, v151, v152
	s_waitcnt lgkmcnt(7)
	v_mfma_f32_32x32x16_bf16 v[16:31], v[48:51], v[88:91], v[16:31]
	v_exp_f32_e32 v49, v58
	v_exp_f32_e32 v50, v59
	v_add_f32_e32 v48, v77, v157
	v_add_f32_e32 v51, v162, v158
	v_add_f32_e32 v78, v49, v161
	v_add_f32_e32 v76, v50, v76
	s_waitcnt lgkmcnt(6)
	v_mfma_f32_32x32x16_bf16 v[0:15], v[64:67], v[88:91], v[0:15]
	v_exp_f32_e32 v60, v60
	v_add_f32_e32 v151, v62, v78
	v_exp_f32_e32 v61, v61
	v_exp_f32_e32 v63, v63
	v_cvt_pk_bf16_f32 v59, v159, v160
	v_exp_f32_e32 v160, v33
	s_waitcnt lgkmcnt(5)
	v_mfma_f32_32x32x16_bf16 v[16:31], v[68:71], v[92:95], v[16:31]
	v_cvt_pk_bf16_f32 v57, v153, v154
	v_cvt_pk_bf16_f32 v58, v155, v156
	v_add_f32_e32 v48, v60, v48
	v_add_f32_e32 v51, v61, v51
	v_cvt_pk_bf16_f32 v49, v49, v50
	s_waitcnt lgkmcnt(4)
	v_mfma_f32_32x32x16_bf16 v[0:15], v[80:83], v[92:95], v[0:15]
	v_exp_f32_e32 v95, v32
	v_add_f32_e32 v32, v63, v76
	v_add_f32_e32 v163, v160, v51
	v_add_f32_e32 v161, v95, v48
	v_cvt_pk_bf16_f32 v48, v77, v162
	v_cvt_pk_bf16_f32 v51, v62, v63
	s_waitcnt lgkmcnt(3)
	v_mfma_f32_32x32x16_bf16 v[78:93], v[52:55], v[96:99], 0
	v_cvt_pk_bf16_f32 v50, v60, v61
	v_exp_f32_e32 v60, v34
	v_exp_f32_e32 v61, v35
	v_exp_f32_e32 v36, v36
	v_exp_f32_e32 v37, v37
	v_exp_f32_e32 v38, v38
	v_exp_f32_e32 v39, v39
	s_waitcnt lgkmcnt(2)
	v_mfma_f32_32x32x16_bf16 v[62:77], v[72:75], v[96:99], 0
	ds_read_b128 v[52:55], v166
	ds_read_b128 v[152:155], v166 offset:4096
	v_add_f32_e32 v151, v60, v151
	v_add_f32_e32 v162, v61, v32
	s_waitcnt lgkmcnt(3)
	v_mfma_f32_32x32x16_bf16 v[78:93], v[112:115], v[100:103], v[78:93]
	v_add_f32_e32 v112, v36, v161
	v_add_f32_e32 v113, v37, v163
	v_add_f32_e32 v114, v38, v151
	v_exp_f32_e32 v115, v40
	v_add_f32_e32 v40, v39, v162
	ds_read_b128 v[32:35], v167
	ds_read_b128 v[156:159], v167 offset:4096
	s_waitcnt lgkmcnt(4)
	v_mfma_f32_32x32x16_bf16 v[62:77], v[116:119], v[100:103], v[62:77]
	v_exp_f32_e32 v116, v41
	v_add_f32_e32 v41, v115, v112
	s_min_u32 s9, s3, s2
	s_lshl_b32 s9, s9, 6
	v_add_f32_e32 v112, v116, v113
	s_waitcnt lgkmcnt(3)
	v_mfma_f32_32x32x16_bf16 v[78:93], v[52:55], v[104:107], v[78:93]
	v_cvt_pk_bf16_f32 v54, v36, v37
	v_exp_f32_e32 v37, v42
	v_cvt_pk_bf16_f32 v55, v38, v39
	v_exp_f32_e32 v38, v43
	v_exp_f32_e32 v39, v44
	v_exp_f32_e32 v44, v45
	v_exp_f32_e32 v45, v46
	v_exp_f32_e32 v46, v47
	v_cvt_pk_bf16_f32 v52, v95, v160
	v_cvt_pk_bf16_f32 v53, v60, v61
	v_add_f32_e32 v36, v37, v114
	v_add_f32_e32 v43, v38, v40
	v_add_f32_e32 v40, v39, v41
	v_add_f32_e32 v42, v44, v112
	v_add_f32_e32 v41, v45, v36
	v_add_f32_e32 v43, v46, v43
	v_cvt_pk_bf16_f32 v36, v115, v116
	v_cvt_pk_bf16_f32 v37, v37, v38
	v_cvt_pk_bf16_f32 v38, v39, v44
	v_cvt_pk_bf16_f32 v39, v45, v46
	s_waitcnt lgkmcnt(1)
	v_mfma_f32_32x32x16_bf16 v[78:93], v[32:35], v[108:111], v[78:93]
	s_waitcnt lgkmcnt(0)
	s_barrier
	v_mad_u64_u32 v[32:33], s[18:19], s9, v237, v[132:133]
	global_load_dwordx4 v[112:115], v[32:33], off offset:2048
	global_load_dwordx4 v[116:119], v[136:137], off
	v_add_f32_e64 v32, v40, v42
	v_add_f32_e64 v33, v41, v43
	s_waitcnt vmcnt(3)
	ds_write_b128 v142, v[120:123]
	s_waitcnt vmcnt(2)
	ds_write_b128 v142, v[124:127] offset:8192
	v_mfma_f32_32x32x16_bf16 v[62:77], v[152:155], v[104:107], v[62:77]
	v_add_f32_e32 v32, v32, v33
	v_add_f32_e32 v150, v150, v32
	s_waitcnt lgkmcnt(2)
	v_mfma_f32_32x32x16_bf16 v[62:77], v[156:159], v[108:111], v[62:77]
	ds_read_b128 v[32:35], v144 offset:24576
	ds_read_b128 v[40:43], v144 offset:28672
	ds_read_b128 v[44:47], v141 offset:24576
	ds_read_b128 v[120:123], v141 offset:28672
	v_exp_f32_e32 v60, v78
	s_waitcnt lgkmcnt(3)
	v_mfma_f32_32x32x16_bf16 v[16:31], v[32:35], v[56:59], v[16:31]
	v_exp_f32_e32 v61, v79
	v_exp_f32_e32 v95, v80
	v_exp_f32_e32 v81, v81
	ds_read_b128 v[152:155], v140 offset:24576
	ds_read_b128 v[156:159], v140 offset:28672
	s_waitcnt lgkmcnt(4)
	v_mfma_f32_32x32x16_bf16 v[0:15], v[40:43], v[56:59], v[0:15]
	v_exp_f32_e32 v82, v82
	v_exp_f32_e32 v83, v83
	v_add_f32_e32 v78, v82, v60
	v_add_f32_e32 v79, v83, v61
	s_waitcnt lgkmcnt(2)
	v_mfma_f32_32x32x16_bf16 v[0:15], v[120:123], v[48:51], v[0:15]
	ds_read_b128 v[56:59], v139 offset:24576
	ds_read_b128 v[160:163], v139 offset:28672
	ds_read_b128 v[40:43], v164 offset:16384
	ds_read_b128 v[32:35], v164 offset:20480
	v_cvt_pk_bf16_f32 v82, v82, v83
	v_exp_f32_e32 v151, v62
	v_exp_f32_e32 v64, v64
	v_exp_f32_e32 v65, v65
	v_mfma_f32_32x32x16_bf16 v[16:31], v[44:47], v[48:51], v[16:31]
	v_exp_f32_e32 v44, v84
	v_exp_f32_e32 v45, v85
	v_exp_f32_e32 v84, v86
	v_exp_f32_e32 v85, v87
	v_add_f32_e32 v46, v44, v95
	v_add_f32_e32 v47, v45, v81
	v_add_f32_e32 v48, v84, v78
	s_waitcnt lgkmcnt(4)
	v_mfma_f32_32x32x16_bf16 v[0:15], v[156:159], v[52:55], v[0:15]
	v_add_f32_e32 v49, v85, v79
	v_exp_f32_e32 v78, v88
	v_exp_f32_e32 v79, v89
	v_exp_f32_e32 v87, v92
	v_cvt_pk_bf16_f32 v83, v44, v45
	v_exp_f32_e32 v44, v90
	v_mfma_f32_32x32x16_bf16 v[16:31], v[152:155], v[52:55], v[16:31]
	v_exp_f32_e32 v45, v91
	v_exp_f32_e32 v92, v93
	v_add_f32_e32 v46, v78, v46
	v_add_f32_e32 v47, v79, v47
	ds_read_b128 v[124:127], v165 offset:16384
	ds_read_b128 v[120:123], v165 offset:20480
	s_waitcnt lgkmcnt(4)
	v_mfma_f32_32x32x16_bf16 v[0:15], v[160:163], v[36:39], v[0:15]
	v_exp_f32_e32 v160, v63
	v_cvt_pk_bf16_f32 v80, v60, v61
	v_cvt_pk_bf16_f32 v81, v95, v81
	v_add_f32_e32 v48, v44, v48
	v_add_f32_e32 v49, v45, v49
	v_add_f32_e32 v46, v87, v46
	v_add_f32_e32 v47, v92, v47
	v_mfma_f32_32x32x16_bf16 v[16:31], v[56:59], v[36:39], v[16:31]
	v_add_f32_e32 v161, v151, v48
	v_add_f32_e32 v162, v160, v49
	v_cvt_pk_bf16_f32 v84, v84, v85
	v_cvt_pk_bf16_f32 v85, v78, v79
	v_cvt_pk_bf16_f32 v86, v44, v45
	v_add_f32_e32 v78, v64, v46
	v_add_f32_e32 v79, v65, v47
	s_waitcnt lgkmcnt(3)
	v_mfma_f32_32x32x16_bf16 v[48:63], v[40:43], v[96:99], 0
	ds_read_b128 v[88:91], v166 offset:16384
	ds_read_b128 v[152:155], v166 offset:20480
	v_exp_f32_e32 v66, v66
	v_exp_f32_e32 v67, v67
	v_exp_f32_e32 v68, v68
	v_exp_f32_e32 v69, v69
	v_cvt_pk_bf16_f32 v87, v87, v92
	s_waitcnt lgkmcnt(4)
	v_mfma_f32_32x32x16_bf16 v[32:47], v[32:35], v[96:99], 0
	ds_read_b128 v[156:159], v167 offset:16384
	ds_read_b128 v[92:95], v167 offset:20480
	v_add_f32_e32 v161, v66, v161
	v_add_f32_e32 v162, v67, v162
	v_add_f32_e32 v78, v68, v78
	v_add_f32_e32 v79, v69, v79
	s_waitcnt lgkmcnt(5)
	v_mfma_f32_32x32x16_bf16 v[48:63], v[124:127], v[100:103], v[48:63]
	v_exp_f32_e32 v70, v70
	v_exp_f32_e32 v71, v71
	s_add_i32 s9, s3, 2
	s_add_i32 s3, s3, -2
	v_lshl_add_u64 v[136:137], v[136:137], 0, s[22:23]
	s_waitcnt lgkmcnt(4)
	v_mfma_f32_32x32x16_bf16 v[32:47], v[120:123], v[100:103], v[32:47]
	v_add_f32_e32 v120, v70, v161
	v_add_f32_e32 v121, v71, v162
	s_cmp_lt_u32 s3, s2
	s_mov_b32 s3, s9
	s_waitcnt lgkmcnt(3)
	v_mfma_f32_32x32x16_bf16 v[48:63], v[88:91], v[104:107], v[48:63]
	v_cvt_pk_bf16_f32 v91, v68, v69
	v_exp_f32_e32 v68, v72
	v_exp_f32_e32 v69, v73
	v_exp_f32_e32 v72, v74
	v_exp_f32_e32 v73, v75
	v_exp_f32_e32 v74, v76
	v_exp_f32_e32 v75, v77
	s_waitcnt lgkmcnt(2)
	v_mfma_f32_32x32x16_bf16 v[32:47], v[152:155], v[104:107], v[32:47]
	v_cvt_pk_bf16_f32 v88, v151, v160
	v_cvt_pk_bf16_f32 v89, v64, v65
	v_cvt_pk_bf16_f32 v90, v66, v67
	v_add_f32_e32 v65, v68, v78
	v_add_f32_e32 v67, v69, v79
	s_waitcnt lgkmcnt(1)
	v_mfma_f32_32x32x16_bf16 v[48:63], v[156:159], v[108:111], v[48:63]
	v_add_f32_e32 v64, v72, v120
	v_add_f32_e32 v66, v73, v121
	v_add_f32_e32 v65, v74, v65
	v_add_f32_e32 v67, v75, v67
	s_waitcnt lgkmcnt(0)
	v_mfma_f32_32x32x16_bf16 v[32:47], v[92:95], v[108:111], v[32:47]
	v_cvt_pk_bf16_f32 v92, v70, v71
	v_cvt_pk_bf16_f32 v93, v68, v69
	v_cvt_pk_bf16_f32 v94, v72, v73
	v_cvt_pk_bf16_f32 v95, v74, v75
	v_add_f32_e64 v64, v64, v66
	v_add_f32_e64 v65, v65, v67
	s_waitcnt lgkmcnt(0)
	s_barrier
	v_add_f32_e32 v64, v64, v65
	v_add_f32_e32 v150, v150, v64
	s_cbranch_scc1 .LBB0_898
	v_ashrrev_i32_e32 v64, 1, v129
	v_and_or_b32 v132, v64, s88, v148
	v_lshlrev_b32_e32 v176, 4, v138
	s_waitcnt vmcnt(1)
	ds_write_b128 v142, v[112:115] offset:16384
	s_waitcnt vmcnt(0)
	ds_write_b128 v142, v[116:119] offset:24576
	ds_read_b128 v[124:127], v172 offset:32768
	ds_read_b128 v[120:123], v172 offset:40960
	ds_read_b128 v[116:119], v172 offset:49152
	ds_read_b128 v[112:115], v172 offset:57344
	v_ashrrev_i32_e32 v133, 31, v132
	ds_read_b128 v[128:131], v144 offset:8192
	ds_read_b128 v[134:137], v144 offset:12288
	ds_read_b128 v[146:149], v141 offset:8192
	ds_read_b128 v[152:155], v141 offset:12288
	v_exp_f32_e32 v138, v48
	v_exp_f32_e32 v142, v49
	s_waitcnt lgkmcnt(3)
	v_mfma_f32_32x32x16_bf16 v[16:31], v[128:131], v[80:83], v[16:31]
	v_exp_f32_e32 v151, v50
	v_add_f32_e32 v143, 0, v138
	v_add_f32_e32 v145, 0, v142
	v_exp_f32_e32 v156, v51
	ds_read_b128 v[48:51], v140 offset:8192
	ds_read_b128 v[128:131], v140 offset:12288
	v_exp_f32_e32 v52, v52
	s_waitcnt lgkmcnt(4)
	v_mfma_f32_32x32x16_bf16 v[0:15], v[134:137], v[80:83], v[0:15]
	v_exp_f32_e32 v53, v53
	v_exp_f32_e32 v54, v54
	v_exp_f32_e32 v55, v55
	v_add_f32_e32 v157, 0, v151
	v_add_f32_e32 v158, 0, v156
	v_add_f32_e32 v143, v52, v143
	s_waitcnt lgkmcnt(3)
	v_mfma_f32_32x32x16_bf16 v[16:31], v[146:149], v[84:87], v[16:31]
	v_add_f32_e32 v145, v53, v145
	v_add_f32_e32 v146, v54, v157
	ds_read_b128 v[80:83], v139 offset:8192
	ds_read_b128 v[134:137], v139 offset:12288
	v_exp_f32_e32 v56, v56
	v_exp_f32_e32 v57, v57
	v_exp_f32_e32 v58, v58
	s_waitcnt lgkmcnt(4)
	v_mfma_f32_32x32x16_bf16 v[0:15], v[152:155], v[84:87], v[0:15]
	v_add_f32_e32 v84, v55, v158
	v_exp_f32_e32 v59, v59
	v_exp_f32_e32 v60, v60
	v_exp_f32_e32 v32, v32
	v_exp_f32_e32 v33, v33
	v_exp_f32_e32 v34, v34
	s_waitcnt lgkmcnt(3)
	v_mfma_f32_32x32x16_bf16 v[16:31], v[48:51], v[88:91], v[16:31]
	v_cvt_pk_bf16_f32 v51, v54, v55
	v_exp_f32_e32 v54, v61
	v_exp_f32_e32 v55, v62
	v_exp_f32_e32 v61, v63
	v_exp_f32_e32 v35, v35
	v_add_f32_e32 v85, v56, v143
	v_add_f32_e32 v86, v57, v145
	v_add_f32_e32 v87, v58, v146
	v_add_f32_e32 v84, v59, v84
	v_cvt_pk_bf16_f32 v48, v138, v142
	v_cvt_pk_bf16_f32 v49, v151, v156
	v_cvt_pk_bf16_f32 v50, v52, v53
	v_add_f32_e32 v52, v60, v85
	v_add_f32_e32 v53, v54, v86
	v_add_f32_e32 v62, v55, v87
	v_add_f32_e32 v63, v61, v84
	v_exp_f32_e32 v36, v36
	v_exp_f32_e32 v37, v37
	v_exp_f32_e32 v38, v38
	v_exp_f32_e32 v39, v39
	s_waitcnt lgkmcnt(1)
	v_mfma_f32_32x32x16_bf16 v[16:31], v[80:83], v[92:95], v[16:31]
	v_add_f32_e32 v80, v32, v52
	v_add_f32_e32 v81, v33, v53
	v_cvt_pk_bf16_f32 v52, v56, v57
	v_cvt_pk_bf16_f32 v53, v58, v59
	v_cvt_pk_bf16_f32 v54, v60, v54
	v_cvt_pk_bf16_f32 v55, v55, v61
	v_add_f32_e32 v56, v34, v62
	v_add_f32_e32 v57, v35, v63
	v_exp_f32_e32 v40, v40
	v_add_f32_e32 v58, v36, v80
	v_add_f32_e32 v59, v37, v81
	v_add_f32_e32 v56, v38, v56
	v_exp_f32_e32 v41, v41
	v_add_f32_e32 v57, v39, v57
	v_mfma_f32_32x32x16_bf16 v[0:15], v[128:131], v[88:91], v[0:15]
	v_cvt_pk_bf16_f32 v32, v32, v33
	v_cvt_pk_bf16_f32 v33, v34, v35
	v_cvt_pk_bf16_f32 v34, v36, v37
	v_exp_f32_e32 v37, v42
	v_cvt_pk_bf16_f32 v35, v38, v39
	v_exp_f32_e32 v38, v43
	v_exp_f32_e32 v39, v44
	v_exp_f32_e32 v43, v45
	v_exp_f32_e32 v44, v46
	v_exp_f32_e32 v45, v47
	v_add_f32_e32 v58, v40, v58
	v_add_f32_e32 v59, v41, v59
	v_add_f32_e32 v36, v37, v56
	v_add_f32_e32 v42, v38, v57
	v_add_f32_e32 v56, v39, v58
	v_add_f32_e32 v58, v43, v59
	s_waitcnt lgkmcnt(0)
	v_mfma_f32_32x32x16_bf16 v[0:15], v[134:137], v[92:95], v[0:15]
	v_add_f32_e32 v57, v44, v36
	v_add_f32_e32 v59, v45, v42
	v_cvt_pk_bf16_f32 v36, v40, v41
	v_cvt_pk_bf16_f32 v37, v37, v38
	v_cvt_pk_bf16_f32 v38, v39, v43
	v_cvt_pk_bf16_f32 v39, v44, v45
	s_waitcnt lgkmcnt(0)
	s_barrier
	ds_read_b128 v[40:43], v144 offset:24576
	ds_read_b128 v[44:47], v144 offset:28672
	s_waitcnt lgkmcnt(1)
	v_mfma_f32_32x32x16_bf16 v[16:31], v[40:43], v[48:51], v[16:31]
	s_waitcnt lgkmcnt(0)
	v_mfma_f32_32x32x16_bf16 v[0:15], v[44:47], v[48:51], v[0:15]
	ds_read_b128 v[40:43], v141 offset:24576
	ds_read_b128 v[44:47], v141 offset:28672
	s_waitcnt lgkmcnt(1)
	v_mfma_f32_32x32x16_bf16 v[16:31], v[40:43], v[52:55], v[16:31]
	s_waitcnt lgkmcnt(0)
	v_mfma_f32_32x32x16_bf16 v[0:15], v[44:47], v[52:55], v[0:15]
	ds_read_b128 v[40:43], v140 offset:24576
	ds_read_b128 v[44:47], v140 offset:28672
	s_waitcnt lgkmcnt(1)
	v_mfma_f32_32x32x16_bf16 v[16:31], v[40:43], v[32:35], v[16:31]
	s_waitcnt lgkmcnt(0)
	v_mfma_f32_32x32x16_bf16 v[0:15], v[44:47], v[32:35], v[0:15]
	ds_read_b128 v[32:35], v139 offset:24576
	ds_read_b128 v[40:43], v139 offset:28672
	s_waitcnt lgkmcnt(1)
	v_mfma_f32_32x32x16_bf16 v[16:31], v[32:35], v[36:39], v[16:31]
	v_add_f32_e64 v32, v56, v58
	v_add_f32_e64 v33, v57, v59
	v_add_f32_e32 v32, v32, v33
	v_add_f32_e32 v32, v150, v32
	v_mov_b32_e32 v33, v32
	s_nop 1
	v_permlane32_swap_b32_e32 v32, v33
	v_add_f32_e32 v32, v32, v33
	v_div_scale_f32 v33, s[2:3], v32, v32, 1.0
	v_rcp_f32_e32 v34, v33
	s_waitcnt lgkmcnt(0)
	v_mfma_f32_32x32x16_bf16 v[0:15], v[40:43], v[36:39], v[0:15]
	s_waitcnt vmcnt(11)
	v_mov_b32_e32 v40, v127
	s_nop 1
	v_permlane32_swap_b32_e32 v125, v40
	v_fma_f32 v35, -v33, v34, 1.0
	v_fmac_f32_e32 v34, v35, v34
	v_div_scale_f32 v35, vcc, 1.0, v32, 1.0
	v_mul_f32_e32 v36, v35, v34
	v_fma_f32 v37, -v33, v36, v35
	v_fmac_f32_e32 v36, v37, v34
	v_fma_f32 v33, -v33, v36, v35
	v_div_fmas_f32 v33, v33, v34, v36
	v_mov_b32_e32 v35, v126
	v_div_fixup_f32 v34, v33, v32, 1.0
	s_nop 0
	v_permlane32_swap_b32_e32 v124, v35
	v_lshlrev_b32_e32 v38, 16, v124
	v_and_b32_e32 v39, 0xffff0000, v124
	v_mul_f32_e32 v16, v16, v34
	v_mul_f32_e32 v17, v17, v34
	v_mul_f32_e32 v18, v18, v34
	v_mul_f32_e32 v19, v19, v34
	v_mul_f32_e32 v16, v16, v38
	v_mul_f32_e32 v17, v17, v39
	v_lshlrev_b32_e32 v38, 16, v125
	v_and_b32_e32 v39, 0xffff0000, v125
	v_mul_f32_e32 v18, v18, v38
	v_mul_f32_e32 v19, v19, v39
	v_cvt_pk_bf16_f32 v16, v16, v17
	v_cvt_pk_bf16_f32 v17, v18, v19
	v_lshlrev_b32_e32 v18, 16, v35
	v_and_b32_e32 v19, 0xffff0000, v35
	v_mul_f32_e32 v20, v20, v34
	v_mul_f32_e32 v21, v21, v34
	v_mul_f32_e32 v22, v22, v34
	v_mul_f32_e32 v23, v23, v34
	v_mul_f32_e32 v18, v20, v18
	v_mul_f32_e32 v19, v21, v19
	v_lshlrev_b32_e32 v20, 16, v40
	v_and_b32_e32 v21, 0xffff0000, v40
	v_lshlrev_b64 v[32:33], 11, v[132:133]
	v_mul_f32_e32 v20, v22, v20
	v_mul_f32_e32 v21, v23, v21
	v_lshl_add_u64 v[32:33], s[6:7], 0, v[32:33]
	v_cvt_pk_bf16_f32 v18, v18, v19
	v_cvt_pk_bf16_f32 v19, v20, v21
	s_waitcnt vmcnt(10)
	v_mov_b32_e32 v22, v122
	v_lshl_add_u64 v[36:37], v[32:33], 0, v[176:177]
	v_permlane32_swap_b32_e32 v16, v18
	v_permlane32_swap_b32_e32 v17, v19
	v_permlane32_swap_b32_e32 v120, v22
	v_mov_b32_e32 v23, v123
	global_store_dwordx4 v[36:37], v[16:19], off offset:512
	s_nop 0
	v_permlane32_swap_b32_e32 v121, v23
	v_lshlrev_b32_e32 v16, 16, v120
	v_and_b32_e32 v17, 0xffff0000, v120
	v_mul_f32_e32 v18, v24, v34
	v_mul_f32_e32 v19, v25, v34
	v_mul_f32_e32 v20, v26, v34
	v_mul_f32_e32 v21, v27, v34
	v_mul_f32_e32 v16, v18, v16
	v_mul_f32_e32 v17, v19, v17
	v_lshlrev_b32_e32 v18, 16, v121
	v_and_b32_e32 v19, 0xffff0000, v121
	v_mul_f32_e32 v18, v20, v18
	v_mul_f32_e32 v19, v21, v19
	v_cvt_pk_bf16_f32 v16, v16, v17
	v_cvt_pk_bf16_f32 v17, v18, v19
	v_lshlrev_b32_e32 v18, 16, v22
	v_and_b32_e32 v19, 0xffff0000, v22
	v_mul_f32_e32 v20, v28, v34
	v_mul_f32_e32 v21, v29, v34
	v_mul_f32_e32 v0, v0, v34
	v_mul_f32_e32 v1, v1, v34
	v_mul_f32_e32 v18, v20, v18
	v_mul_f32_e32 v19, v21, v19
	v_lshlrev_b32_e32 v20, 16, v23
	v_and_b32_e32 v21, 0xffff0000, v23
	v_mul_f32_e32 v22, v30, v34
	v_mul_f32_e32 v23, v31, v34
	v_cvt_pk_bf16_f32 v18, v18, v19
	v_mul_f32_e32 v20, v22, v20
	v_mul_f32_e32 v21, v23, v21
	s_nop 0
	v_permlane32_swap_b32_e32 v16, v18
	v_cvt_pk_bf16_f32 v19, v20, v21
	s_nop 1
	v_permlane32_swap_b32_e32 v17, v19
	global_store_dwordx4 v[36:37], v[16:19], off offset:544
	v_mul_f32_e32 v2, v2, v34
	v_mul_f32_e32 v3, v3, v34
	v_mul_f32_e32 v4, v4, v34
	v_mul_f32_e32 v5, v5, v34
	s_waitcnt vmcnt(11)
	v_mov_b32_e32 v18, v118
	s_nop 1
	v_permlane32_swap_b32_e32 v116, v18
	v_mov_b32_e32 v19, v119
	s_nop 1
	v_permlane32_swap_b32_e32 v117, v19
	v_lshlrev_b32_e32 v16, 16, v116
	v_and_b32_e32 v17, 0xffff0000, v116
	v_mul_f32_e32 v0, v0, v16
	v_mul_f32_e32 v1, v1, v17
	v_lshlrev_b32_e32 v16, 16, v117
	v_and_b32_e32 v17, 0xffff0000, v117
	v_mul_f32_e32 v2, v2, v16
	v_mul_f32_e32 v3, v3, v17
	v_cvt_pk_bf16_f32 v0, v0, v1
	v_cvt_pk_bf16_f32 v1, v2, v3
	v_lshlrev_b32_e32 v2, 16, v18
	v_and_b32_e32 v3, 0xffff0000, v18
	v_mul_f32_e32 v2, v4, v2
	v_mul_f32_e32 v3, v5, v3
	v_lshlrev_b32_e32 v4, 16, v19
	v_and_b32_e32 v5, 0xffff0000, v19
	v_mul_f32_e32 v6, v6, v34
	v_mul_f32_e32 v7, v7, v34
	v_cvt_pk_bf16_f32 v2, v2, v3
	v_mul_f32_e32 v4, v6, v4
	v_mul_f32_e32 v5, v7, v5
	s_waitcnt vmcnt(10)
	v_mov_b32_e32 v6, v114
	v_cvt_pk_bf16_f32 v3, v4, v5
	v_permlane32_swap_b32_e32 v0, v2
	s_nop 0
	v_permlane32_swap_b32_e32 v1, v3
	v_permlane32_swap_b32_e32 v112, v6
	v_mov_b32_e32 v7, v115
	global_store_dwordx4 v[36:37], v[0:3], off offset:576
	s_nop 0
	v_permlane32_swap_b32_e32 v113, v7
	v_lshlrev_b32_e32 v0, 16, v112
	v_and_b32_e32 v1, 0xffff0000, v112
	v_mul_f32_e32 v2, v8, v34
	v_mul_f32_e32 v3, v9, v34
	v_mul_f32_e32 v4, v10, v34
	v_mul_f32_e32 v5, v11, v34
	v_mul_f32_e32 v0, v2, v0
	v_mul_f32_e32 v1, v3, v1
	v_lshlrev_b32_e32 v2, 16, v113
	v_and_b32_e32 v3, 0xffff0000, v113
	v_mul_f32_e32 v2, v4, v2
	v_mul_f32_e32 v3, v5, v3
	v_cvt_pk_bf16_f32 v0, v0, v1
	v_cvt_pk_bf16_f32 v1, v2, v3
	v_lshlrev_b32_e32 v2, 16, v6
	v_and_b32_e32 v3, 0xffff0000, v6
	v_mul_f32_e32 v4, v12, v34
	v_mul_f32_e32 v5, v13, v34
	s_mov_b64 s[2:3], 0x200
	v_mul_f32_e32 v2, v4, v2
	v_mul_f32_e32 v3, v5, v3
	v_lshlrev_b32_e32 v4, 16, v7
	v_and_b32_e32 v5, 0xffff0000, v7
	v_mul_f32_e32 v6, v14, v34
	v_mul_f32_e32 v7, v15, v34
	v_cvt_pk_bf16_f32 v2, v2, v3
	v_mul_f32_e32 v4, v6, v4
	v_mul_f32_e32 v5, v7, v5
	v_lshl_add_u64 v[32:33], v[36:37], 0, s[2:3]
	v_cvt_pk_bf16_f32 v3, v4, v5
	v_permlane32_swap_b32_e32 v0, v2
	s_nop 0
	v_permlane32_swap_b32_e32 v1, v3
	s_branch .LBB0_876
